# GEMM K-loops: LDS-DMA pieces in SGPR-base + 32-bit lane-offset form (no per-piece 64-bit VALU address add)
# baseline (speedup 1.0000x reference)
; template <class Epi>
; DI void gemm_tile256(const u16* __restrict__ Ag, long lda, const u16* __restrict__ Bg, long ldb, int nk, char* shm, Epi&& epi) {
;   const int tid = RTID, wid = tid >> 6, lane = tid & 63, wr = wid >> 2, wc = wid & 3, fr = lane & 15, fq = lane >> 4;
;   f32x4 acc[8][4];
; #pragma unroll
;   for (int m = 0; m < 8; ++m)
; #pragma unroll
;     for (int n = 0; n < 4; ++n) acc[m][n] = f32x4{0.f, 0.f, 0.f, 0.f};
;   const int q0 = tid, q1 = 512 + tid;
;   const int r0 = q0 >> 2, r1 = q1 >> 2, c0 = (q0 & 3) ^ ((r0 >> 2) & 3), c1 = (q1 & 3) ^ ((r1 >> 2) & 3);
;   const u16* a0 = Ag + (long)r0 * lda + c0 * 8; const u16* a1 = Ag + (long)r1 * lda + c1 * 8;
;   const u16* b0 = Bg + (long)r0 * ldb + c0 * 8; const u16* b1 = Bg + (long)r1 * ldb + c1 * 8;
;   auto stage = [&](int j) {
;     char* SA = shm + (j & 3) * 32768; char* SB = SA + 16384;
;     __builtin_amdgcn_global_load_lds((const unsigned*)(a0 + j * 32), (__attribute__((address_space(3))) unsigned*)(SA + q0 * 16), 16, 0, 0);
;     __builtin_amdgcn_global_load_lds((const unsigned*)(a1 + j * 32), (__attribute__((address_space(3))) unsigned*)(SA + q1 * 16), 16, 0, 0);
;     __builtin_amdgcn_global_load_lds((const unsigned*)(b0 + j * 32), (__attribute__((address_space(3))) unsigned*)(SB + q0 * 16), 16, 0, 0);
;     __builtin_amdgcn_global_load_lds((const unsigned*)(b1 + j * 32), (__attribute__((address_space(3))) unsigned*)(SB + q1 * 16), 16, 0, 0);
;   };
;   __syncthreads();
;   stage(0);
;   if (nk > 1) stage(1);
;   if (nk > 2) stage(2);
;   for (int i = 0; i < nk; ++i) {
;     if (i + 2 < nk) asm volatile("s_waitcnt vmcnt(8)" ::: "memory");
;     else if (i + 1 < nk) asm volatile("s_waitcnt vmcnt(4)" ::: "memory");
;     else asm volatile("s_waitcnt vmcnt(0)" ::: "memory");
;     __builtin_amdgcn_s_barrier();
;     const char* SA = shm + (i & 3) * 32768; const char* SB = SA + 16384;
;     bf16x8 At[8], Bt[4];
; #pragma unroll
;     for (int n = 0; n < 4; ++n) { const int rb = wc * 64 + n * 16 + fr; Bt[n] = *reinterpret_cast<const bf16x8*>(SB + rb * 64 + ((fq ^ ((rb >> 2) & 3)) * 16)); }
; #pragma unroll
;     for (int m = 0; m < 8; ++m) { const int ra = wr * 128 + m * 16 + fr; At[m] = *reinterpret_cast<const bf16x8*>(SA + ra * 64 + ((fq ^ ((ra >> 2) & 3)) * 16)); }
.LBB0_107:
	v_lshl_add_u64 v[176:177], v[138:139], 0, 64
	v_lshl_add_u64 v[178:179], v[140:141], 0, 64
	v_lshl_add_u64 v[180:181], v[138:139], 0, s[0:1]
	v_lshl_add_u64 v[182:183], v[140:141], 0, s[0:1]
	s_lshl_b32 s30, s27, 8
	s_ashr_i32 s29, s28, 31
	s_ashr_i32 s31, s30, 31
	s_lshl_b64 s[6:7], s[28:29], 11
	s_lshl_b64 s[4:5], s[30:31], 11
	s_add_u32 s4, s54, s4
	s_addc_u32 s5, s55, s5
	v_add_u32_e32 v6, 0, v209
	v_lshl_add_u64 v[0:1], s[4:5], 0, v[132:133]
	v_lshl_add_u64 v[2:3], s[4:5], 0, v[136:137]
	v_readfirstlane_b32 s4, v6
	v_add_u32_e32 v7, 0, v131
	v_lshl_add_u64 v[0:1], v[0:1], 0, v[134:135]
	s_mov_b32 m0, s4
	v_readfirstlane_b32 s4, v7
	v_add_u32_e32 v4, 0x4000, v6
	v_lshl_add_u64 v[2:3], v[2:3], 0, v[134:135]
	s_barrier
	global_load_lds_dwordx4 v[0:1], off
	s_mov_b32 m0, s4
	v_readfirstlane_b32 s4, v4
	v_add_u32_e32 v4, 0x4000, v7
	global_load_lds_dwordx4 v[2:3], off
	s_mov_b32 m0, s4
	v_readfirstlane_b32 s4, v4
	v_add_u32_e32 v8, 0x8000, v6
	global_load_lds_dwordx4 v[138:139], off
	s_mov_b32 m0, s4
	v_readfirstlane_b32 s4, v8
	v_add_u32_e32 v8, 0x8000, v7
	global_load_lds_dwordx4 v[140:141], off
	v_lshl_add_u64 v[4:5], v[0:1], 0, 64
	s_mov_b32 m0, s4
	v_readfirstlane_b32 s4, v8
	global_load_lds_dwordx4 v[4:5], off
	v_lshl_add_u64 v[4:5], v[2:3], 0, 64
	s_mov_b32 m0, s4
	v_lshl_add_u64 v[0:1], v[0:1], 0, s[0:1]
	global_load_lds_dwordx4 v[4:5], off
	v_add_u32_e32 v4, 0xc000, v6
	s_mov_b32 s8, 0x18000
	v_readfirstlane_b32 s4, v4
	v_add_u32_e32 v4, 0xc000, v7
	s_mov_b32 m0, s4
	v_readfirstlane_b32 s4, v4
	v_add_u32_e32 v4, s2, v209
	global_load_lds_dwordx4 v[176:177], off
	s_mov_b32 m0, s4
	v_readfirstlane_b32 s4, v4
	global_load_lds_dwordx4 v[178:179], off
	s_mov_b32 m0, s4
	v_mov_b32_e32 v4, 0
	global_load_lds_dwordx4 v[0:1], off
	v_lshl_add_u64 v[0:1], v[2:3], 0, s[0:1]
	v_add_u32_e32 v2, s2, v131
	v_mov_b32_e32 v3, v135
	v_readfirstlane_b32 s4, v2
	s_mov_b32 m0, s4
	v_mov_b32_e32 v2, v135
	global_load_lds_dwordx4 v[0:1], off
	v_add_u32_e32 v0, s15, v209
	v_mov_b32_e32 v1, v135
	v_readfirstlane_b32 s4, v0
	v_add_u32_e32 v0, s15, v131
	s_mov_b32 m0, s4
	v_readfirstlane_b32 s4, v0
	global_load_lds_dwordx4 v[180:181], off
	s_mov_b32 m0, s4
	s_mov_b64 s[4:5], 0
	global_load_lds_dwordx4 v[182:183], off
	v_mov_b32_e32 v0, 0
	v_mov_b32_e32 v5, v135
	v_mov_b32_e32 v6, v135
	v_mov_b32_e32 v7, v135
	v_mov_b32_e32 v8, 0
	v_mov_b32_e32 v9, v135
	v_mov_b32_e32 v10, v135
	v_mov_b32_e32 v11, v135
	v_mov_b32_e32 v12, 0
	v_mov_b32_e32 v13, v135
	v_mov_b32_e32 v14, v135
	v_mov_b32_e32 v15, v135
	v_mov_b32_e32 v16, 0
	v_mov_b32_e32 v17, v135
	v_mov_b32_e32 v18, v135
	v_mov_b32_e32 v19, v135
	v_mov_b32_e32 v20, 0
	v_mov_b32_e32 v21, v135
	v_mov_b32_e32 v22, v135
	v_mov_b32_e32 v23, v135
	v_mov_b32_e32 v24, 0
	v_mov_b32_e32 v25, v135
	v_mov_b32_e32 v26, v135
	v_mov_b32_e32 v27, v135
	v_mov_b32_e32 v28, 0
	v_mov_b32_e32 v29, v135
	v_mov_b32_e32 v30, v135
	v_mov_b32_e32 v31, v135
	v_mov_b32_e32 v32, 0
	v_mov_b32_e32 v33, v135
	v_mov_b32_e32 v34, v135
	v_mov_b32_e32 v35, v135
	v_mov_b32_e32 v36, 0
	v_mov_b32_e32 v37, v135
	v_mov_b32_e32 v38, v135
	v_mov_b32_e32 v39, v135
	v_mov_b32_e32 v40, 0
	v_mov_b32_e32 v41, v135
	v_mov_b32_e32 v42, v135
	v_mov_b32_e32 v43, v135
	v_mov_b32_e32 v44, 0
	v_mov_b32_e32 v45, v135
	v_mov_b32_e32 v46, v135
	v_mov_b32_e32 v47, v135
	v_mov_b32_e32 v48, 0
	v_mov_b32_e32 v49, v135
	v_mov_b32_e32 v50, v135
	v_mov_b32_e32 v51, v135
	v_mov_b32_e32 v52, 0
	v_mov_b32_e32 v53, v135
	v_mov_b32_e32 v54, v135
	v_mov_b32_e32 v55, v135
	v_mov_b32_e32 v56, 0
	v_mov_b32_e32 v57, v135
	v_mov_b32_e32 v58, v135
	v_mov_b32_e32 v59, v135
	v_mov_b32_e32 v60, 0
	v_mov_b32_e32 v61, v135
	v_mov_b32_e32 v62, v135
	v_mov_b32_e32 v63, v135
	v_mov_b32_e32 v64, 0
	v_mov_b32_e32 v65, v135
	v_mov_b32_e32 v66, v135
	v_mov_b32_e32 v67, v135
	v_mov_b32_e32 v68, 0
	v_mov_b32_e32 v69, v135
	v_mov_b32_e32 v70, v135
	v_mov_b32_e32 v71, v135
	v_mov_b32_e32 v72, 0
	v_mov_b32_e32 v73, v135
	v_mov_b32_e32 v74, v135
	v_mov_b32_e32 v75, v135
	v_mov_b32_e32 v76, 0
	v_mov_b32_e32 v77, v135
	v_mov_b32_e32 v78, v135
	v_mov_b32_e32 v79, v135
	v_mov_b32_e32 v80, 0
	v_mov_b32_e32 v81, v135
	v_mov_b32_e32 v82, v135
	v_mov_b32_e32 v83, v135
	v_mov_b32_e32 v84, 0
	v_mov_b32_e32 v85, v135
	v_mov_b32_e32 v86, v135
	v_mov_b32_e32 v87, v135
	v_mov_b32_e32 v88, 0
	v_mov_b32_e32 v89, v135
	v_mov_b32_e32 v90, v135
	v_mov_b32_e32 v91, v135
	v_mov_b32_e32 v92, 0
	v_mov_b32_e32 v93, v135
	v_mov_b32_e32 v94, v135
	v_mov_b32_e32 v95, v135
	v_mov_b32_e32 v96, 0
	v_mov_b32_e32 v97, v135
	v_mov_b32_e32 v98, v135
	v_mov_b32_e32 v99, v135
	v_mov_b32_e32 v100, 0
	v_mov_b32_e32 v101, v135
	v_mov_b32_e32 v102, v135
	v_mov_b32_e32 v103, v135
	v_mov_b32_e32 v104, 0
	v_mov_b32_e32 v105, v135
	v_mov_b32_e32 v106, v135
	v_mov_b32_e32 v107, v135
	v_mov_b32_e32 v108, 0
	v_mov_b32_e32 v109, v135
	v_mov_b32_e32 v110, v135
	v_mov_b32_e32 v111, v135
	v_mov_b32_e32 v112, 0
	v_mov_b32_e32 v113, v135
	v_mov_b32_e32 v114, v135
	v_mov_b32_e32 v115, v135
	v_mov_b32_e32 v116, 0
	v_mov_b32_e32 v117, v135
	v_mov_b32_e32 v118, v135
	v_mov_b32_e32 v119, v135
	v_mov_b32_e32 v120, 0
	v_mov_b32_e32 v121, v135
	v_mov_b32_e32 v122, v135
	v_mov_b32_e32 v123, v135
	v_mov_b32_e32 v124, 0
	v_mov_b32_e32 v125, v135
	v_mov_b32_e32 v126, v135
	v_mov_b32_e32 v127, v135
	v_lshl_add_u64 v[184:185], v[168:169], 0, s[6:7]
	v_lshl_add_u64 v[186:187], v[170:171], 0, s[6:7]
	v_readfirstlane_b32 s7, v209
	s_mov_b32 s8, 0
	s_mov_b64 s[4:5], 0
	v_readfirstlane_b32 s36, v184
	v_readfirstlane_b32 s37, v185
	v_readfirstlane_b32 s38, v186
	v_readfirstlane_b32 s39, v187
	v_readfirstlane_b32 s40, v172
	v_readfirstlane_b32 s41, v173
	v_readfirstlane_b32 s42, v174
	v_readfirstlane_b32 s43, v175
	s_sub_u32 s36, s36, 64
	s_subb_u32 s37, s37, 0
	v_subrev_u32_e32 v206, s36, v184
	s_sub_u32 s38, s38, 64
	s_subb_u32 s39, s39, 0
	v_subrev_u32_e32 v207, s38, v186
	s_sub_u32 s40, s40, 64
	s_subb_u32 s41, s41, 0
	v_subrev_u32_e32 v252, s40, v172
	s_sub_u32 s42, s42, 64
	s_subb_u32 s43, s43, 0
	v_subrev_u32_e32 v253, s42, v174
	s_and_b64 vcc, exec, s[24:25]
	s_cbranch_vccz .Lgemm_p1_n
	s_waitcnt vmcnt(8)
	s_barrier
	v_add3_u32 v236, v205, v147, s8
	v_add3_u32 v215, v205, v151, s8
	s_nop 0
	ds_read_b128 v[216:219], v236 offset:16384
	ds_read_b128 v[220:223], v236 offset:17408
	ds_read_b128 v[232:235], v236 offset:18432
	ds_read_b128 v[236:239], v236 offset:19456
	ds_read_b128 v[224:227], v215
	ds_read_b128 v[228:231], v215 offset:1024
; template <class Epi>
; DI void gemm_tile256(const u16* __restrict__ Ag, long lda, const u16* __restrict__ Bg, long ldb, int nk, char* shm, Epi&& epi) {
;     ...
;   for (int i = 0; i < nk; ++i) {
;     if (i + 2 < nk) asm volatile("s_waitcnt vmcnt(8)" ::: "memory");
;     else if (i + 1 < nk) asm volatile("s_waitcnt vmcnt(4)" ::: "memory");
;     else asm volatile("s_waitcnt vmcnt(0)" ::: "memory");
;     __builtin_amdgcn_s_barrier();
;     const char* SA = shm + (i & 3) * 32768; const char* SB = SA + 16384;
;     bf16x8 At[8], Bt[4];
; #pragma unroll
;     for (int n = 0; n < 4; ++n) { const int rb = wc * 64 + n * 16 + fr; Bt[n] = *reinterpret_cast<const bf16x8*>(SB + rb * 64 + ((fq ^ ((rb >> 2) & 3)) * 16)); }
; #pragma unroll
;     for (int m = 0; m < 8; ++m) { const int ra = wr * 128 + m * 16 + fr; At[m] = *reinterpret_cast<const bf16x8*>(SA + ra * 64 + ((fq ^ ((ra >> 2) & 3)) * 16)); }
;     if (i + 3 < nk) stage(i + 3);
; #pragma unroll
;     for (int m = 0; m < 8; ++m)
; #pragma unroll
;       for (int n = 0; n < 4; ++n) acc[m][n] = __builtin_amdgcn_mfma_f32_16x16x32_bf16(Bt[n], At[m], acc[m][n], 0, 0, 0);
;   }
.Lgemm_p1_kloopv:
	s_add_i32 s6, s8, 0x18000
	s_and_b32 s6, s6, 0x18000
	s_add_i32 s9, s6, s7
	ds_read_b128 v[180:183], v215 offset:2048
	ds_read_b128 v[210:213], v215 offset:3072
	s_waitcnt lgkmcnt(2)
	v_mfma_f32_16x16x32_bf16 v[124:127], v[224:227], v[216:219], v[124:127]
	v_lshl_add_u64 v[206:207], v[184:185], 0, s[4:5]
	v_mfma_f32_16x16x32_bf16 v[120:123], v[224:227], v[220:223], v[120:123]
	s_mov_b32 m0, s9
	v_mfma_f32_16x16x32_bf16 v[116:119], v[224:227], v[232:235], v[116:119]
	s_add_i32 s9, s9, 0x2000
	v_mfma_f32_16x16x32_bf16 v[112:115], v[224:227], v[236:239], v[112:115]
	global_load_lds_dwordx4 v[206:207], off
	v_mfma_f32_16x16x32_bf16 v[108:111], v[228:231], v[216:219], v[108:111]
	v_mfma_f32_16x16x32_bf16 v[104:107], v[228:231], v[220:223], v[104:107]
	v_mfma_f32_16x16x32_bf16 v[100:103], v[228:231], v[232:235], v[100:103]
	v_mfma_f32_16x16x32_bf16 v[96:99], v[228:231], v[236:239], v[96:99]
	ds_read_b128 v[224:227], v215 offset:4096
	ds_read_b128 v[228:231], v215 offset:5120
	s_waitcnt lgkmcnt(2)
	v_mfma_f32_16x16x32_bf16 v[92:95], v[180:183], v[216:219], v[92:95]
	v_lshl_add_u64 v[206:207], v[186:187], 0, s[4:5]
	v_mfma_f32_16x16x32_bf16 v[88:91], v[180:183], v[220:223], v[88:91]
	s_mov_b32 m0, s9
	v_mfma_f32_16x16x32_bf16 v[84:87], v[180:183], v[232:235], v[84:87]
	s_add_i32 s9, s9, 0x2000
	v_mfma_f32_16x16x32_bf16 v[80:83], v[180:183], v[236:239], v[80:83]
	global_load_lds_dwordx4 v[206:207], off
	v_mfma_f32_16x16x32_bf16 v[76:79], v[210:213], v[216:219], v[76:79]
	v_mfma_f32_16x16x32_bf16 v[72:75], v[210:213], v[220:223], v[72:75]
	v_mfma_f32_16x16x32_bf16 v[68:71], v[210:213], v[232:235], v[68:71]
	v_mfma_f32_16x16x32_bf16 v[64:67], v[210:213], v[236:239], v[64:67]
	ds_read_b128 v[180:183], v215 offset:6144
	ds_read_b128 v[210:213], v215 offset:7168
	s_waitcnt lgkmcnt(2)
	v_mfma_f32_16x16x32_bf16 v[60:63], v[224:227], v[216:219], v[60:63]
	v_lshl_add_u64 v[206:207], v[172:173], 0, s[4:5]
	v_mfma_f32_16x16x32_bf16 v[56:59], v[224:227], v[220:223], v[56:59]
	s_mov_b32 m0, s9
	v_mfma_f32_16x16x32_bf16 v[52:55], v[224:227], v[232:235], v[52:55]
	s_add_i32 s9, s9, 0x2000
	v_mfma_f32_16x16x32_bf16 v[48:51], v[224:227], v[236:239], v[48:51]
	global_load_lds_dwordx4 v[206:207], off
	v_mfma_f32_16x16x32_bf16 v[44:47], v[228:231], v[216:219], v[44:47]
	v_mfma_f32_16x16x32_bf16 v[40:43], v[228:231], v[220:223], v[40:43]
	v_mfma_f32_16x16x32_bf16 v[36:39], v[228:231], v[232:235], v[36:39]
	v_mfma_f32_16x16x32_bf16 v[32:35], v[228:231], v[236:239], v[32:35]
	s_add_i32 s8, s8, 0x8000
	s_and_b32 s8, s8, 0x18000
	s_waitcnt vmcnt(7) lgkmcnt(0)
	s_barrier
	v_add3_u32 v176, v205, v147, s8
	v_add3_u32 v215, v205, v151, s8
	s_nop 0
	ds_read_b128 v[240:243], v176 offset:16384
	ds_read_b128 v[244:247], v176 offset:17408
	ds_read_b128 v[248:251], v176 offset:18432
	ds_read_b128 v[176:179], v176 offset:19456
	ds_read_b128 v[224:227], v215
	ds_read_b128 v[228:231], v215 offset:1024
	v_mfma_f32_16x16x32_bf16 v[28:31], v[180:183], v[216:219], v[28:31]
	v_lshl_add_u64 v[206:207], v[174:175], 0, s[4:5]
	v_mfma_f32_16x16x32_bf16 v[24:27], v[180:183], v[220:223], v[24:27]
	s_mov_b32 m0, s9
	v_mfma_f32_16x16x32_bf16 v[20:23], v[180:183], v[232:235], v[20:23]
	s_add_i32 s9, s9, 0x2000
	v_mfma_f32_16x16x32_bf16 v[16:19], v[180:183], v[236:239], v[16:19]
	global_load_lds_dwordx4 v[206:207], off
	v_mfma_f32_16x16x32_bf16 v[12:15], v[210:213], v[216:219], v[12:15]
	s_add_u32 s4, s4, 64
	v_mfma_f32_16x16x32_bf16 v[8:11], v[210:213], v[220:223], v[8:11]
	s_addc_u32 s5, s5, 0
	v_mfma_f32_16x16x32_bf16 v[4:7], v[210:213], v[232:235], v[4:7]
	v_mfma_f32_16x16x32_bf16 v[0:3], v[210:213], v[236:239], v[0:3]
	s_add_i32 s6, s8, 0x18000
	s_and_b32 s6, s6, 0x18000
	s_add_i32 s9, s6, s7
	ds_read_b128 v[180:183], v215 offset:2048
	ds_read_b128 v[210:213], v215 offset:3072
	s_waitcnt lgkmcnt(2)
	v_mfma_f32_16x16x32_bf16 v[124:127], v[224:227], v[240:243], v[124:127]
	v_lshl_add_u64 v[206:207], v[184:185], 0, s[4:5]
	v_mfma_f32_16x16x32_bf16 v[120:123], v[224:227], v[244:247], v[120:123]
	s_mov_b32 m0, s9
	v_mfma_f32_16x16x32_bf16 v[116:119], v[224:227], v[248:251], v[116:119]
	s_add_i32 s9, s9, 0x2000
	v_mfma_f32_16x16x32_bf16 v[112:115], v[224:227], v[176:179], v[112:115]
	global_load_lds_dwordx4 v[206:207], off
	v_mfma_f32_16x16x32_bf16 v[108:111], v[228:231], v[240:243], v[108:111]
	v_mfma_f32_16x16x32_bf16 v[104:107], v[228:231], v[244:247], v[104:107]
	v_mfma_f32_16x16x32_bf16 v[100:103], v[228:231], v[248:251], v[100:103]
	v_mfma_f32_16x16x32_bf16 v[96:99], v[228:231], v[176:179], v[96:99]
	ds_read_b128 v[224:227], v215 offset:4096
	ds_read_b128 v[228:231], v215 offset:5120
	s_waitcnt lgkmcnt(2)
	v_mfma_f32_16x16x32_bf16 v[92:95], v[180:183], v[240:243], v[92:95]
	v_lshl_add_u64 v[206:207], v[186:187], 0, s[4:5]
	v_mfma_f32_16x16x32_bf16 v[88:91], v[180:183], v[244:247], v[88:91]
	s_mov_b32 m0, s9
	v_mfma_f32_16x16x32_bf16 v[84:87], v[180:183], v[248:251], v[84:87]
	s_add_i32 s9, s9, 0x2000
	v_mfma_f32_16x16x32_bf16 v[80:83], v[180:183], v[176:179], v[80:83]
	global_load_lds_dwordx4 v[206:207], off
	v_mfma_f32_16x16x32_bf16 v[76:79], v[210:213], v[240:243], v[76:79]
	v_mfma_f32_16x16x32_bf16 v[72:75], v[210:213], v[244:247], v[72:75]
	v_mfma_f32_16x16x32_bf16 v[68:71], v[210:213], v[248:251], v[68:71]
	v_mfma_f32_16x16x32_bf16 v[64:67], v[210:213], v[176:179], v[64:67]
	ds_read_b128 v[180:183], v215 offset:6144
	ds_read_b128 v[210:213], v215 offset:7168
	s_waitcnt lgkmcnt(2)
	v_mfma_f32_16x16x32_bf16 v[60:63], v[224:227], v[240:243], v[60:63]
	v_lshl_add_u64 v[206:207], v[172:173], 0, s[4:5]
	v_mfma_f32_16x16x32_bf16 v[56:59], v[224:227], v[244:247], v[56:59]
	s_mov_b32 m0, s9
	v_mfma_f32_16x16x32_bf16 v[52:55], v[224:227], v[248:251], v[52:55]
	s_add_i32 s9, s9, 0x2000
	v_mfma_f32_16x16x32_bf16 v[48:51], v[224:227], v[176:179], v[48:51]
	global_load_lds_dwordx4 v[206:207], off
	v_mfma_f32_16x16x32_bf16 v[44:47], v[228:231], v[240:243], v[44:47]
	v_mfma_f32_16x16x32_bf16 v[40:43], v[228:231], v[244:247], v[40:43]
	v_mfma_f32_16x16x32_bf16 v[36:39], v[228:231], v[248:251], v[36:39]
	v_mfma_f32_16x16x32_bf16 v[32:35], v[228:231], v[176:179], v[32:35]
	s_add_i32 s8, s8, 0x8000
	s_and_b32 s8, s8, 0x18000
	s_waitcnt vmcnt(7) lgkmcnt(0)
	s_barrier
; template <class Epi>
; DI void gemm_tile256(const u16* __restrict__ Ag, long lda, const u16* __restrict__ Bg, long ldb, int nk, char* shm, Epi&& epi) {
;     ...
;   for (int i = 0; i < nk; ++i) {
;     if (i + 2 < nk) asm volatile("s_waitcnt vmcnt(8)" ::: "memory");
;     else if (i + 1 < nk) asm volatile("s_waitcnt vmcnt(4)" ::: "memory");
;     else asm volatile("s_waitcnt vmcnt(0)" ::: "memory");
;     __builtin_amdgcn_s_barrier();
;     const char* SA = shm + (i & 3) * 32768; const char* SB = SA + 16384;
;     bf16x8 At[8], Bt[4];
; #pragma unroll
;     for (int n = 0; n < 4; ++n) { const int rb = wc * 64 + n * 16 + fr; Bt[n] = *reinterpret_cast<const bf16x8*>(SB + rb * 64 + ((fq ^ ((rb >> 2) & 3)) * 16)); }
; #pragma unroll
;     for (int m = 0; m < 8; ++m) { const int ra = wr * 128 + m * 16 + fr; At[m] = *reinterpret_cast<const bf16x8*>(SA + ra * 64 + ((fq ^ ((ra >> 2) & 3)) * 16)); }
;     if (i + 3 < nk) stage(i + 3);
; #pragma unroll
;     for (int m = 0; m < 8; ++m)
; #pragma unroll
;       for (int n = 0; n < 4; ++n) acc[m][n] = __builtin_amdgcn_mfma_f32_16x16x32_bf16(Bt[n], At[m], acc[m][n], 0, 0, 0);
;   }
	v_add3_u32 v236, v205, v147, s8
	v_add3_u32 v215, v205, v151, s8
	s_nop 0
	ds_read_b128 v[216:219], v236 offset:16384
	ds_read_b128 v[220:223], v236 offset:17408
	ds_read_b128 v[232:235], v236 offset:18432
	ds_read_b128 v[236:239], v236 offset:19456
	ds_read_b128 v[224:227], v215
	ds_read_b128 v[228:231], v215 offset:1024
	v_mfma_f32_16x16x32_bf16 v[28:31], v[180:183], v[240:243], v[28:31]
	v_lshl_add_u64 v[206:207], v[174:175], 0, s[4:5]
	v_mfma_f32_16x16x32_bf16 v[24:27], v[180:183], v[244:247], v[24:27]
	s_mov_b32 m0, s9
	v_mfma_f32_16x16x32_bf16 v[20:23], v[180:183], v[248:251], v[20:23]
	s_add_i32 s9, s9, 0x2000
	v_mfma_f32_16x16x32_bf16 v[16:19], v[180:183], v[176:179], v[16:19]
	global_load_lds_dwordx4 v[206:207], off
	v_mfma_f32_16x16x32_bf16 v[12:15], v[210:213], v[240:243], v[12:15]
	s_add_u32 s4, s4, 64
	v_mfma_f32_16x16x32_bf16 v[8:11], v[210:213], v[244:247], v[8:11]
	s_addc_u32 s5, s5, 0
	v_mfma_f32_16x16x32_bf16 v[4:7], v[210:213], v[248:251], v[4:7]
	v_mfma_f32_16x16x32_bf16 v[0:3], v[210:213], v[176:179], v[0:3]
	s_cmpk_lg_i32 s4, 0x700
	s_cbranch_scc1 .Lgemm_p1_kloopv
	s_add_i32 s6, s8, 0x18000
	s_and_b32 s6, s6, 0x18000
	s_add_i32 s9, s6, s7
	ds_read_b128 v[180:183], v215 offset:2048
	ds_read_b128 v[210:213], v215 offset:3072
	s_waitcnt lgkmcnt(2)
	v_mfma_f32_16x16x32_bf16 v[124:127], v[224:227], v[216:219], v[124:127]
	v_lshl_add_u64 v[206:207], v[184:185], 0, s[4:5]
	v_mfma_f32_16x16x32_bf16 v[120:123], v[224:227], v[220:223], v[120:123]
	s_mov_b32 m0, s9
	v_mfma_f32_16x16x32_bf16 v[116:119], v[224:227], v[232:235], v[116:119]
	s_add_i32 s9, s9, 0x2000
	v_mfma_f32_16x16x32_bf16 v[112:115], v[224:227], v[236:239], v[112:115]
	global_load_lds_dwordx4 v[206:207], off
	v_mfma_f32_16x16x32_bf16 v[108:111], v[228:231], v[216:219], v[108:111]
	v_mfma_f32_16x16x32_bf16 v[104:107], v[228:231], v[220:223], v[104:107]
	v_mfma_f32_16x16x32_bf16 v[100:103], v[228:231], v[232:235], v[100:103]
	v_mfma_f32_16x16x32_bf16 v[96:99], v[228:231], v[236:239], v[96:99]
	ds_read_b128 v[224:227], v215 offset:4096
	ds_read_b128 v[228:231], v215 offset:5120
	s_waitcnt lgkmcnt(2)
	v_mfma_f32_16x16x32_bf16 v[92:95], v[180:183], v[216:219], v[92:95]
	v_lshl_add_u64 v[206:207], v[186:187], 0, s[4:5]
	v_mfma_f32_16x16x32_bf16 v[88:91], v[180:183], v[220:223], v[88:91]
	s_mov_b32 m0, s9
	v_mfma_f32_16x16x32_bf16 v[84:87], v[180:183], v[232:235], v[84:87]
	s_add_i32 s9, s9, 0x2000
	v_mfma_f32_16x16x32_bf16 v[80:83], v[180:183], v[236:239], v[80:83]
	global_load_lds_dwordx4 v[206:207], off
	v_mfma_f32_16x16x32_bf16 v[76:79], v[210:213], v[216:219], v[76:79]
	v_mfma_f32_16x16x32_bf16 v[72:75], v[210:213], v[220:223], v[72:75]
	v_mfma_f32_16x16x32_bf16 v[68:71], v[210:213], v[232:235], v[68:71]
	v_mfma_f32_16x16x32_bf16 v[64:67], v[210:213], v[236:239], v[64:67]
	ds_read_b128 v[180:183], v215 offset:6144
	ds_read_b128 v[210:213], v215 offset:7168
	s_waitcnt lgkmcnt(2)
	v_mfma_f32_16x16x32_bf16 v[60:63], v[224:227], v[216:219], v[60:63]
	v_lshl_add_u64 v[206:207], v[172:173], 0, s[4:5]
	v_mfma_f32_16x16x32_bf16 v[56:59], v[224:227], v[220:223], v[56:59]
	s_mov_b32 m0, s9
	v_mfma_f32_16x16x32_bf16 v[52:55], v[224:227], v[232:235], v[52:55]
	s_add_i32 s9, s9, 0x2000
	v_mfma_f32_16x16x32_bf16 v[48:51], v[224:227], v[236:239], v[48:51]
	global_load_lds_dwordx4 v[206:207], off
	v_mfma_f32_16x16x32_bf16 v[44:47], v[228:231], v[216:219], v[44:47]
	v_mfma_f32_16x16x32_bf16 v[40:43], v[228:231], v[220:223], v[40:43]
	v_mfma_f32_16x16x32_bf16 v[36:39], v[228:231], v[232:235], v[36:39]
	v_mfma_f32_16x16x32_bf16 v[32:35], v[228:231], v[236:239], v[32:35]
	s_add_i32 s8, s8, 0x8000
	s_and_b32 s8, s8, 0x18000
	s_waitcnt vmcnt(7) lgkmcnt(0)
	s_barrier
	v_add3_u32 v176, v205, v147, s8
	v_add3_u32 v215, v205, v151, s8
	s_nop 0
	ds_read_b128 v[240:243], v176 offset:16384
	ds_read_b128 v[244:247], v176 offset:17408
	ds_read_b128 v[248:251], v176 offset:18432
	ds_read_b128 v[176:179], v176 offset:19456
	ds_read_b128 v[224:227], v215
	ds_read_b128 v[228:231], v215 offset:1024
	v_mfma_f32_16x16x32_bf16 v[28:31], v[180:183], v[216:219], v[28:31]
	v_lshl_add_u64 v[206:207], v[174:175], 0, s[4:5]
	v_mfma_f32_16x16x32_bf16 v[24:27], v[180:183], v[220:223], v[24:27]
	s_mov_b32 m0, s9
	v_mfma_f32_16x16x32_bf16 v[20:23], v[180:183], v[232:235], v[20:23]
	s_add_i32 s9, s9, 0x2000
	v_mfma_f32_16x16x32_bf16 v[16:19], v[180:183], v[236:239], v[16:19]
	global_load_lds_dwordx4 v[206:207], off
	v_mfma_f32_16x16x32_bf16 v[12:15], v[210:213], v[216:219], v[12:15]
	s_add_u32 s4, s4, 64
	v_mfma_f32_16x16x32_bf16 v[8:11], v[210:213], v[220:223], v[8:11]
	s_addc_u32 s5, s5, 0
	v_mfma_f32_16x16x32_bf16 v[4:7], v[210:213], v[232:235], v[4:7]
	v_mfma_f32_16x16x32_bf16 v[0:3], v[210:213], v[236:239], v[0:3]
	ds_read_b128 v[180:183], v215 offset:2048
	ds_read_b128 v[210:213], v215 offset:3072
	s_waitcnt lgkmcnt(2)
	v_mfma_f32_16x16x32_bf16 v[124:127], v[224:227], v[240:243], v[124:127]
	v_mfma_f32_16x16x32_bf16 v[120:123], v[224:227], v[244:247], v[120:123]
	v_mfma_f32_16x16x32_bf16 v[116:119], v[224:227], v[248:251], v[116:119]
	v_mfma_f32_16x16x32_bf16 v[112:115], v[224:227], v[176:179], v[112:115]
	v_mfma_f32_16x16x32_bf16 v[108:111], v[228:231], v[240:243], v[108:111]
	v_mfma_f32_16x16x32_bf16 v[104:107], v[228:231], v[244:247], v[104:107]
	v_mfma_f32_16x16x32_bf16 v[100:103], v[228:231], v[248:251], v[100:103]
	v_mfma_f32_16x16x32_bf16 v[96:99], v[228:231], v[176:179], v[96:99]
	ds_read_b128 v[224:227], v215 offset:4096
	ds_read_b128 v[228:231], v215 offset:5120
	s_waitcnt lgkmcnt(2)
	v_mfma_f32_16x16x32_bf16 v[92:95], v[180:183], v[240:243], v[92:95]
	v_mfma_f32_16x16x32_bf16 v[88:91], v[180:183], v[244:247], v[88:91]
	v_mfma_f32_16x16x32_bf16 v[84:87], v[180:183], v[248:251], v[84:87]
	v_mfma_f32_16x16x32_bf16 v[80:83], v[180:183], v[176:179], v[80:83]
	v_mfma_f32_16x16x32_bf16 v[76:79], v[210:213], v[240:243], v[76:79]
	v_mfma_f32_16x16x32_bf16 v[72:75], v[210:213], v[244:247], v[72:75]
	v_mfma_f32_16x16x32_bf16 v[68:71], v[210:213], v[248:251], v[68:71]
	v_mfma_f32_16x16x32_bf16 v[64:67], v[210:213], v[176:179], v[64:67]
	ds_read_b128 v[180:183], v215 offset:6144
	ds_read_b128 v[210:213], v215 offset:7168
	s_waitcnt lgkmcnt(2)
	v_mfma_f32_16x16x32_bf16 v[60:63], v[224:227], v[240:243], v[60:63]
	v_mfma_f32_16x16x32_bf16 v[56:59], v[224:227], v[244:247], v[56:59]
	v_mfma_f32_16x16x32_bf16 v[52:55], v[224:227], v[248:251], v[52:55]
	v_mfma_f32_16x16x32_bf16 v[48:51], v[224:227], v[176:179], v[48:51]
	v_mfma_f32_16x16x32_bf16 v[44:47], v[228:231], v[240:243], v[44:47]
	v_mfma_f32_16x16x32_bf16 v[40:43], v[228:231], v[244:247], v[40:43]
	v_mfma_f32_16x16x32_bf16 v[36:39], v[228:231], v[248:251], v[36:39]
	v_mfma_f32_16x16x32_bf16 v[32:35], v[228:231], v[176:179], v[32:35]
	s_add_i32 s8, s8, 0x8000
	s_and_b32 s8, s8, 0x18000
	s_waitcnt vmcnt(4) lgkmcnt(0)
	s_barrier
; template <class Epi>
; DI void gemm_tile256(const u16* __restrict__ Ag, long lda, const u16* __restrict__ Bg, long ldb, int nk, char* shm, Epi&& epi) {
;     ...
;   for (int i = 0; i < nk; ++i) {
;     if (i + 2 < nk) asm volatile("s_waitcnt vmcnt(8)" ::: "memory");
;     else if (i + 1 < nk) asm volatile("s_waitcnt vmcnt(4)" ::: "memory");
;     else asm volatile("s_waitcnt vmcnt(0)" ::: "memory");
;     __builtin_amdgcn_s_barrier();
;     const char* SA = shm + (i & 3) * 32768; const char* SB = SA + 16384;
;     bf16x8 At[8], Bt[4];
; #pragma unroll
;     for (int n = 0; n < 4; ++n) { const int rb = wc * 64 + n * 16 + fr; Bt[n] = *reinterpret_cast<const bf16x8*>(SB + rb * 64 + ((fq ^ ((rb >> 2) & 3)) * 16)); }
; #pragma unroll
;     for (int m = 0; m < 8; ++m) { const int ra = wr * 128 + m * 16 + fr; At[m] = *reinterpret_cast<const bf16x8*>(SA + ra * 64 + ((fq ^ ((ra >> 2) & 3)) * 16)); }
;     if (i + 3 < nk) stage(i + 3);
; #pragma unroll
;     for (int m = 0; m < 8; ++m)
; #pragma unroll
;       for (int n = 0; n < 4; ++n) acc[m][n] = __builtin_amdgcn_mfma_f32_16x16x32_bf16(Bt[n], At[m], acc[m][n], 0, 0, 0);
;   }
;   __syncthreads();
	v_add3_u32 v236, v205, v147, s8
	v_add3_u32 v215, v205, v151, s8
	s_nop 0
	ds_read_b128 v[216:219], v236 offset:16384
	ds_read_b128 v[220:223], v236 offset:17408
	ds_read_b128 v[232:235], v236 offset:18432
	ds_read_b128 v[236:239], v236 offset:19456
	ds_read_b128 v[224:227], v215
	ds_read_b128 v[228:231], v215 offset:1024
	v_mfma_f32_16x16x32_bf16 v[28:31], v[180:183], v[240:243], v[28:31]
	v_mfma_f32_16x16x32_bf16 v[24:27], v[180:183], v[244:247], v[24:27]
	v_mfma_f32_16x16x32_bf16 v[20:23], v[180:183], v[248:251], v[20:23]
	v_mfma_f32_16x16x32_bf16 v[16:19], v[180:183], v[176:179], v[16:19]
	v_mfma_f32_16x16x32_bf16 v[12:15], v[210:213], v[240:243], v[12:15]
	v_mfma_f32_16x16x32_bf16 v[8:11], v[210:213], v[244:247], v[8:11]
	v_mfma_f32_16x16x32_bf16 v[4:7], v[210:213], v[248:251], v[4:7]
	v_mfma_f32_16x16x32_bf16 v[0:3], v[210:213], v[176:179], v[0:3]
	ds_read_b128 v[180:183], v215 offset:2048
	ds_read_b128 v[210:213], v215 offset:3072
	s_waitcnt lgkmcnt(2)
	v_mfma_f32_16x16x32_bf16 v[124:127], v[224:227], v[216:219], v[124:127]
	v_mfma_f32_16x16x32_bf16 v[120:123], v[224:227], v[220:223], v[120:123]
	v_mfma_f32_16x16x32_bf16 v[116:119], v[224:227], v[232:235], v[116:119]
	v_mfma_f32_16x16x32_bf16 v[112:115], v[224:227], v[236:239], v[112:115]
	v_mfma_f32_16x16x32_bf16 v[108:111], v[228:231], v[216:219], v[108:111]
	v_mfma_f32_16x16x32_bf16 v[104:107], v[228:231], v[220:223], v[104:107]
	v_mfma_f32_16x16x32_bf16 v[100:103], v[228:231], v[232:235], v[100:103]
	v_mfma_f32_16x16x32_bf16 v[96:99], v[228:231], v[236:239], v[96:99]
	ds_read_b128 v[224:227], v215 offset:4096
	ds_read_b128 v[228:231], v215 offset:5120
	s_waitcnt lgkmcnt(2)
	v_mfma_f32_16x16x32_bf16 v[92:95], v[180:183], v[216:219], v[92:95]
	v_mfma_f32_16x16x32_bf16 v[88:91], v[180:183], v[220:223], v[88:91]
	v_mfma_f32_16x16x32_bf16 v[84:87], v[180:183], v[232:235], v[84:87]
	v_mfma_f32_16x16x32_bf16 v[80:83], v[180:183], v[236:239], v[80:83]
	v_mfma_f32_16x16x32_bf16 v[76:79], v[210:213], v[216:219], v[76:79]
	v_mfma_f32_16x16x32_bf16 v[72:75], v[210:213], v[220:223], v[72:75]
	v_mfma_f32_16x16x32_bf16 v[68:71], v[210:213], v[232:235], v[68:71]
	v_mfma_f32_16x16x32_bf16 v[64:67], v[210:213], v[236:239], v[64:67]
	ds_read_b128 v[180:183], v215 offset:6144
	ds_read_b128 v[210:213], v215 offset:7168
	s_waitcnt lgkmcnt(2)
	v_mfma_f32_16x16x32_bf16 v[60:63], v[224:227], v[216:219], v[60:63]
	v_mfma_f32_16x16x32_bf16 v[56:59], v[224:227], v[220:223], v[56:59]
	v_mfma_f32_16x16x32_bf16 v[52:55], v[224:227], v[232:235], v[52:55]
	v_mfma_f32_16x16x32_bf16 v[48:51], v[224:227], v[236:239], v[48:51]
	v_mfma_f32_16x16x32_bf16 v[44:47], v[228:231], v[216:219], v[44:47]
	v_mfma_f32_16x16x32_bf16 v[40:43], v[228:231], v[220:223], v[40:43]
	v_mfma_f32_16x16x32_bf16 v[36:39], v[228:231], v[232:235], v[36:39]
	v_mfma_f32_16x16x32_bf16 v[32:35], v[228:231], v[236:239], v[32:35]
	s_add_i32 s8, s8, 0x8000
	s_and_b32 s8, s8, 0x18000
	s_waitcnt vmcnt(0) lgkmcnt(0)
	s_barrier
	v_add3_u32 v176, v205, v147, s8
	v_add3_u32 v215, v205, v151, s8
	s_nop 0
	ds_read_b128 v[240:243], v176 offset:16384
	ds_read_b128 v[244:247], v176 offset:17408
	ds_read_b128 v[248:251], v176 offset:18432
	ds_read_b128 v[176:179], v176 offset:19456
	ds_read_b128 v[224:227], v215
	ds_read_b128 v[228:231], v215 offset:1024
	v_mfma_f32_16x16x32_bf16 v[28:31], v[180:183], v[216:219], v[28:31]
	v_mfma_f32_16x16x32_bf16 v[24:27], v[180:183], v[220:223], v[24:27]
	v_mfma_f32_16x16x32_bf16 v[20:23], v[180:183], v[232:235], v[20:23]
	v_mfma_f32_16x16x32_bf16 v[16:19], v[180:183], v[236:239], v[16:19]
	v_mfma_f32_16x16x32_bf16 v[12:15], v[210:213], v[216:219], v[12:15]
	v_mfma_f32_16x16x32_bf16 v[8:11], v[210:213], v[220:223], v[8:11]
	v_mfma_f32_16x16x32_bf16 v[4:7], v[210:213], v[232:235], v[4:7]
	v_mfma_f32_16x16x32_bf16 v[0:3], v[210:213], v[236:239], v[0:3]
	ds_read_b128 v[180:183], v215 offset:2048
	ds_read_b128 v[210:213], v215 offset:3072
	s_waitcnt lgkmcnt(2)
	v_mfma_f32_16x16x32_bf16 v[124:127], v[224:227], v[240:243], v[124:127]
	v_mfma_f32_16x16x32_bf16 v[120:123], v[224:227], v[244:247], v[120:123]
	v_mfma_f32_16x16x32_bf16 v[116:119], v[224:227], v[248:251], v[116:119]
	v_mfma_f32_16x16x32_bf16 v[112:115], v[224:227], v[176:179], v[112:115]
	v_mfma_f32_16x16x32_bf16 v[108:111], v[228:231], v[240:243], v[108:111]
	v_mfma_f32_16x16x32_bf16 v[104:107], v[228:231], v[244:247], v[104:107]
	v_mfma_f32_16x16x32_bf16 v[100:103], v[228:231], v[248:251], v[100:103]
	v_mfma_f32_16x16x32_bf16 v[96:99], v[228:231], v[176:179], v[96:99]
	ds_read_b128 v[224:227], v215 offset:4096
	ds_read_b128 v[228:231], v215 offset:5120
	s_waitcnt lgkmcnt(2)
	v_mfma_f32_16x16x32_bf16 v[92:95], v[180:183], v[240:243], v[92:95]
	v_mfma_f32_16x16x32_bf16 v[88:91], v[180:183], v[244:247], v[88:91]
	v_mfma_f32_16x16x32_bf16 v[84:87], v[180:183], v[248:251], v[84:87]
	v_mfma_f32_16x16x32_bf16 v[80:83], v[180:183], v[176:179], v[80:83]
	v_mfma_f32_16x16x32_bf16 v[76:79], v[210:213], v[240:243], v[76:79]
	v_mfma_f32_16x16x32_bf16 v[72:75], v[210:213], v[244:247], v[72:75]
	v_mfma_f32_16x16x32_bf16 v[68:71], v[210:213], v[248:251], v[68:71]
	v_mfma_f32_16x16x32_bf16 v[64:67], v[210:213], v[176:179], v[64:67]
	ds_read_b128 v[180:183], v215 offset:6144
	ds_read_b128 v[210:213], v215 offset:7168
	s_waitcnt lgkmcnt(2)
	v_mfma_f32_16x16x32_bf16 v[60:63], v[224:227], v[240:243], v[60:63]
	v_mfma_f32_16x16x32_bf16 v[56:59], v[224:227], v[244:247], v[56:59]
	v_mfma_f32_16x16x32_bf16 v[52:55], v[224:227], v[248:251], v[52:55]
	v_mfma_f32_16x16x32_bf16 v[48:51], v[224:227], v[176:179], v[48:51]
	v_mfma_f32_16x16x32_bf16 v[44:47], v[228:231], v[240:243], v[44:47]
	v_mfma_f32_16x16x32_bf16 v[40:43], v[228:231], v[244:247], v[40:43]
	v_mfma_f32_16x16x32_bf16 v[36:39], v[228:231], v[248:251], v[36:39]
	v_mfma_f32_16x16x32_bf16 v[32:35], v[228:231], v[176:179], v[32:35]
	s_waitcnt lgkmcnt(0)
	v_mfma_f32_16x16x32_bf16 v[28:31], v[180:183], v[240:243], v[28:31]
	v_mfma_f32_16x16x32_bf16 v[24:27], v[180:183], v[244:247], v[24:27]
	v_mfma_f32_16x16x32_bf16 v[20:23], v[180:183], v[248:251], v[20:23]
	v_mfma_f32_16x16x32_bf16 v[16:19], v[180:183], v[176:179], v[16:19]
	v_mfma_f32_16x16x32_bf16 v[12:15], v[210:213], v[240:243], v[12:15]
	v_mfma_f32_16x16x32_bf16 v[8:11], v[210:213], v[244:247], v[8:11]
	v_mfma_f32_16x16x32_bf16 v[4:7], v[210:213], v[248:251], v[4:7]
	v_mfma_f32_16x16x32_bf16 v[0:3], v[210:213], v[176:179], v[0:3]
	s_nop 7
	s_nop 3
	s_waitcnt vmcnt(0) lgkmcnt(0)
	s_barrier
; DI u16 f2bf(float x) { return (u16)(pack2bf(x, 0.f) & 0xffffu); }
; template <class Epi>
; DI void gemm_tile256(const u16* __restrict__ Ag, long lda, const u16* __restrict__ Bg, long ldb, int nk, char* shm, Epi&& epi) {
;     ...
;   __syncthreads();
; #pragma unroll
;   for (int m = 0; m < 8; ++m)
; #pragma unroll
;     for (int n = 0; n < 4; ++n) epi(wr * 128 + m * 16 + fr, wc * 64 + n * 16 + fq * 4, acc[m][n]);
; DI void phase1(const Params& P, char* smem) {
;     ...
;         const int hd = c - 1536, b = r >> 13, l = r & 8191;
; #pragma unroll
;         for (int j = 0; j < 4; ++j) Vt[((long)(b * 512 + hd + j)) * 8192 + l] = f2bf(v[j]);
	v_and_b32_e32 v184, 15, v208
	v_lshrrev_b32_e32 v185, 4, v208
	v_lshrrev_b32_e32 v186, 6, v189
	v_lshlrev_b32_e32 v186, 14, v186
	v_lshrrev_b32_e32 v206, 1, v185
	v_and_b32_e32 v207, 1, v185
	v_lshl_add_u32 v215, v184, 8, v186
	v_lshl_add_u32 v215, v207, 3, v215
	v_or_b32_e32 v252, 0, v206
	v_xor_b32_e32 v252, v252, v184
	v_lshl_add_u32 v176, v252, 4, v215
	v_or_b32_e32 v252, 2, v206
	v_xor_b32_e32 v252, v252, v184
	v_lshl_add_u32 v177, v252, 4, v215
	v_or_b32_e32 v252, 4, v206
	v_xor_b32_e32 v252, v252, v184
	v_lshl_add_u32 v178, v252, 4, v215
	v_or_b32_e32 v252, 6, v206
	v_xor_b32_e32 v252, v252, v184
	v_lshl_add_u32 v179, v252, 4, v215
	v_or_b32_e32 v252, 8, v206
	v_xor_b32_e32 v252, v252, v184
	v_lshl_add_u32 v180, v252, 4, v215
	v_or_b32_e32 v252, 10, v206
	v_xor_b32_e32 v252, v252, v184
	v_lshl_add_u32 v181, v252, 4, v215
	v_or_b32_e32 v252, 12, v206
	v_xor_b32_e32 v252, v252, v184
	v_lshl_add_u32 v211, v252, 4, v215
	v_or_b32_e32 v252, 14, v206
	v_xor_b32_e32 v252, v252, v184
	v_lshl_add_u32 v242, v252, 4, v215
	v_add_u32_e32 v253, 0, v185
	v_xor_b32_e32 v252, v184, v253
	v_lshl_add_u32 v243, v253, 8, v186
	v_lshl_add_u32 v243, v252, 4, v243
	v_add_u32_e32 v253, 4, v185
	v_xor_b32_e32 v252, v184, v253
	v_lshl_add_u32 v212, v253, 8, v186
	v_lshl_add_u32 v212, v252, 4, v212
	v_add_u32_e32 v253, 8, v185
	v_xor_b32_e32 v252, v184, v253
	v_lshl_add_u32 v213, v253, 8, v186
	v_lshl_add_u32 v213, v252, 4, v213
	v_add_u32_e32 v253, 12, v185
	v_xor_b32_e32 v252, v184, v253
	v_lshl_add_u32 v187, v253, 8, v186
	v_lshl_add_u32 v187, v252, 4, v187
	v_bfe_u32 v252, v189, 6, 2
	v_lshl_add_u32 v252, v252, 6, v185
	s_lshr_b32 s36, s30, 13
	s_lshl_b32 s36, s36, 9
	s_and_b32 s37, s74, 1
	s_lshl_b32 s37, s37, 8
	s_add_i32 s36, s36, s37
	v_add_u32_e32 v252, s36, v252
	v_lshlrev_b32_e32 v182, 14, v252
	s_and_b32 s36, s30, 0x1fff
	v_lshl_add_u32 v252, v190, 7, s36
	v_lshl_add_u32 v182, v252, 1, v182
	v_lshl_add_u32 v182, v184, 4, v182
	v_mov_b32_e32 v183, 0
	v_lshl_add_u64 v[182:183], v[182:183], 0, s[62:63]
	s_mov_b32 s38, 0x10000
	s_mov_b32 s39, 0
	v_lshl_add_u64 v[240:241], v[182:183], 0, s[38:39]
	s_lshl_b32 s38, s38, 1
	v_cvt_pk_bf16_f32 v124, v124, v125
	v_cvt_pk_bf16_f32 v125, v126, v127
	ds_write_b64 v176, v[124:125] offset:0
	v_cvt_pk_bf16_f32 v120, v120, v121
	v_cvt_pk_bf16_f32 v121, v122, v123
	ds_write_b64 v176, v[120:121] offset:4096
	v_cvt_pk_bf16_f32 v116, v116, v117
	v_cvt_pk_bf16_f32 v117, v118, v119
	ds_write_b64 v176, v[116:117] offset:8192
	v_cvt_pk_bf16_f32 v112, v112, v113
	v_cvt_pk_bf16_f32 v113, v114, v115
	ds_write_b64 v176, v[112:113] offset:12288
	v_cvt_pk_bf16_f32 v108, v108, v109
	v_cvt_pk_bf16_f32 v109, v110, v111
	ds_write_b64 v177, v[108:109] offset:0
	v_cvt_pk_bf16_f32 v104, v104, v105
	v_cvt_pk_bf16_f32 v105, v106, v107
	ds_write_b64 v177, v[104:105] offset:4096
	v_cvt_pk_bf16_f32 v100, v100, v101
	v_cvt_pk_bf16_f32 v101, v102, v103
	ds_write_b64 v177, v[100:101] offset:8192
	v_cvt_pk_bf16_f32 v96, v96, v97
	v_cvt_pk_bf16_f32 v97, v98, v99
	ds_write_b64 v177, v[96:97] offset:12288
	v_cvt_pk_bf16_f32 v92, v92, v93
	v_cvt_pk_bf16_f32 v93, v94, v95
	ds_write_b64 v178, v[92:93] offset:0
	v_cvt_pk_bf16_f32 v88, v88, v89
	v_cvt_pk_bf16_f32 v89, v90, v91
	ds_write_b64 v178, v[88:89] offset:4096
	v_cvt_pk_bf16_f32 v84, v84, v85
	v_cvt_pk_bf16_f32 v85, v86, v87
	ds_write_b64 v178, v[84:85] offset:8192
	v_cvt_pk_bf16_f32 v80, v80, v81
	v_cvt_pk_bf16_f32 v81, v82, v83
	ds_write_b64 v178, v[80:81] offset:12288
	v_cvt_pk_bf16_f32 v76, v76, v77
	v_cvt_pk_bf16_f32 v77, v78, v79
	ds_write_b64 v179, v[76:77] offset:0
	v_cvt_pk_bf16_f32 v72, v72, v73
	v_cvt_pk_bf16_f32 v73, v74, v75
	ds_write_b64 v179, v[72:73] offset:4096
	v_cvt_pk_bf16_f32 v68, v68, v69
	v_cvt_pk_bf16_f32 v69, v70, v71
	ds_write_b64 v179, v[68:69] offset:8192
	v_cvt_pk_bf16_f32 v64, v64, v65
	v_cvt_pk_bf16_f32 v65, v66, v67
	ds_write_b64 v179, v[64:65] offset:12288
	v_cvt_pk_bf16_f32 v60, v60, v61
	v_cvt_pk_bf16_f32 v61, v62, v63
	ds_write_b64 v180, v[60:61] offset:0
	v_cvt_pk_bf16_f32 v56, v56, v57
	v_cvt_pk_bf16_f32 v57, v58, v59
	ds_write_b64 v180, v[56:57] offset:4096
	v_cvt_pk_bf16_f32 v52, v52, v53
	v_cvt_pk_bf16_f32 v53, v54, v55
	ds_write_b64 v180, v[52:53] offset:8192
	v_cvt_pk_bf16_f32 v48, v48, v49
	v_cvt_pk_bf16_f32 v49, v50, v51
	ds_write_b64 v180, v[48:49] offset:12288
	v_cvt_pk_bf16_f32 v44, v44, v45
	v_cvt_pk_bf16_f32 v45, v46, v47
	ds_write_b64 v181, v[44:45] offset:0
	v_cvt_pk_bf16_f32 v40, v40, v41
	v_cvt_pk_bf16_f32 v41, v42, v43
	ds_write_b64 v181, v[40:41] offset:4096
	v_cvt_pk_bf16_f32 v36, v36, v37
	v_cvt_pk_bf16_f32 v37, v38, v39
	ds_write_b64 v181, v[36:37] offset:8192
	v_cvt_pk_bf16_f32 v32, v32, v33
	v_cvt_pk_bf16_f32 v33, v34, v35
	ds_write_b64 v181, v[32:33] offset:12288
	v_cvt_pk_bf16_f32 v28, v28, v29
	v_cvt_pk_bf16_f32 v29, v30, v31
	ds_write_b64 v211, v[28:29] offset:0
	v_cvt_pk_bf16_f32 v24, v24, v25
	v_cvt_pk_bf16_f32 v25, v26, v27
	ds_write_b64 v211, v[24:25] offset:4096
	v_cvt_pk_bf16_f32 v20, v20, v21
	v_cvt_pk_bf16_f32 v21, v22, v23
	ds_write_b64 v211, v[20:21] offset:8192
	v_cvt_pk_bf16_f32 v16, v16, v17
	v_cvt_pk_bf16_f32 v17, v18, v19
	ds_write_b64 v211, v[16:17] offset:12288
	v_cvt_pk_bf16_f32 v12, v12, v13
	v_cvt_pk_bf16_f32 v13, v14, v15
	ds_write_b64 v242, v[12:13] offset:0
	v_cvt_pk_bf16_f32 v8, v8, v9
	v_cvt_pk_bf16_f32 v9, v10, v11
	ds_write_b64 v242, v[8:9] offset:4096
	v_cvt_pk_bf16_f32 v4, v4, v5
	v_cvt_pk_bf16_f32 v5, v6, v7
	ds_write_b64 v242, v[4:5] offset:8192
	v_cvt_pk_bf16_f32 v0, v0, v1
	v_cvt_pk_bf16_f32 v1, v2, v3
	ds_write_b64 v242, v[0:1] offset:12288
	s_waitcnt lgkmcnt(0)
; DI u16 f2bf(float x) { return (u16)(pack2bf(x, 0.f) & 0xffffu); }
; template <class Epi>
; DI void gemm_tile256(const u16* __restrict__ Ag, long lda, const u16* __restrict__ Bg, long ldb, int nk, char* shm, Epi&& epi) {
;     ...
;   for (int i = 0; i < nk; ++i) {
;     if (i + 2 < nk) asm volatile("s_waitcnt vmcnt(8)" ::: "memory");
;     else if (i + 1 < nk) asm volatile("s_waitcnt vmcnt(4)" ::: "memory");
;     else asm volatile("s_waitcnt vmcnt(0)" ::: "memory");
;     __builtin_amdgcn_s_barrier();
;     const char* SA = shm + (i & 3) * 32768; const char* SB = SA + 16384;
;     bf16x8 At[8], Bt[4];
; #pragma unroll
;     for (int n = 0; n < 4; ++n) { const int rb = wc * 64 + n * 16 + fr; Bt[n] = *reinterpret_cast<const bf16x8*>(SB + rb * 64 + ((fq ^ ((rb >> 2) & 3)) * 16)); }
; #pragma unroll
;     for (int m = 0; m < 8; ++m) { const int ra = wr * 128 + m * 16 + fr; At[m] = *reinterpret_cast<const bf16x8*>(SA + ra * 64 + ((fq ^ ((ra >> 2) & 3)) * 16)); }
;     if (i + 3 < nk) stage(i + 3);
; #pragma unroll
;     for (int m = 0; m < 8; ++m)
; #pragma unroll
;       for (int n = 0; n < 4; ++n) acc[m][n] = __builtin_amdgcn_mfma_f32_16x16x32_bf16(Bt[n], At[m], acc[m][n], 0, 0, 0);
;   }
; DI void phase1(const Params& P, char* smem) {
;     ...
;         const int hd = c - 1536, b = r >> 13, l = r & 8191;
; #pragma unroll
;         for (int j = 0; j < 4; ++j) Vt[((long)(b * 512 + hd + j)) * 8192 + l] = f2bf(v[j]);
	ds_read_b128 v[216:219], v243 offset:0
	ds_read_b128 v[220:223], v212 offset:0
	ds_read_b128 v[224:227], v213 offset:0
	ds_read_b128 v[228:231], v187 offset:0
	s_waitcnt lgkmcnt(3)
	global_store_dwordx4 v[182:183], v[216:219], off
	s_nop 0
	v_lshl_add_u64 v[182:183], v[182:183], 0, s[38:39]
	s_waitcnt lgkmcnt(2)
	global_store_dwordx4 v[240:241], v[220:223], off
	s_nop 0
	v_lshl_add_u64 v[240:241], v[240:241], 0, s[38:39]
	s_waitcnt lgkmcnt(1)
	global_store_dwordx4 v[182:183], v[224:227], off
	s_nop 0
	v_lshl_add_u64 v[182:183], v[182:183], 0, s[38:39]
	s_waitcnt lgkmcnt(0)
	global_store_dwordx4 v[240:241], v[228:231], off
	s_nop 0
	v_lshl_add_u64 v[240:241], v[240:241], 0, s[38:39]
	ds_read_b128 v[232:235], v243 offset:4096
	ds_read_b128 v[236:239], v212 offset:4096
	ds_read_b128 v[244:247], v213 offset:4096
	ds_read_b128 v[248:251], v187 offset:4096
	s_waitcnt lgkmcnt(3)
	global_store_dwordx4 v[182:183], v[232:235], off
	s_nop 0
	v_lshl_add_u64 v[182:183], v[182:183], 0, s[38:39]
	s_waitcnt lgkmcnt(2)
	global_store_dwordx4 v[240:241], v[236:239], off
	s_nop 0
	v_lshl_add_u64 v[240:241], v[240:241], 0, s[38:39]
	s_waitcnt lgkmcnt(1)
	global_store_dwordx4 v[182:183], v[244:247], off
	s_nop 0
	v_lshl_add_u64 v[182:183], v[182:183], 0, s[38:39]
	s_waitcnt lgkmcnt(0)
	global_store_dwordx4 v[240:241], v[248:251], off
	s_nop 0
	v_lshl_add_u64 v[240:241], v[240:241], 0, s[38:39]
	ds_read_b128 v[216:219], v243 offset:8192
	ds_read_b128 v[220:223], v212 offset:8192
	ds_read_b128 v[224:227], v213 offset:8192
	ds_read_b128 v[228:231], v187 offset:8192
	s_waitcnt lgkmcnt(3)
	global_store_dwordx4 v[182:183], v[216:219], off
	s_nop 0
	v_lshl_add_u64 v[182:183], v[182:183], 0, s[38:39]
	s_waitcnt lgkmcnt(2)
	global_store_dwordx4 v[240:241], v[220:223], off
	s_nop 0
	v_lshl_add_u64 v[240:241], v[240:241], 0, s[38:39]
	s_waitcnt lgkmcnt(1)
	global_store_dwordx4 v[182:183], v[224:227], off
	s_nop 0
	v_lshl_add_u64 v[182:183], v[182:183], 0, s[38:39]
	s_waitcnt lgkmcnt(0)
	global_store_dwordx4 v[240:241], v[228:231], off
	s_nop 0
	v_lshl_add_u64 v[240:241], v[240:241], 0, s[38:39]
	ds_read_b128 v[232:235], v243 offset:12288
	ds_read_b128 v[236:239], v212 offset:12288
	ds_read_b128 v[244:247], v213 offset:12288
	ds_read_b128 v[248:251], v187 offset:12288
	s_waitcnt lgkmcnt(3)
	global_store_dwordx4 v[182:183], v[232:235], off
	s_nop 0
	v_lshl_add_u64 v[182:183], v[182:183], 0, s[38:39]
	s_waitcnt lgkmcnt(2)
	global_store_dwordx4 v[240:241], v[236:239], off
	s_nop 0
	v_lshl_add_u64 v[240:241], v[240:241], 0, s[38:39]
	s_waitcnt lgkmcnt(1)
	global_store_dwordx4 v[182:183], v[244:247], off
	s_nop 0
	v_lshl_add_u64 v[182:183], v[182:183], 0, s[38:39]
	s_waitcnt lgkmcnt(0)
	global_store_dwordx4 v[240:241], v[248:251], off
	s_nop 0
	v_lshl_add_u64 v[240:241], v[240:241], 0, s[38:39]
	v_or_b32_e32 v212, 0x50, v153
	v_or_b32_e32 v213, 0x60, v153
	s_branch .LBB0_106
.Lgemm_p1_n:
	s_waitcnt vmcnt(8)
	s_barrier
	v_add3_u32 v236, v205, v147, s8
	v_add3_u32 v215, v205, v151, s8
	s_nop 0
	ds_read_b128 v[216:219], v236 offset:16384
	ds_read_b128 v[220:223], v236 offset:17408
	ds_read_b128 v[232:235], v236 offset:18432
	ds_read_b128 v[236:239], v236 offset:19456
	ds_read_b128 v[224:227], v215
	ds_read_b128 v[228:231], v215 offset:1024
.Lgemm_p1_kloopn:
	s_add_i32 s6, s8, 0x18000
	s_and_b32 s6, s6, 0x18000
	s_add_i32 s9, s6, s7
	ds_read_b128 v[180:183], v215 offset:2048
	ds_read_b128 v[210:213], v215 offset:3072
	s_waitcnt lgkmcnt(2)
	v_mfma_f32_16x16x32_bf16 v[124:127], v[216:219], v[224:227], v[124:127]
	v_lshl_add_u64 v[206:207], v[184:185], 0, s[4:5]
	v_mfma_f32_16x16x32_bf16 v[120:123], v[220:223], v[224:227], v[120:123]
	s_mov_b32 m0, s9
	v_mfma_f32_16x16x32_bf16 v[116:119], v[232:235], v[224:227], v[116:119]
	s_add_i32 s9, s9, 0x2000
	v_mfma_f32_16x16x32_bf16 v[112:115], v[236:239], v[224:227], v[112:115]
	global_load_lds_dwordx4 v[206:207], off
	v_mfma_f32_16x16x32_bf16 v[108:111], v[216:219], v[228:231], v[108:111]
	v_mfma_f32_16x16x32_bf16 v[104:107], v[220:223], v[228:231], v[104:107]
	v_mfma_f32_16x16x32_bf16 v[100:103], v[232:235], v[228:231], v[100:103]
	v_mfma_f32_16x16x32_bf16 v[96:99], v[236:239], v[228:231], v[96:99]
	ds_read_b128 v[224:227], v215 offset:4096
	ds_read_b128 v[228:231], v215 offset:5120
	s_waitcnt lgkmcnt(2)
	v_mfma_f32_16x16x32_bf16 v[92:95], v[216:219], v[180:183], v[92:95]
	v_lshl_add_u64 v[206:207], v[186:187], 0, s[4:5]
	v_mfma_f32_16x16x32_bf16 v[88:91], v[220:223], v[180:183], v[88:91]
	s_mov_b32 m0, s9
	v_mfma_f32_16x16x32_bf16 v[84:87], v[232:235], v[180:183], v[84:87]
	s_add_i32 s9, s9, 0x2000
	v_mfma_f32_16x16x32_bf16 v[80:83], v[236:239], v[180:183], v[80:83]
	global_load_lds_dwordx4 v[206:207], off
	v_mfma_f32_16x16x32_bf16 v[76:79], v[216:219], v[210:213], v[76:79]
	v_mfma_f32_16x16x32_bf16 v[72:75], v[220:223], v[210:213], v[72:75]
	v_mfma_f32_16x16x32_bf16 v[68:71], v[232:235], v[210:213], v[68:71]
	v_mfma_f32_16x16x32_bf16 v[64:67], v[236:239], v[210:213], v[64:67]
	ds_read_b128 v[180:183], v215 offset:6144
	ds_read_b128 v[210:213], v215 offset:7168
	s_waitcnt lgkmcnt(2)
	v_mfma_f32_16x16x32_bf16 v[60:63], v[216:219], v[224:227], v[60:63]
	v_lshl_add_u64 v[206:207], v[172:173], 0, s[4:5]
	v_mfma_f32_16x16x32_bf16 v[56:59], v[220:223], v[224:227], v[56:59]
	s_mov_b32 m0, s9
	v_mfma_f32_16x16x32_bf16 v[52:55], v[232:235], v[224:227], v[52:55]
	s_add_i32 s9, s9, 0x2000
	v_mfma_f32_16x16x32_bf16 v[48:51], v[236:239], v[224:227], v[48:51]
	global_load_lds_dwordx4 v[206:207], off
	v_mfma_f32_16x16x32_bf16 v[44:47], v[216:219], v[228:231], v[44:47]
	v_mfma_f32_16x16x32_bf16 v[40:43], v[220:223], v[228:231], v[40:43]
	v_mfma_f32_16x16x32_bf16 v[36:39], v[232:235], v[228:231], v[36:39]
	v_mfma_f32_16x16x32_bf16 v[32:35], v[236:239], v[228:231], v[32:35]
	s_add_i32 s8, s8, 0x8000
	s_and_b32 s8, s8, 0x18000
	s_waitcnt vmcnt(7) lgkmcnt(0)
	s_barrier
; template <class Epi>
; DI void gemm_tile256(const u16* __restrict__ Ag, long lda, const u16* __restrict__ Bg, long ldb, int nk, char* shm, Epi&& epi) {
;     ...
;   for (int i = 0; i < nk; ++i) {
;     if (i + 2 < nk) asm volatile("s_waitcnt vmcnt(8)" ::: "memory");
;     else if (i + 1 < nk) asm volatile("s_waitcnt vmcnt(4)" ::: "memory");
;     else asm volatile("s_waitcnt vmcnt(0)" ::: "memory");
;     __builtin_amdgcn_s_barrier();
;     const char* SA = shm + (i & 3) * 32768; const char* SB = SA + 16384;
;     bf16x8 At[8], Bt[4];
; #pragma unroll
;     for (int n = 0; n < 4; ++n) { const int rb = wc * 64 + n * 16 + fr; Bt[n] = *reinterpret_cast<const bf16x8*>(SB + rb * 64 + ((fq ^ ((rb >> 2) & 3)) * 16)); }
; #pragma unroll
;     for (int m = 0; m < 8; ++m) { const int ra = wr * 128 + m * 16 + fr; At[m] = *reinterpret_cast<const bf16x8*>(SA + ra * 64 + ((fq ^ ((ra >> 2) & 3)) * 16)); }
;     if (i + 3 < nk) stage(i + 3);
; #pragma unroll
;     for (int m = 0; m < 8; ++m)
; #pragma unroll
;       for (int n = 0; n < 4; ++n) acc[m][n] = __builtin_amdgcn_mfma_f32_16x16x32_bf16(Bt[n], At[m], acc[m][n], 0, 0, 0);
;   }
	v_add3_u32 v176, v205, v147, s8
	v_add3_u32 v215, v205, v151, s8
	s_nop 0
	ds_read_b128 v[240:243], v176 offset:16384
	ds_read_b128 v[244:247], v176 offset:17408
	ds_read_b128 v[248:251], v176 offset:18432
	ds_read_b128 v[176:179], v176 offset:19456
	ds_read_b128 v[224:227], v215
	ds_read_b128 v[228:231], v215 offset:1024
	v_mfma_f32_16x16x32_bf16 v[28:31], v[216:219], v[180:183], v[28:31]
	v_lshl_add_u64 v[206:207], v[174:175], 0, s[4:5]
	v_mfma_f32_16x16x32_bf16 v[24:27], v[220:223], v[180:183], v[24:27]
	s_mov_b32 m0, s9
	v_mfma_f32_16x16x32_bf16 v[20:23], v[232:235], v[180:183], v[20:23]
	s_add_i32 s9, s9, 0x2000
	v_mfma_f32_16x16x32_bf16 v[16:19], v[236:239], v[180:183], v[16:19]
	global_load_lds_dwordx4 v[206:207], off
	v_mfma_f32_16x16x32_bf16 v[12:15], v[216:219], v[210:213], v[12:15]
	s_add_u32 s4, s4, 64
	v_mfma_f32_16x16x32_bf16 v[8:11], v[220:223], v[210:213], v[8:11]
	s_addc_u32 s5, s5, 0
	v_mfma_f32_16x16x32_bf16 v[4:7], v[232:235], v[210:213], v[4:7]
	v_mfma_f32_16x16x32_bf16 v[0:3], v[236:239], v[210:213], v[0:3]
	s_add_i32 s6, s8, 0x18000
	s_and_b32 s6, s6, 0x18000
	s_add_i32 s9, s6, s7
	ds_read_b128 v[180:183], v215 offset:2048
	ds_read_b128 v[210:213], v215 offset:3072
	s_waitcnt lgkmcnt(2)
	v_mfma_f32_16x16x32_bf16 v[124:127], v[240:243], v[224:227], v[124:127]
	v_lshl_add_u64 v[206:207], v[184:185], 0, s[4:5]
	v_mfma_f32_16x16x32_bf16 v[120:123], v[244:247], v[224:227], v[120:123]
	s_mov_b32 m0, s9
	v_mfma_f32_16x16x32_bf16 v[116:119], v[248:251], v[224:227], v[116:119]
	s_add_i32 s9, s9, 0x2000
	v_mfma_f32_16x16x32_bf16 v[112:115], v[176:179], v[224:227], v[112:115]
	global_load_lds_dwordx4 v[206:207], off
	v_mfma_f32_16x16x32_bf16 v[108:111], v[240:243], v[228:231], v[108:111]
	v_mfma_f32_16x16x32_bf16 v[104:107], v[244:247], v[228:231], v[104:107]
	v_mfma_f32_16x16x32_bf16 v[100:103], v[248:251], v[228:231], v[100:103]
	v_mfma_f32_16x16x32_bf16 v[96:99], v[176:179], v[228:231], v[96:99]
	ds_read_b128 v[224:227], v215 offset:4096
	ds_read_b128 v[228:231], v215 offset:5120
	s_waitcnt lgkmcnt(2)
	v_mfma_f32_16x16x32_bf16 v[92:95], v[240:243], v[180:183], v[92:95]
	v_lshl_add_u64 v[206:207], v[186:187], 0, s[4:5]
	v_mfma_f32_16x16x32_bf16 v[88:91], v[244:247], v[180:183], v[88:91]
	s_mov_b32 m0, s9
	v_mfma_f32_16x16x32_bf16 v[84:87], v[248:251], v[180:183], v[84:87]
	s_add_i32 s9, s9, 0x2000
	v_mfma_f32_16x16x32_bf16 v[80:83], v[176:179], v[180:183], v[80:83]
	global_load_lds_dwordx4 v[206:207], off
	v_mfma_f32_16x16x32_bf16 v[76:79], v[240:243], v[210:213], v[76:79]
	v_mfma_f32_16x16x32_bf16 v[72:75], v[244:247], v[210:213], v[72:75]
	v_mfma_f32_16x16x32_bf16 v[68:71], v[248:251], v[210:213], v[68:71]
	v_mfma_f32_16x16x32_bf16 v[64:67], v[176:179], v[210:213], v[64:67]
	ds_read_b128 v[180:183], v215 offset:6144
	ds_read_b128 v[210:213], v215 offset:7168
	s_waitcnt lgkmcnt(2)
	v_mfma_f32_16x16x32_bf16 v[60:63], v[240:243], v[224:227], v[60:63]
	v_lshl_add_u64 v[206:207], v[172:173], 0, s[4:5]
	v_mfma_f32_16x16x32_bf16 v[56:59], v[244:247], v[224:227], v[56:59]
	s_mov_b32 m0, s9
	v_mfma_f32_16x16x32_bf16 v[52:55], v[248:251], v[224:227], v[52:55]
	s_add_i32 s9, s9, 0x2000
	v_mfma_f32_16x16x32_bf16 v[48:51], v[176:179], v[224:227], v[48:51]
	global_load_lds_dwordx4 v[206:207], off
	v_mfma_f32_16x16x32_bf16 v[44:47], v[240:243], v[228:231], v[44:47]
	v_mfma_f32_16x16x32_bf16 v[40:43], v[244:247], v[228:231], v[40:43]
	v_mfma_f32_16x16x32_bf16 v[36:39], v[248:251], v[228:231], v[36:39]
	v_mfma_f32_16x16x32_bf16 v[32:35], v[176:179], v[228:231], v[32:35]
	s_add_i32 s8, s8, 0x8000
	s_and_b32 s8, s8, 0x18000
	s_waitcnt vmcnt(7) lgkmcnt(0)
	s_barrier
	v_add3_u32 v236, v205, v147, s8
	v_add3_u32 v215, v205, v151, s8
	s_nop 0
	ds_read_b128 v[216:219], v236 offset:16384
	ds_read_b128 v[220:223], v236 offset:17408
	ds_read_b128 v[232:235], v236 offset:18432
	ds_read_b128 v[236:239], v236 offset:19456
	ds_read_b128 v[224:227], v215
	ds_read_b128 v[228:231], v215 offset:1024
	v_mfma_f32_16x16x32_bf16 v[28:31], v[240:243], v[180:183], v[28:31]
	v_lshl_add_u64 v[206:207], v[174:175], 0, s[4:5]
	v_mfma_f32_16x16x32_bf16 v[24:27], v[244:247], v[180:183], v[24:27]
	s_mov_b32 m0, s9
	v_mfma_f32_16x16x32_bf16 v[20:23], v[248:251], v[180:183], v[20:23]
	s_add_i32 s9, s9, 0x2000
	v_mfma_f32_16x16x32_bf16 v[16:19], v[176:179], v[180:183], v[16:19]
	global_load_lds_dwordx4 v[206:207], off
	v_mfma_f32_16x16x32_bf16 v[12:15], v[240:243], v[210:213], v[12:15]
	s_add_u32 s4, s4, 64
	v_mfma_f32_16x16x32_bf16 v[8:11], v[244:247], v[210:213], v[8:11]
	s_addc_u32 s5, s5, 0
	v_mfma_f32_16x16x32_bf16 v[4:7], v[248:251], v[210:213], v[4:7]
	v_mfma_f32_16x16x32_bf16 v[0:3], v[176:179], v[210:213], v[0:3]
	s_cmpk_lg_i32 s4, 0x700
	s_cbranch_scc1 .Lgemm_p1_kloopn
; template <class Epi>
; DI void gemm_tile256(const u16* __restrict__ Ag, long lda, const u16* __restrict__ Bg, long ldb, int nk, char* shm, Epi&& epi) {
;     ...
;   for (int i = 0; i < nk; ++i) {
;     if (i + 2 < nk) asm volatile("s_waitcnt vmcnt(8)" ::: "memory");
;     else if (i + 1 < nk) asm volatile("s_waitcnt vmcnt(4)" ::: "memory");
;     else asm volatile("s_waitcnt vmcnt(0)" ::: "memory");
;     __builtin_amdgcn_s_barrier();
;     const char* SA = shm + (i & 3) * 32768; const char* SB = SA + 16384;
;     bf16x8 At[8], Bt[4];
; #pragma unroll
;     for (int n = 0; n < 4; ++n) { const int rb = wc * 64 + n * 16 + fr; Bt[n] = *reinterpret_cast<const bf16x8*>(SB + rb * 64 + ((fq ^ ((rb >> 2) & 3)) * 16)); }
; #pragma unroll
;     for (int m = 0; m < 8; ++m) { const int ra = wr * 128 + m * 16 + fr; At[m] = *reinterpret_cast<const bf16x8*>(SA + ra * 64 + ((fq ^ ((ra >> 2) & 3)) * 16)); }
;     if (i + 3 < nk) stage(i + 3);
; #pragma unroll
;     for (int m = 0; m < 8; ++m)
; #pragma unroll
;       for (int n = 0; n < 4; ++n) acc[m][n] = __builtin_amdgcn_mfma_f32_16x16x32_bf16(Bt[n], At[m], acc[m][n], 0, 0, 0);
;   }
	s_add_i32 s6, s8, 0x18000
	s_and_b32 s6, s6, 0x18000
	s_add_i32 s9, s6, s7
	ds_read_b128 v[180:183], v215 offset:2048
	ds_read_b128 v[210:213], v215 offset:3072
	s_waitcnt lgkmcnt(2)
	v_mfma_f32_16x16x32_bf16 v[124:127], v[216:219], v[224:227], v[124:127]
	v_lshl_add_u64 v[206:207], v[184:185], 0, s[4:5]
	v_mfma_f32_16x16x32_bf16 v[120:123], v[220:223], v[224:227], v[120:123]
	s_mov_b32 m0, s9
	v_mfma_f32_16x16x32_bf16 v[116:119], v[232:235], v[224:227], v[116:119]
	s_add_i32 s9, s9, 0x2000
	v_mfma_f32_16x16x32_bf16 v[112:115], v[236:239], v[224:227], v[112:115]
	global_load_lds_dwordx4 v[206:207], off
	v_mfma_f32_16x16x32_bf16 v[108:111], v[216:219], v[228:231], v[108:111]
	v_mfma_f32_16x16x32_bf16 v[104:107], v[220:223], v[228:231], v[104:107]
	v_mfma_f32_16x16x32_bf16 v[100:103], v[232:235], v[228:231], v[100:103]
	v_mfma_f32_16x16x32_bf16 v[96:99], v[236:239], v[228:231], v[96:99]
	ds_read_b128 v[224:227], v215 offset:4096
	ds_read_b128 v[228:231], v215 offset:5120
	s_waitcnt lgkmcnt(2)
	v_mfma_f32_16x16x32_bf16 v[92:95], v[216:219], v[180:183], v[92:95]
	v_lshl_add_u64 v[206:207], v[186:187], 0, s[4:5]
	v_mfma_f32_16x16x32_bf16 v[88:91], v[220:223], v[180:183], v[88:91]
	s_mov_b32 m0, s9
	v_mfma_f32_16x16x32_bf16 v[84:87], v[232:235], v[180:183], v[84:87]
	s_add_i32 s9, s9, 0x2000
	v_mfma_f32_16x16x32_bf16 v[80:83], v[236:239], v[180:183], v[80:83]
	global_load_lds_dwordx4 v[206:207], off
	v_mfma_f32_16x16x32_bf16 v[76:79], v[216:219], v[210:213], v[76:79]
	v_mfma_f32_16x16x32_bf16 v[72:75], v[220:223], v[210:213], v[72:75]
	v_mfma_f32_16x16x32_bf16 v[68:71], v[232:235], v[210:213], v[68:71]
	v_mfma_f32_16x16x32_bf16 v[64:67], v[236:239], v[210:213], v[64:67]
	ds_read_b128 v[180:183], v215 offset:6144
	ds_read_b128 v[210:213], v215 offset:7168
	s_waitcnt lgkmcnt(2)
	v_mfma_f32_16x16x32_bf16 v[60:63], v[216:219], v[224:227], v[60:63]
	v_lshl_add_u64 v[206:207], v[172:173], 0, s[4:5]
	v_mfma_f32_16x16x32_bf16 v[56:59], v[220:223], v[224:227], v[56:59]
	s_mov_b32 m0, s9
	v_mfma_f32_16x16x32_bf16 v[52:55], v[232:235], v[224:227], v[52:55]
	s_add_i32 s9, s9, 0x2000
	v_mfma_f32_16x16x32_bf16 v[48:51], v[236:239], v[224:227], v[48:51]
	global_load_lds_dwordx4 v[206:207], off
	v_mfma_f32_16x16x32_bf16 v[44:47], v[216:219], v[228:231], v[44:47]
	v_mfma_f32_16x16x32_bf16 v[40:43], v[220:223], v[228:231], v[40:43]
	v_mfma_f32_16x16x32_bf16 v[36:39], v[232:235], v[228:231], v[36:39]
	v_mfma_f32_16x16x32_bf16 v[32:35], v[236:239], v[228:231], v[32:35]
	s_add_i32 s8, s8, 0x8000
	s_and_b32 s8, s8, 0x18000
	s_waitcnt vmcnt(7) lgkmcnt(0)
	s_barrier
	v_add3_u32 v176, v205, v147, s8
	v_add3_u32 v215, v205, v151, s8
	s_nop 0
	ds_read_b128 v[240:243], v176 offset:16384
	ds_read_b128 v[244:247], v176 offset:17408
	ds_read_b128 v[248:251], v176 offset:18432
	ds_read_b128 v[176:179], v176 offset:19456
	ds_read_b128 v[224:227], v215
	ds_read_b128 v[228:231], v215 offset:1024
	v_mfma_f32_16x16x32_bf16 v[28:31], v[216:219], v[180:183], v[28:31]
	v_lshl_add_u64 v[206:207], v[174:175], 0, s[4:5]
	v_mfma_f32_16x16x32_bf16 v[24:27], v[220:223], v[180:183], v[24:27]
	s_mov_b32 m0, s9
	v_mfma_f32_16x16x32_bf16 v[20:23], v[232:235], v[180:183], v[20:23]
	s_add_i32 s9, s9, 0x2000
	v_mfma_f32_16x16x32_bf16 v[16:19], v[236:239], v[180:183], v[16:19]
	global_load_lds_dwordx4 v[206:207], off
	v_mfma_f32_16x16x32_bf16 v[12:15], v[216:219], v[210:213], v[12:15]
	s_add_u32 s4, s4, 64
	v_mfma_f32_16x16x32_bf16 v[8:11], v[220:223], v[210:213], v[8:11]
	s_addc_u32 s5, s5, 0
	v_mfma_f32_16x16x32_bf16 v[4:7], v[232:235], v[210:213], v[4:7]
	v_mfma_f32_16x16x32_bf16 v[0:3], v[236:239], v[210:213], v[0:3]
	ds_read_b128 v[180:183], v215 offset:2048
	ds_read_b128 v[210:213], v215 offset:3072
	s_waitcnt lgkmcnt(2)
	v_mfma_f32_16x16x32_bf16 v[124:127], v[240:243], v[224:227], v[124:127]
	v_mfma_f32_16x16x32_bf16 v[120:123], v[244:247], v[224:227], v[120:123]
	v_mfma_f32_16x16x32_bf16 v[116:119], v[248:251], v[224:227], v[116:119]
	v_mfma_f32_16x16x32_bf16 v[112:115], v[176:179], v[224:227], v[112:115]
	v_mfma_f32_16x16x32_bf16 v[108:111], v[240:243], v[228:231], v[108:111]
	v_mfma_f32_16x16x32_bf16 v[104:107], v[244:247], v[228:231], v[104:107]
	v_mfma_f32_16x16x32_bf16 v[100:103], v[248:251], v[228:231], v[100:103]
	v_mfma_f32_16x16x32_bf16 v[96:99], v[176:179], v[228:231], v[96:99]
	ds_read_b128 v[224:227], v215 offset:4096
	ds_read_b128 v[228:231], v215 offset:5120
	s_waitcnt lgkmcnt(2)
	v_mfma_f32_16x16x32_bf16 v[92:95], v[240:243], v[180:183], v[92:95]
	v_mfma_f32_16x16x32_bf16 v[88:91], v[244:247], v[180:183], v[88:91]
	v_mfma_f32_16x16x32_bf16 v[84:87], v[248:251], v[180:183], v[84:87]
	v_mfma_f32_16x16x32_bf16 v[80:83], v[176:179], v[180:183], v[80:83]
	v_mfma_f32_16x16x32_bf16 v[76:79], v[240:243], v[210:213], v[76:79]
	v_mfma_f32_16x16x32_bf16 v[72:75], v[244:247], v[210:213], v[72:75]
	v_mfma_f32_16x16x32_bf16 v[68:71], v[248:251], v[210:213], v[68:71]
	v_mfma_f32_16x16x32_bf16 v[64:67], v[176:179], v[210:213], v[64:67]
	ds_read_b128 v[180:183], v215 offset:6144
	ds_read_b128 v[210:213], v215 offset:7168
	s_waitcnt lgkmcnt(2)
	v_mfma_f32_16x16x32_bf16 v[60:63], v[240:243], v[224:227], v[60:63]
	v_mfma_f32_16x16x32_bf16 v[56:59], v[244:247], v[224:227], v[56:59]
	v_mfma_f32_16x16x32_bf16 v[52:55], v[248:251], v[224:227], v[52:55]
	v_mfma_f32_16x16x32_bf16 v[48:51], v[176:179], v[224:227], v[48:51]
	v_mfma_f32_16x16x32_bf16 v[44:47], v[240:243], v[228:231], v[44:47]
	v_mfma_f32_16x16x32_bf16 v[40:43], v[244:247], v[228:231], v[40:43]
	v_mfma_f32_16x16x32_bf16 v[36:39], v[248:251], v[228:231], v[36:39]
	v_mfma_f32_16x16x32_bf16 v[32:35], v[176:179], v[228:231], v[32:35]
	s_add_i32 s8, s8, 0x8000
	s_and_b32 s8, s8, 0x18000
	s_waitcnt vmcnt(4) lgkmcnt(0)
	s_barrier
; template <class Epi>
; DI void gemm_tile256(const u16* __restrict__ Ag, long lda, const u16* __restrict__ Bg, long ldb, int nk, char* shm, Epi&& epi) {
;     ...
;   for (int i = 0; i < nk; ++i) {
;     if (i + 2 < nk) asm volatile("s_waitcnt vmcnt(8)" ::: "memory");
;     else if (i + 1 < nk) asm volatile("s_waitcnt vmcnt(4)" ::: "memory");
;     else asm volatile("s_waitcnt vmcnt(0)" ::: "memory");
;     __builtin_amdgcn_s_barrier();
;     const char* SA = shm + (i & 3) * 32768; const char* SB = SA + 16384;
;     bf16x8 At[8], Bt[4];
; #pragma unroll
;     for (int n = 0; n < 4; ++n) { const int rb = wc * 64 + n * 16 + fr; Bt[n] = *reinterpret_cast<const bf16x8*>(SB + rb * 64 + ((fq ^ ((rb >> 2) & 3)) * 16)); }
; #pragma unroll
;     for (int m = 0; m < 8; ++m) { const int ra = wr * 128 + m * 16 + fr; At[m] = *reinterpret_cast<const bf16x8*>(SA + ra * 64 + ((fq ^ ((ra >> 2) & 3)) * 16)); }
;     if (i + 3 < nk) stage(i + 3);
; #pragma unroll
;     for (int m = 0; m < 8; ++m)
; #pragma unroll
;       for (int n = 0; n < 4; ++n) acc[m][n] = __builtin_amdgcn_mfma_f32_16x16x32_bf16(Bt[n], At[m], acc[m][n], 0, 0, 0);
;   }
;   __syncthreads();
	v_add3_u32 v236, v205, v147, s8
	v_add3_u32 v215, v205, v151, s8
	s_nop 0
	ds_read_b128 v[216:219], v236 offset:16384
	ds_read_b128 v[220:223], v236 offset:17408
	ds_read_b128 v[232:235], v236 offset:18432
	ds_read_b128 v[236:239], v236 offset:19456
	ds_read_b128 v[224:227], v215
	ds_read_b128 v[228:231], v215 offset:1024
	v_mfma_f32_16x16x32_bf16 v[28:31], v[240:243], v[180:183], v[28:31]
	v_mfma_f32_16x16x32_bf16 v[24:27], v[244:247], v[180:183], v[24:27]
	v_mfma_f32_16x16x32_bf16 v[20:23], v[248:251], v[180:183], v[20:23]
	v_mfma_f32_16x16x32_bf16 v[16:19], v[176:179], v[180:183], v[16:19]
	v_mfma_f32_16x16x32_bf16 v[12:15], v[240:243], v[210:213], v[12:15]
	v_mfma_f32_16x16x32_bf16 v[8:11], v[244:247], v[210:213], v[8:11]
	v_mfma_f32_16x16x32_bf16 v[4:7], v[248:251], v[210:213], v[4:7]
	v_mfma_f32_16x16x32_bf16 v[0:3], v[176:179], v[210:213], v[0:3]
	ds_read_b128 v[180:183], v215 offset:2048
	ds_read_b128 v[210:213], v215 offset:3072
	s_waitcnt lgkmcnt(2)
	v_mfma_f32_16x16x32_bf16 v[124:127], v[216:219], v[224:227], v[124:127]
	v_mfma_f32_16x16x32_bf16 v[120:123], v[220:223], v[224:227], v[120:123]
	v_mfma_f32_16x16x32_bf16 v[116:119], v[232:235], v[224:227], v[116:119]
	v_mfma_f32_16x16x32_bf16 v[112:115], v[236:239], v[224:227], v[112:115]
	v_mfma_f32_16x16x32_bf16 v[108:111], v[216:219], v[228:231], v[108:111]
	v_mfma_f32_16x16x32_bf16 v[104:107], v[220:223], v[228:231], v[104:107]
	v_mfma_f32_16x16x32_bf16 v[100:103], v[232:235], v[228:231], v[100:103]
	v_mfma_f32_16x16x32_bf16 v[96:99], v[236:239], v[228:231], v[96:99]
	ds_read_b128 v[224:227], v215 offset:4096
	ds_read_b128 v[228:231], v215 offset:5120
	s_waitcnt lgkmcnt(2)
	v_mfma_f32_16x16x32_bf16 v[92:95], v[216:219], v[180:183], v[92:95]
	v_mfma_f32_16x16x32_bf16 v[88:91], v[220:223], v[180:183], v[88:91]
	v_mfma_f32_16x16x32_bf16 v[84:87], v[232:235], v[180:183], v[84:87]
	v_mfma_f32_16x16x32_bf16 v[80:83], v[236:239], v[180:183], v[80:83]
	v_mfma_f32_16x16x32_bf16 v[76:79], v[216:219], v[210:213], v[76:79]
	v_mfma_f32_16x16x32_bf16 v[72:75], v[220:223], v[210:213], v[72:75]
	v_mfma_f32_16x16x32_bf16 v[68:71], v[232:235], v[210:213], v[68:71]
	v_mfma_f32_16x16x32_bf16 v[64:67], v[236:239], v[210:213], v[64:67]
	ds_read_b128 v[180:183], v215 offset:6144
	ds_read_b128 v[210:213], v215 offset:7168
	s_waitcnt lgkmcnt(2)
	v_mfma_f32_16x16x32_bf16 v[60:63], v[216:219], v[224:227], v[60:63]
	v_mfma_f32_16x16x32_bf16 v[56:59], v[220:223], v[224:227], v[56:59]
	v_mfma_f32_16x16x32_bf16 v[52:55], v[232:235], v[224:227], v[52:55]
	v_mfma_f32_16x16x32_bf16 v[48:51], v[236:239], v[224:227], v[48:51]
	v_mfma_f32_16x16x32_bf16 v[44:47], v[216:219], v[228:231], v[44:47]
	v_mfma_f32_16x16x32_bf16 v[40:43], v[220:223], v[228:231], v[40:43]
	v_mfma_f32_16x16x32_bf16 v[36:39], v[232:235], v[228:231], v[36:39]
	v_mfma_f32_16x16x32_bf16 v[32:35], v[236:239], v[228:231], v[32:35]
	s_add_i32 s8, s8, 0x8000
	s_and_b32 s8, s8, 0x18000
	s_waitcnt vmcnt(0) lgkmcnt(0)
	s_barrier
	v_add3_u32 v176, v205, v147, s8
	v_add3_u32 v215, v205, v151, s8
	s_nop 0
	ds_read_b128 v[240:243], v176 offset:16384
	ds_read_b128 v[244:247], v176 offset:17408
	ds_read_b128 v[248:251], v176 offset:18432
	ds_read_b128 v[176:179], v176 offset:19456
	ds_read_b128 v[224:227], v215
	ds_read_b128 v[228:231], v215 offset:1024
	v_mfma_f32_16x16x32_bf16 v[28:31], v[216:219], v[180:183], v[28:31]
	v_mfma_f32_16x16x32_bf16 v[24:27], v[220:223], v[180:183], v[24:27]
	v_mfma_f32_16x16x32_bf16 v[20:23], v[232:235], v[180:183], v[20:23]
	v_mfma_f32_16x16x32_bf16 v[16:19], v[236:239], v[180:183], v[16:19]
	v_mfma_f32_16x16x32_bf16 v[12:15], v[216:219], v[210:213], v[12:15]
	v_mfma_f32_16x16x32_bf16 v[8:11], v[220:223], v[210:213], v[8:11]
	v_mfma_f32_16x16x32_bf16 v[4:7], v[232:235], v[210:213], v[4:7]
	v_mfma_f32_16x16x32_bf16 v[0:3], v[236:239], v[210:213], v[0:3]
	ds_read_b128 v[180:183], v215 offset:2048
	ds_read_b128 v[210:213], v215 offset:3072
	s_waitcnt lgkmcnt(2)
	v_mfma_f32_16x16x32_bf16 v[124:127], v[240:243], v[224:227], v[124:127]
	v_mfma_f32_16x16x32_bf16 v[120:123], v[244:247], v[224:227], v[120:123]
	v_mfma_f32_16x16x32_bf16 v[116:119], v[248:251], v[224:227], v[116:119]
	v_mfma_f32_16x16x32_bf16 v[112:115], v[176:179], v[224:227], v[112:115]
	v_mfma_f32_16x16x32_bf16 v[108:111], v[240:243], v[228:231], v[108:111]
	v_mfma_f32_16x16x32_bf16 v[104:107], v[244:247], v[228:231], v[104:107]
	v_mfma_f32_16x16x32_bf16 v[100:103], v[248:251], v[228:231], v[100:103]
	v_mfma_f32_16x16x32_bf16 v[96:99], v[176:179], v[228:231], v[96:99]
	ds_read_b128 v[224:227], v215 offset:4096
	ds_read_b128 v[228:231], v215 offset:5120
	s_waitcnt lgkmcnt(2)
	v_mfma_f32_16x16x32_bf16 v[92:95], v[240:243], v[180:183], v[92:95]
	v_mfma_f32_16x16x32_bf16 v[88:91], v[244:247], v[180:183], v[88:91]
	v_mfma_f32_16x16x32_bf16 v[84:87], v[248:251], v[180:183], v[84:87]
	v_mfma_f32_16x16x32_bf16 v[80:83], v[176:179], v[180:183], v[80:83]
	v_mfma_f32_16x16x32_bf16 v[76:79], v[240:243], v[210:213], v[76:79]
	v_mfma_f32_16x16x32_bf16 v[72:75], v[244:247], v[210:213], v[72:75]
	v_mfma_f32_16x16x32_bf16 v[68:71], v[248:251], v[210:213], v[68:71]
	v_mfma_f32_16x16x32_bf16 v[64:67], v[176:179], v[210:213], v[64:67]
	ds_read_b128 v[180:183], v215 offset:6144
	ds_read_b128 v[210:213], v215 offset:7168
	s_waitcnt lgkmcnt(2)
	v_mfma_f32_16x16x32_bf16 v[60:63], v[240:243], v[224:227], v[60:63]
	v_mfma_f32_16x16x32_bf16 v[56:59], v[244:247], v[224:227], v[56:59]
	v_mfma_f32_16x16x32_bf16 v[52:55], v[248:251], v[224:227], v[52:55]
	v_mfma_f32_16x16x32_bf16 v[48:51], v[176:179], v[224:227], v[48:51]
	v_mfma_f32_16x16x32_bf16 v[44:47], v[240:243], v[228:231], v[44:47]
	v_mfma_f32_16x16x32_bf16 v[40:43], v[244:247], v[228:231], v[40:43]
	v_mfma_f32_16x16x32_bf16 v[36:39], v[248:251], v[228:231], v[36:39]
	v_mfma_f32_16x16x32_bf16 v[32:35], v[176:179], v[228:231], v[32:35]
	s_waitcnt lgkmcnt(0)
	v_mfma_f32_16x16x32_bf16 v[28:31], v[240:243], v[180:183], v[28:31]
	v_mfma_f32_16x16x32_bf16 v[24:27], v[244:247], v[180:183], v[24:27]
	v_mfma_f32_16x16x32_bf16 v[20:23], v[248:251], v[180:183], v[20:23]
	v_mfma_f32_16x16x32_bf16 v[16:19], v[176:179], v[180:183], v[16:19]
	v_mfma_f32_16x16x32_bf16 v[12:15], v[240:243], v[210:213], v[12:15]
	v_mfma_f32_16x16x32_bf16 v[8:11], v[244:247], v[210:213], v[8:11]
	v_mfma_f32_16x16x32_bf16 v[4:7], v[248:251], v[210:213], v[4:7]
	v_mfma_f32_16x16x32_bf16 v[0:3], v[176:179], v[210:213], v[0:3]
	s_nop 7
	s_nop 3
	s_and_b64 vcc, exec, s[10:11]
	s_cbranch_vccz .Lgemm_p1_u
; template <class Epi>
; DI void gemm_tile256(const u16* __restrict__ Ag, long lda, const u16* __restrict__ Bg, long ldb, int nk, char* shm, Epi&& epi) {
;     ...
;   __syncthreads();
; #pragma unroll
;   for (int m = 0; m < 8; ++m)
; #pragma unroll
;     for (int n = 0; n < 4; ++n) epi(wr * 128 + m * 16 + fr, wc * 64 + n * 16 + fq * 4, acc[m][n]);
; DI void phase1(const Params& P, char* smem) {
;     ...
;       } else if (bcol < 1024) {
;         *reinterpret_cast<uint2*>(Qb + (long)r * 512 + (c - 512)) = pk;
;       } else if (bcol < 1536) {
;         *reinterpret_cast<uint2*>(Kb + (long)r * 512 + (c - 1024)) = pk;
	s_waitcnt vmcnt(0) lgkmcnt(0)
	s_barrier
	v_and_b32_e32 v184, 15, v208
	v_lshrrev_b32_e32 v185, 4, v208
	v_lshrrev_b32_e32 v186, 6, v189
	v_lshlrev_b32_e32 v186, 14, v186
	v_and_b32_e32 v187, 7, v184
	v_lshrrev_b32_e32 v206, 1, v185
	v_and_b32_e32 v207, 1, v185
	v_lshl_add_u32 v215, v184, 7, v186
	v_lshl_add_u32 v215, v207, 3, v215
	v_or_b32_e32 v252, 0, v206
	v_xor_b32_e32 v252, v252, v187
	v_lshl_add_u32 v176, v252, 4, v215
	v_or_b32_e32 v252, 2, v206
	v_xor_b32_e32 v252, v252, v187
	v_lshl_add_u32 v177, v252, 4, v215
	v_or_b32_e32 v252, 4, v206
	v_xor_b32_e32 v252, v252, v187
	v_lshl_add_u32 v178, v252, 4, v215
	v_or_b32_e32 v252, 6, v206
	v_xor_b32_e32 v252, v252, v187
	v_lshl_add_u32 v179, v252, 4, v215
	v_lshrrev_b32_e32 v253, 3, v208
	v_and_b32_e32 v210, 7, v208
	v_xor_b32_e32 v252, v210, v253
	v_lshl_add_u32 v180, v253, 7, v186
	v_lshl_add_u32 v180, v252, 4, v180
	v_lshl_add_u32 v252, v190, 7, v253
	v_add_u32_e32 v252, s30, v252
	v_lshlrev_b32_e32 v182, 10, v252
	v_bfe_u32 v252, v189, 6, 2
	v_lshl_add_u32 v182, v252, 7, v182
	v_lshl_add_u32 v182, v210, 4, v182
	v_mov_b32_e32 v183, 0
	s_and_b32 s36, s74, 1
	s_lshl_b32 s36, s36, 9
	s_and_b32 s37, s74, 4
	s_lshl_b32 s37, s37, 23
	s_add_u32 s36, s36, s37
	s_add_u32 s36, s78, s36
	s_addc_u32 s37, s79, 0
	v_lshl_add_u64 v[182:183], v[182:183], 0, s[36:37]
	s_mov_b32 s38, 0x2000
	s_mov_b32 s39, 0
	v_lshl_add_u64 v[240:241], v[182:183], 0, s[38:39]
	s_lshl_b32 s38, s38, 1
	v_cvt_pk_bf16_f32 v124, v124, v125
	v_cvt_pk_bf16_f32 v125, v126, v127
	ds_write_b64 v176, v[124:125] offset:0
	v_cvt_pk_bf16_f32 v120, v120, v121
	v_cvt_pk_bf16_f32 v121, v122, v123
	ds_write_b64 v177, v[120:121] offset:0
	v_cvt_pk_bf16_f32 v116, v116, v117
	v_cvt_pk_bf16_f32 v117, v118, v119
	ds_write_b64 v178, v[116:117] offset:0
	v_cvt_pk_bf16_f32 v112, v112, v113
	v_cvt_pk_bf16_f32 v113, v114, v115
	ds_write_b64 v179, v[112:113] offset:0
	v_cvt_pk_bf16_f32 v108, v108, v109
	v_cvt_pk_bf16_f32 v109, v110, v111
	ds_write_b64 v176, v[108:109] offset:2048
	v_cvt_pk_bf16_f32 v104, v104, v105
	v_cvt_pk_bf16_f32 v105, v106, v107
	ds_write_b64 v177, v[104:105] offset:2048
	v_cvt_pk_bf16_f32 v100, v100, v101
	v_cvt_pk_bf16_f32 v101, v102, v103
	ds_write_b64 v178, v[100:101] offset:2048
	v_cvt_pk_bf16_f32 v96, v96, v97
	v_cvt_pk_bf16_f32 v97, v98, v99
	ds_write_b64 v179, v[96:97] offset:2048
	v_cvt_pk_bf16_f32 v92, v92, v93
	v_cvt_pk_bf16_f32 v93, v94, v95
	ds_write_b64 v176, v[92:93] offset:4096
	v_cvt_pk_bf16_f32 v88, v88, v89
	v_cvt_pk_bf16_f32 v89, v90, v91
	ds_write_b64 v177, v[88:89] offset:4096
	v_cvt_pk_bf16_f32 v84, v84, v85
	v_cvt_pk_bf16_f32 v85, v86, v87
	ds_write_b64 v178, v[84:85] offset:4096
	v_cvt_pk_bf16_f32 v80, v80, v81
	v_cvt_pk_bf16_f32 v81, v82, v83
	ds_write_b64 v179, v[80:81] offset:4096
	v_cvt_pk_bf16_f32 v76, v76, v77
	v_cvt_pk_bf16_f32 v77, v78, v79
	ds_write_b64 v176, v[76:77] offset:6144
	v_cvt_pk_bf16_f32 v72, v72, v73
	v_cvt_pk_bf16_f32 v73, v74, v75
	ds_write_b64 v177, v[72:73] offset:6144
	v_cvt_pk_bf16_f32 v68, v68, v69
	v_cvt_pk_bf16_f32 v69, v70, v71
	ds_write_b64 v178, v[68:69] offset:6144
	v_cvt_pk_bf16_f32 v64, v64, v65
	v_cvt_pk_bf16_f32 v65, v66, v67
	ds_write_b64 v179, v[64:65] offset:6144
	v_cvt_pk_bf16_f32 v60, v60, v61
	v_cvt_pk_bf16_f32 v61, v62, v63
	ds_write_b64 v176, v[60:61] offset:8192
	v_cvt_pk_bf16_f32 v56, v56, v57
	v_cvt_pk_bf16_f32 v57, v58, v59
	ds_write_b64 v177, v[56:57] offset:8192
	v_cvt_pk_bf16_f32 v52, v52, v53
	v_cvt_pk_bf16_f32 v53, v54, v55
	ds_write_b64 v178, v[52:53] offset:8192
	v_cvt_pk_bf16_f32 v48, v48, v49
	v_cvt_pk_bf16_f32 v49, v50, v51
	ds_write_b64 v179, v[48:49] offset:8192
	v_cvt_pk_bf16_f32 v44, v44, v45
	v_cvt_pk_bf16_f32 v45, v46, v47
	ds_write_b64 v176, v[44:45] offset:10240
	v_cvt_pk_bf16_f32 v40, v40, v41
	v_cvt_pk_bf16_f32 v41, v42, v43
	ds_write_b64 v177, v[40:41] offset:10240
	v_cvt_pk_bf16_f32 v36, v36, v37
	v_cvt_pk_bf16_f32 v37, v38, v39
	ds_write_b64 v178, v[36:37] offset:10240
	v_cvt_pk_bf16_f32 v32, v32, v33
	v_cvt_pk_bf16_f32 v33, v34, v35
	ds_write_b64 v179, v[32:33] offset:10240
	v_cvt_pk_bf16_f32 v28, v28, v29
	v_cvt_pk_bf16_f32 v29, v30, v31
	ds_write_b64 v176, v[28:29] offset:12288
	v_cvt_pk_bf16_f32 v24, v24, v25
	v_cvt_pk_bf16_f32 v25, v26, v27
	ds_write_b64 v177, v[24:25] offset:12288
	v_cvt_pk_bf16_f32 v20, v20, v21
	v_cvt_pk_bf16_f32 v21, v22, v23
	ds_write_b64 v178, v[20:21] offset:12288
	v_cvt_pk_bf16_f32 v16, v16, v17
	v_cvt_pk_bf16_f32 v17, v18, v19
	ds_write_b64 v179, v[16:17] offset:12288
	v_cvt_pk_bf16_f32 v12, v12, v13
	v_cvt_pk_bf16_f32 v13, v14, v15
	ds_write_b64 v176, v[12:13] offset:14336
	v_cvt_pk_bf16_f32 v8, v8, v9
	v_cvt_pk_bf16_f32 v9, v10, v11
	ds_write_b64 v177, v[8:9] offset:14336
	v_cvt_pk_bf16_f32 v4, v4, v5
	v_cvt_pk_bf16_f32 v5, v6, v7
	ds_write_b64 v178, v[4:5] offset:14336
	v_cvt_pk_bf16_f32 v0, v0, v1
	v_cvt_pk_bf16_f32 v1, v2, v3
	ds_write_b64 v179, v[0:1] offset:14336
	s_waitcnt lgkmcnt(0)
; DI void phase1(const Params& P, char* smem) {
;     ...
;       } else if (bcol < 1024) {
;         *reinterpret_cast<uint2*>(Qb + (long)r * 512 + (c - 512)) = pk;
;       } else if (bcol < 1536) {
;         *reinterpret_cast<uint2*>(Kb + (long)r * 512 + (c - 1024)) = pk;
	ds_read_b128 v[216:219], v180 offset:0
	ds_read_b128 v[220:223], v180 offset:1024
	ds_read_b128 v[224:227], v180 offset:2048
	ds_read_b128 v[228:231], v180 offset:3072
	s_waitcnt lgkmcnt(3)
	global_store_dwordx4 v[182:183], v[216:219], off
	s_nop 0
	v_lshl_add_u64 v[182:183], v[182:183], 0, s[38:39]
	s_waitcnt lgkmcnt(2)
	global_store_dwordx4 v[240:241], v[220:223], off
	s_nop 0
	v_lshl_add_u64 v[240:241], v[240:241], 0, s[38:39]
	s_waitcnt lgkmcnt(1)
	global_store_dwordx4 v[182:183], v[224:227], off
	s_nop 0
	v_lshl_add_u64 v[182:183], v[182:183], 0, s[38:39]
	s_waitcnt lgkmcnt(0)
	global_store_dwordx4 v[240:241], v[228:231], off
	s_nop 0
	v_lshl_add_u64 v[240:241], v[240:241], 0, s[38:39]
	ds_read_b128 v[232:235], v180 offset:4096
	ds_read_b128 v[236:239], v180 offset:5120
	ds_read_b128 v[244:247], v180 offset:6144
	ds_read_b128 v[248:251], v180 offset:7168
	s_waitcnt lgkmcnt(3)
	global_store_dwordx4 v[182:183], v[232:235], off
	s_nop 0
	v_lshl_add_u64 v[182:183], v[182:183], 0, s[38:39]
	s_waitcnt lgkmcnt(2)
	global_store_dwordx4 v[240:241], v[236:239], off
	s_nop 0
	v_lshl_add_u64 v[240:241], v[240:241], 0, s[38:39]
	s_waitcnt lgkmcnt(1)
	global_store_dwordx4 v[182:183], v[244:247], off
	s_nop 0
	v_lshl_add_u64 v[182:183], v[182:183], 0, s[38:39]
	s_waitcnt lgkmcnt(0)
	global_store_dwordx4 v[240:241], v[248:251], off
	s_nop 0
	v_lshl_add_u64 v[240:241], v[240:241], 0, s[38:39]
	ds_read_b128 v[216:219], v180 offset:8192
	ds_read_b128 v[220:223], v180 offset:9216
	ds_read_b128 v[224:227], v180 offset:10240
	ds_read_b128 v[228:231], v180 offset:11264
	s_waitcnt lgkmcnt(3)
	global_store_dwordx4 v[182:183], v[216:219], off
	s_nop 0
	v_lshl_add_u64 v[182:183], v[182:183], 0, s[38:39]
	s_waitcnt lgkmcnt(2)
	global_store_dwordx4 v[240:241], v[220:223], off
	s_nop 0
	v_lshl_add_u64 v[240:241], v[240:241], 0, s[38:39]
	s_waitcnt lgkmcnt(1)
	global_store_dwordx4 v[182:183], v[224:227], off
	s_nop 0
	v_lshl_add_u64 v[182:183], v[182:183], 0, s[38:39]
	s_waitcnt lgkmcnt(0)
	global_store_dwordx4 v[240:241], v[228:231], off
	s_nop 0
	v_lshl_add_u64 v[240:241], v[240:241], 0, s[38:39]
	ds_read_b128 v[232:235], v180 offset:12288
	ds_read_b128 v[236:239], v180 offset:13312
	ds_read_b128 v[244:247], v180 offset:14336
	ds_read_b128 v[248:251], v180 offset:15360
	s_waitcnt lgkmcnt(3)
	global_store_dwordx4 v[182:183], v[232:235], off
	s_nop 0
	v_lshl_add_u64 v[182:183], v[182:183], 0, s[38:39]
	s_waitcnt lgkmcnt(2)
	global_store_dwordx4 v[240:241], v[236:239], off
	s_nop 0
	v_lshl_add_u64 v[240:241], v[240:241], 0, s[38:39]
	s_waitcnt lgkmcnt(1)
	global_store_dwordx4 v[182:183], v[244:247], off
	s_nop 0
	v_lshl_add_u64 v[182:183], v[182:183], 0, s[38:39]
	s_waitcnt lgkmcnt(0)
	global_store_dwordx4 v[240:241], v[248:251], off
	s_nop 0
	v_lshl_add_u64 v[240:241], v[240:241], 0, s[38:39]
	v_or_b32_e32 v212, 0x50, v153
	v_or_b32_e32 v213, 0x60, v153
	s_branch .LBB0_106

; template <class Epi>
; DI void gemm_tile256(const u16* __restrict__ Ag, long lda, const u16* __restrict__ Bg, long ldb, int nk, char* shm, Epi&& epi) {
;     ...
;   const int q0 = tid, q1 = 512 + tid;
;   const int r0 = q0 >> 2, r1 = q1 >> 2, c0 = (q0 & 3) ^ ((r0 >> 2) & 3), c1 = (q1 & 3) ^ ((r1 >> 2) & 3);
;   const u16* a0 = Ag + (long)r0 * lda + c0 * 8; const u16* a1 = Ag + (long)r1 * lda + c1 * 8;
;   const u16* b0 = Bg + (long)r0 * ldb + c0 * 8; const u16* b1 = Bg + (long)r1 * ldb + c1 * 8;
;   auto stage = [&](int j) {
;     char* SA = shm + (j & 3) * 32768; char* SB = SA + 16384;
;     __builtin_amdgcn_global_load_lds((const unsigned*)(a0 + j * 32), (__attribute__((address_space(3))) unsigned*)(SA + q0 * 16), 16, 0, 0);
;     __builtin_amdgcn_global_load_lds((const unsigned*)(a1 + j * 32), (__attribute__((address_space(3))) unsigned*)(SA + q1 * 16), 16, 0, 0);
;     __builtin_amdgcn_global_load_lds((const unsigned*)(b0 + j * 32), (__attribute__((address_space(3))) unsigned*)(SB + q0 * 16), 16, 0, 0);
;     __builtin_amdgcn_global_load_lds((const unsigned*)(b1 + j * 32), (__attribute__((address_space(3))) unsigned*)(SB + q1 * 16), 16, 0, 0);
;   };
;   __syncthreads();
;   stage(0);
;   if (nk > 1) stage(1);
;   if (nk > 2) stage(2);
; DI void phase6(const Params& P, char* smem) {
;     ...
;   for (int q = RBLK >> 3; q < 64; q += RGRID >> 3) {
;     const int brow = (q * 2 + ((RBLK & 7) >> 2)) * 256, bcol = (RBLK & 3) * 256;
;     gemm_tile256(cat + (long)brow * 1024, 1024, WoT + (long)bcol * 1024, 1024, 32, smem, [&](int row, int col0, f32x4 v) {
.LBB0_946:
	s_ashr_i32 s5, s4, 31
	s_lshl_b64 s[10:11], s[4:5], 11
	s_lshl_b32 s5, s15, 9
	v_lshl_add_u64 v[164:165], v[156:157], 0, s[10:11]
	v_lshl_add_u64 v[166:167], v[158:159], 0, s[10:11]
	s_or_b32 s10, s5, s2
	s_ashr_i32 s11, s10, 31
	s_lshl_b64 s[12:13], s[10:11], 11
	s_add_u32 s12, s62, s12
	s_addc_u32 s13, s63, s13
	v_add_u32_e32 v6, 0, v209
	v_lshl_add_u64 v[0:1], s[12:13], 0, v[130:131]
	v_readfirstlane_b32 s5, v6
	v_add_u32_e32 v7, 0, v149
	v_lshl_add_u64 v[0:1], v[0:1], 0, v[132:133]
	v_lshl_add_u64 v[2:3], s[12:13], 0, v[134:135]
	s_mov_b32 m0, s5
	v_readfirstlane_b32 s5, v7
	v_add_u32_e32 v4, 0x4000, v6
	v_lshl_add_u64 v[2:3], v[2:3], 0, v[132:133]
	s_barrier
	global_load_lds_dwordx4 v[0:1], off
	s_mov_b32 m0, s5
	v_readfirstlane_b32 s5, v4
	v_add_u32_e32 v4, 0x4000, v7
	global_load_lds_dwordx4 v[2:3], off
	s_mov_b32 m0, s5
	v_readfirstlane_b32 s5, v4
	v_add_u32_e32 v8, 0x8000, v6
	global_load_lds_dwordx4 v[136:137], off
	s_mov_b32 m0, s5
	v_readfirstlane_b32 s5, v8
	v_add_u32_e32 v8, 0x8000, v7
	global_load_lds_dwordx4 v[138:139], off
	v_lshl_add_u64 v[4:5], v[0:1], 0, 64
	s_mov_b32 m0, s5
	v_readfirstlane_b32 s5, v8
	global_load_lds_dwordx4 v[4:5], off
	v_lshl_add_u64 v[4:5], v[2:3], 0, 64
	s_mov_b32 m0, s5
	v_lshl_add_u64 v[0:1], v[0:1], 0, s[0:1]
	global_load_lds_dwordx4 v[4:5], off
	v_add_u32_e32 v4, 0xc000, v6
	s_mov_b64 s[12:13], 0
	v_readfirstlane_b32 s5, v4
	v_add_u32_e32 v4, 0xc000, v7
	s_mov_b32 m0, s5
	v_readfirstlane_b32 s5, v4
	v_add_u32_e32 v4, s7, v209
	global_load_lds_dwordx4 v[140:141], off
	s_mov_b32 m0, s5
	v_readfirstlane_b32 s5, v4
	global_load_lds_dwordx4 v[142:143], off
	s_mov_b32 m0, s5
	v_mov_b32_e32 v4, 0
	global_load_lds_dwordx4 v[0:1], off
	v_lshl_add_u64 v[0:1], v[2:3], 0, s[0:1]
	v_add_u32_e32 v2, s7, v149
	v_mov_b32_e32 v3, v133
	v_readfirstlane_b32 s5, v2
	s_mov_b32 m0, s5
	v_mov_b32_e32 v2, v133
	global_load_lds_dwordx4 v[0:1], off
	v_add_u32_e32 v0, s8, v209
	v_mov_b32_e32 v1, v133
	v_readfirstlane_b32 s5, v0
	v_add_u32_e32 v0, s8, v149
	s_mov_b32 m0, s5
	v_readfirstlane_b32 s5, v0
	global_load_lds_dwordx4 v[144:145], off
	s_mov_b32 m0, s5
	s_mov_b32 s5, 0x18000
	global_load_lds_dwordx4 v[146:147], off
	v_mov_b32_e32 v0, 0
	v_mov_b32_e32 v5, v133
	v_mov_b32_e32 v6, v133
	v_mov_b32_e32 v7, v133
	v_mov_b32_e32 v8, 0
	v_mov_b32_e32 v9, v133
	v_mov_b32_e32 v10, v133
	v_mov_b32_e32 v11, v133
	v_mov_b32_e32 v12, 0
	v_mov_b32_e32 v13, v133
	v_mov_b32_e32 v14, v133
	v_mov_b32_e32 v15, v133
	v_mov_b32_e32 v16, 0
	v_mov_b32_e32 v17, v133
	v_mov_b32_e32 v18, v133
	v_mov_b32_e32 v19, v133
	v_mov_b32_e32 v20, 0
	v_mov_b32_e32 v21, v133
	v_mov_b32_e32 v22, v133
	v_mov_b32_e32 v23, v133
	v_mov_b32_e32 v24, 0
	v_mov_b32_e32 v25, v133
	v_mov_b32_e32 v26, v133
	v_mov_b32_e32 v27, v133
	v_mov_b32_e32 v28, 0
	v_mov_b32_e32 v29, v133
	v_mov_b32_e32 v30, v133
	v_mov_b32_e32 v31, v133
	v_mov_b32_e32 v32, 0
	v_mov_b32_e32 v33, v133
	v_mov_b32_e32 v34, v133
	v_mov_b32_e32 v35, v133
	v_mov_b32_e32 v36, 0
	v_mov_b32_e32 v37, v133
	v_mov_b32_e32 v38, v133
	v_mov_b32_e32 v39, v133
	v_mov_b32_e32 v40, 0
	v_mov_b32_e32 v41, v133
	v_mov_b32_e32 v42, v133
	v_mov_b32_e32 v43, v133
	v_mov_b32_e32 v44, 0
	v_mov_b32_e32 v45, v133
	v_mov_b32_e32 v46, v133
	v_mov_b32_e32 v47, v133
	v_mov_b32_e32 v48, 0
	v_mov_b32_e32 v49, v133
	v_mov_b32_e32 v50, v133
	v_mov_b32_e32 v51, v133
	v_mov_b32_e32 v52, 0
	v_mov_b32_e32 v53, v133
	v_mov_b32_e32 v54, v133
	v_mov_b32_e32 v55, v133
	v_mov_b32_e32 v56, 0
	v_mov_b32_e32 v57, v133
	v_mov_b32_e32 v58, v133
	v_mov_b32_e32 v59, v133
	v_mov_b32_e32 v60, 0
	v_mov_b32_e32 v61, v133
	v_mov_b32_e32 v62, v133
	v_mov_b32_e32 v63, v133
	v_mov_b32_e32 v64, 0
	v_mov_b32_e32 v65, v133
	v_mov_b32_e32 v66, v133
	v_mov_b32_e32 v67, v133
	v_mov_b32_e32 v68, 0
	v_mov_b32_e32 v69, v133
	v_mov_b32_e32 v70, v133
	v_mov_b32_e32 v71, v133
	v_mov_b32_e32 v72, 0
	v_mov_b32_e32 v73, v133
	v_mov_b32_e32 v74, v133
	v_mov_b32_e32 v75, v133
	v_mov_b32_e32 v76, 0
	v_mov_b32_e32 v77, v133
	v_mov_b32_e32 v78, v133
	v_mov_b32_e32 v79, v133
	v_mov_b32_e32 v80, 0
	v_mov_b32_e32 v81, v133
	v_mov_b32_e32 v82, v133
	v_mov_b32_e32 v83, v133
	v_mov_b32_e32 v84, 0
	v_mov_b32_e32 v85, v133
	v_mov_b32_e32 v86, v133
	v_mov_b32_e32 v87, v133
	v_mov_b32_e32 v88, 0
	v_mov_b32_e32 v89, v133
	v_mov_b32_e32 v90, v133
	v_mov_b32_e32 v91, v133
	v_mov_b32_e32 v92, 0
	v_mov_b32_e32 v93, v133
	v_mov_b32_e32 v94, v133
	v_mov_b32_e32 v95, v133
	v_mov_b32_e32 v96, 0
	v_mov_b32_e32 v97, v133
	v_mov_b32_e32 v98, v133
	v_mov_b32_e32 v99, v133
	v_mov_b32_e32 v100, 0
	v_mov_b32_e32 v101, v133
	v_mov_b32_e32 v102, v133
	v_mov_b32_e32 v103, v133
	v_mov_b32_e32 v104, 0
	v_mov_b32_e32 v105, v133
	v_mov_b32_e32 v106, v133
	v_mov_b32_e32 v107, v133
	v_mov_b32_e32 v108, 0
	v_mov_b32_e32 v109, v133
	v_mov_b32_e32 v110, v133
	v_mov_b32_e32 v111, v133
	v_mov_b32_e32 v112, 0
	v_mov_b32_e32 v113, v133
	v_mov_b32_e32 v114, v133
	v_mov_b32_e32 v115, v133
	v_mov_b32_e32 v116, 0
	v_mov_b32_e32 v117, v133
	v_mov_b32_e32 v118, v133
	v_mov_b32_e32 v119, v133
	v_mov_b32_e32 v120, 0
	v_mov_b32_e32 v121, v133
	v_mov_b32_e32 v122, v133
	v_mov_b32_e32 v123, v133
	v_mov_b32_e32 v124, 0
	v_mov_b32_e32 v125, v133
	v_mov_b32_e32 v126, v133
	v_mov_b32_e32 v127, v133
	v_readfirstlane_b32 s16, v209
	s_mov_b32 s5, 0
	s_mov_b64 s[12:13], 0
	v_readfirstlane_b32 s26, v164
	v_readfirstlane_b32 s27, v165
	v_readfirstlane_b32 s28, v166
	v_readfirstlane_b32 s29, v167
	v_readfirstlane_b32 s30, v160
	v_readfirstlane_b32 s31, v161
	v_readfirstlane_b32 s32, v162
	v_readfirstlane_b32 s33, v163
	s_sub_u32 s26, s26, 64
	s_subb_u32 s27, s27, 0
	v_subrev_u32_e32 v226, s26, v164
	s_sub_u32 s28, s28, 64
	s_subb_u32 s29, s29, 0
	v_subrev_u32_e32 v227, s28, v166
	s_sub_u32 s30, s30, 64
	s_subb_u32 s31, s31, 0
	v_subrev_u32_e32 v228, s30, v160
	s_sub_u32 s32, s32, 64
	s_subb_u32 s33, s33, 0
	v_subrev_u32_e32 v229, s32, v162
	s_waitcnt vmcnt(8)
	s_barrier
	v_add3_u32 v218, v183, v151, s5
	v_add3_u32 v230, v183, v153, s5
	s_nop 0
	ds_read_b128 v[196:199], v218 offset:16384
	ds_read_b128 v[200:203], v218 offset:17408
	ds_read_b128 v[214:217], v218 offset:18432
	ds_read_b128 v[218:221], v218 offset:19456
	ds_read_b128 v[204:207], v230
	ds_read_b128 v[210:213], v230 offset:1024
; template <class Epi>
; DI void gemm_tile256(const u16* __restrict__ Ag, long lda, const u16* __restrict__ Bg, long ldb, int nk, char* shm, Epi&& epi) {
;     ...
;   for (int i = 0; i < nk; ++i) {
;     if (i + 2 < nk) asm volatile("s_waitcnt vmcnt(8)" ::: "memory");
;     else if (i + 1 < nk) asm volatile("s_waitcnt vmcnt(4)" ::: "memory");
;     else asm volatile("s_waitcnt vmcnt(0)" ::: "memory");
;     __builtin_amdgcn_s_barrier();
;     const char* SA = shm + (i & 3) * 32768; const char* SB = SA + 16384;
;     bf16x8 At[8], Bt[4];
; #pragma unroll
;     for (int n = 0; n < 4; ++n) { const int rb = wc * 64 + n * 16 + fr; Bt[n] = *reinterpret_cast<const bf16x8*>(SB + rb * 64 + ((fq ^ ((rb >> 2) & 3)) * 16)); }
; #pragma unroll
;     for (int m = 0; m < 8; ++m) { const int ra = wr * 128 + m * 16 + fr; At[m] = *reinterpret_cast<const bf16x8*>(SA + ra * 64 + ((fq ^ ((ra >> 2) & 3)) * 16)); }
;     if (i + 3 < nk) stage(i + 3);
; #pragma unroll
;     for (int m = 0; m < 8; ++m)
; #pragma unroll
;       for (int n = 0; n < 4; ++n) acc[m][n] = __builtin_amdgcn_mfma_f32_16x16x32_bf16(Bt[n], At[m], acc[m][n], 0, 0, 0);
;   }
.Lgemm_p6_kloop0:
	s_add_i32 s11, s5, 0x18000
	s_and_b32 s11, s11, 0x18000
	s_add_i32 s17, s11, s16
	ds_read_b128 v[248:251], v230 offset:2048
	ds_read_b128 v[222:225], v230 offset:3072
	s_waitcnt lgkmcnt(2)
	v_mfma_f32_16x16x32_bf16 v[124:127], v[196:199], v[204:207], v[124:127]
	v_lshl_add_u64 v[226:227], v[164:165], 0, s[12:13]
	v_mfma_f32_16x16x32_bf16 v[120:123], v[200:203], v[204:207], v[120:123]
	s_mov_b32 m0, s17
	v_mfma_f32_16x16x32_bf16 v[116:119], v[214:217], v[204:207], v[116:119]
	s_add_i32 s17, s17, 0x2000
	v_mfma_f32_16x16x32_bf16 v[112:115], v[218:221], v[204:207], v[112:115]
	global_load_lds_dwordx4 v[226:227], off
	v_mfma_f32_16x16x32_bf16 v[108:111], v[196:199], v[210:213], v[108:111]
	v_mfma_f32_16x16x32_bf16 v[104:107], v[200:203], v[210:213], v[104:107]
	v_mfma_f32_16x16x32_bf16 v[100:103], v[214:217], v[210:213], v[100:103]
	v_mfma_f32_16x16x32_bf16 v[96:99], v[218:221], v[210:213], v[96:99]
	ds_read_b128 v[204:207], v230 offset:4096
	ds_read_b128 v[210:213], v230 offset:5120
	s_waitcnt lgkmcnt(2)
	v_mfma_f32_16x16x32_bf16 v[92:95], v[196:199], v[248:251], v[92:95]
	v_lshl_add_u64 v[226:227], v[166:167], 0, s[12:13]
	v_mfma_f32_16x16x32_bf16 v[88:91], v[200:203], v[248:251], v[88:91]
	s_mov_b32 m0, s17
	v_mfma_f32_16x16x32_bf16 v[84:87], v[214:217], v[248:251], v[84:87]
	s_add_i32 s17, s17, 0x2000
	v_mfma_f32_16x16x32_bf16 v[80:83], v[218:221], v[248:251], v[80:83]
	global_load_lds_dwordx4 v[226:227], off
	v_mfma_f32_16x16x32_bf16 v[76:79], v[196:199], v[222:225], v[76:79]
	v_mfma_f32_16x16x32_bf16 v[72:75], v[200:203], v[222:225], v[72:75]
	v_mfma_f32_16x16x32_bf16 v[68:71], v[214:217], v[222:225], v[68:71]
	v_mfma_f32_16x16x32_bf16 v[64:67], v[218:221], v[222:225], v[64:67]
	ds_read_b128 v[248:251], v230 offset:6144
	ds_read_b128 v[222:225], v230 offset:7168
	s_waitcnt lgkmcnt(2)
	v_mfma_f32_16x16x32_bf16 v[60:63], v[196:199], v[204:207], v[60:63]
	v_lshl_add_u64 v[226:227], v[160:161], 0, s[12:13]
	v_mfma_f32_16x16x32_bf16 v[56:59], v[200:203], v[204:207], v[56:59]
	s_mov_b32 m0, s17
	v_mfma_f32_16x16x32_bf16 v[52:55], v[214:217], v[204:207], v[52:55]
	s_add_i32 s17, s17, 0x2000
	v_mfma_f32_16x16x32_bf16 v[48:51], v[218:221], v[204:207], v[48:51]
	global_load_lds_dwordx4 v[226:227], off
	v_mfma_f32_16x16x32_bf16 v[44:47], v[196:199], v[210:213], v[44:47]
	v_mfma_f32_16x16x32_bf16 v[40:43], v[200:203], v[210:213], v[40:43]
	v_mfma_f32_16x16x32_bf16 v[36:39], v[214:217], v[210:213], v[36:39]
	v_mfma_f32_16x16x32_bf16 v[32:35], v[218:221], v[210:213], v[32:35]
	s_add_i32 s5, s5, 0x8000
	s_and_b32 s5, s5, 0x18000
	s_waitcnt vmcnt(7) lgkmcnt(0)
	s_barrier
	v_add3_u32 v244, v183, v151, s5
	v_add3_u32 v230, v183, v153, s5
	s_nop 0
	ds_read_b128 v[232:235], v244 offset:16384
	ds_read_b128 v[236:239], v244 offset:17408
	ds_read_b128 v[240:243], v244 offset:18432
	ds_read_b128 v[244:247], v244 offset:19456
	ds_read_b128 v[204:207], v230
	ds_read_b128 v[210:213], v230 offset:1024
	v_mfma_f32_16x16x32_bf16 v[28:31], v[196:199], v[248:251], v[28:31]
	v_lshl_add_u64 v[226:227], v[162:163], 0, s[12:13]
	v_mfma_f32_16x16x32_bf16 v[24:27], v[200:203], v[248:251], v[24:27]
	s_mov_b32 m0, s17
	v_mfma_f32_16x16x32_bf16 v[20:23], v[214:217], v[248:251], v[20:23]
	s_add_i32 s17, s17, 0x2000
	v_mfma_f32_16x16x32_bf16 v[16:19], v[218:221], v[248:251], v[16:19]
	global_load_lds_dwordx4 v[226:227], off
	v_mfma_f32_16x16x32_bf16 v[12:15], v[196:199], v[222:225], v[12:15]
	s_add_u32 s12, s12, 64
	v_mfma_f32_16x16x32_bf16 v[8:11], v[200:203], v[222:225], v[8:11]
	s_addc_u32 s13, s13, 0
	v_mfma_f32_16x16x32_bf16 v[4:7], v[214:217], v[222:225], v[4:7]
	v_mfma_f32_16x16x32_bf16 v[0:3], v[218:221], v[222:225], v[0:3]
	s_add_i32 s11, s5, 0x18000
	s_and_b32 s11, s11, 0x18000
	s_add_i32 s17, s11, s16
	ds_read_b128 v[248:251], v230 offset:2048
	ds_read_b128 v[222:225], v230 offset:3072
	s_waitcnt lgkmcnt(2)
	v_mfma_f32_16x16x32_bf16 v[124:127], v[232:235], v[204:207], v[124:127]
	v_lshl_add_u64 v[226:227], v[164:165], 0, s[12:13]
	v_mfma_f32_16x16x32_bf16 v[120:123], v[236:239], v[204:207], v[120:123]
	s_mov_b32 m0, s17
	v_mfma_f32_16x16x32_bf16 v[116:119], v[240:243], v[204:207], v[116:119]
	s_add_i32 s17, s17, 0x2000
	v_mfma_f32_16x16x32_bf16 v[112:115], v[244:247], v[204:207], v[112:115]
	global_load_lds_dwordx4 v[226:227], off
	v_mfma_f32_16x16x32_bf16 v[108:111], v[232:235], v[210:213], v[108:111]
	v_mfma_f32_16x16x32_bf16 v[104:107], v[236:239], v[210:213], v[104:107]
	v_mfma_f32_16x16x32_bf16 v[100:103], v[240:243], v[210:213], v[100:103]
	v_mfma_f32_16x16x32_bf16 v[96:99], v[244:247], v[210:213], v[96:99]
	ds_read_b128 v[204:207], v230 offset:4096
	ds_read_b128 v[210:213], v230 offset:5120
	s_waitcnt lgkmcnt(2)
	v_mfma_f32_16x16x32_bf16 v[92:95], v[232:235], v[248:251], v[92:95]
	v_lshl_add_u64 v[226:227], v[166:167], 0, s[12:13]
	v_mfma_f32_16x16x32_bf16 v[88:91], v[236:239], v[248:251], v[88:91]
	s_mov_b32 m0, s17
	v_mfma_f32_16x16x32_bf16 v[84:87], v[240:243], v[248:251], v[84:87]
	s_add_i32 s17, s17, 0x2000
	v_mfma_f32_16x16x32_bf16 v[80:83], v[244:247], v[248:251], v[80:83]
	global_load_lds_dwordx4 v[226:227], off
	v_mfma_f32_16x16x32_bf16 v[76:79], v[232:235], v[222:225], v[76:79]
	v_mfma_f32_16x16x32_bf16 v[72:75], v[236:239], v[222:225], v[72:75]
	v_mfma_f32_16x16x32_bf16 v[68:71], v[240:243], v[222:225], v[68:71]
	v_mfma_f32_16x16x32_bf16 v[64:67], v[244:247], v[222:225], v[64:67]
	ds_read_b128 v[248:251], v230 offset:6144
	ds_read_b128 v[222:225], v230 offset:7168
	s_waitcnt lgkmcnt(2)
	v_mfma_f32_16x16x32_bf16 v[60:63], v[232:235], v[204:207], v[60:63]
	v_lshl_add_u64 v[226:227], v[160:161], 0, s[12:13]
	v_mfma_f32_16x16x32_bf16 v[56:59], v[236:239], v[204:207], v[56:59]
	s_mov_b32 m0, s17
	v_mfma_f32_16x16x32_bf16 v[52:55], v[240:243], v[204:207], v[52:55]
	s_add_i32 s17, s17, 0x2000
	v_mfma_f32_16x16x32_bf16 v[48:51], v[244:247], v[204:207], v[48:51]
	global_load_lds_dwordx4 v[226:227], off
	v_mfma_f32_16x16x32_bf16 v[44:47], v[232:235], v[210:213], v[44:47]
	v_mfma_f32_16x16x32_bf16 v[40:43], v[236:239], v[210:213], v[40:43]
	v_mfma_f32_16x16x32_bf16 v[36:39], v[240:243], v[210:213], v[36:39]
	v_mfma_f32_16x16x32_bf16 v[32:35], v[244:247], v[210:213], v[32:35]
	s_add_i32 s5, s5, 0x8000
	s_and_b32 s5, s5, 0x18000
	s_waitcnt vmcnt(7) lgkmcnt(0)
	s_barrier
; template <class Epi>
; DI void gemm_tile256(const u16* __restrict__ Ag, long lda, const u16* __restrict__ Bg, long ldb, int nk, char* shm, Epi&& epi) {
;     ...
;   for (int i = 0; i < nk; ++i) {
;     if (i + 2 < nk) asm volatile("s_waitcnt vmcnt(8)" ::: "memory");
;     else if (i + 1 < nk) asm volatile("s_waitcnt vmcnt(4)" ::: "memory");
;     else asm volatile("s_waitcnt vmcnt(0)" ::: "memory");
;     __builtin_amdgcn_s_barrier();
;     const char* SA = shm + (i & 3) * 32768; const char* SB = SA + 16384;
;     bf16x8 At[8], Bt[4];
; #pragma unroll
;     for (int n = 0; n < 4; ++n) { const int rb = wc * 64 + n * 16 + fr; Bt[n] = *reinterpret_cast<const bf16x8*>(SB + rb * 64 + ((fq ^ ((rb >> 2) & 3)) * 16)); }
; #pragma unroll
;     for (int m = 0; m < 8; ++m) { const int ra = wr * 128 + m * 16 + fr; At[m] = *reinterpret_cast<const bf16x8*>(SA + ra * 64 + ((fq ^ ((ra >> 2) & 3)) * 16)); }
;     if (i + 3 < nk) stage(i + 3);
; #pragma unroll
;     for (int m = 0; m < 8; ++m)
; #pragma unroll
;       for (int n = 0; n < 4; ++n) acc[m][n] = __builtin_amdgcn_mfma_f32_16x16x32_bf16(Bt[n], At[m], acc[m][n], 0, 0, 0);
;   }
	v_add3_u32 v218, v183, v151, s5
	v_add3_u32 v230, v183, v153, s5
	s_nop 0
	ds_read_b128 v[196:199], v218 offset:16384
	ds_read_b128 v[200:203], v218 offset:17408
	ds_read_b128 v[214:217], v218 offset:18432
	ds_read_b128 v[218:221], v218 offset:19456
	ds_read_b128 v[204:207], v230
	ds_read_b128 v[210:213], v230 offset:1024
	v_mfma_f32_16x16x32_bf16 v[28:31], v[232:235], v[248:251], v[28:31]
	v_lshl_add_u64 v[226:227], v[162:163], 0, s[12:13]
	v_mfma_f32_16x16x32_bf16 v[24:27], v[236:239], v[248:251], v[24:27]
	s_mov_b32 m0, s17
	v_mfma_f32_16x16x32_bf16 v[20:23], v[240:243], v[248:251], v[20:23]
	s_add_i32 s17, s17, 0x2000
	v_mfma_f32_16x16x32_bf16 v[16:19], v[244:247], v[248:251], v[16:19]
	global_load_lds_dwordx4 v[226:227], off
	v_mfma_f32_16x16x32_bf16 v[12:15], v[232:235], v[222:225], v[12:15]
	s_add_u32 s12, s12, 64
	v_mfma_f32_16x16x32_bf16 v[8:11], v[236:239], v[222:225], v[8:11]
	s_addc_u32 s13, s13, 0
	v_mfma_f32_16x16x32_bf16 v[4:7], v[240:243], v[222:225], v[4:7]
	v_mfma_f32_16x16x32_bf16 v[0:3], v[244:247], v[222:225], v[0:3]
	s_cmpk_lg_i32 s12, 0x700
	s_cbranch_scc1 .Lgemm_p6_kloop0
	s_add_i32 s11, s5, 0x18000
	s_and_b32 s11, s11, 0x18000
	s_add_i32 s17, s11, s16
	ds_read_b128 v[248:251], v230 offset:2048
	ds_read_b128 v[222:225], v230 offset:3072
	s_waitcnt lgkmcnt(2)
	v_mfma_f32_16x16x32_bf16 v[124:127], v[196:199], v[204:207], v[124:127]
	v_lshl_add_u64 v[226:227], v[164:165], 0, s[12:13]
	v_mfma_f32_16x16x32_bf16 v[120:123], v[200:203], v[204:207], v[120:123]
	s_mov_b32 m0, s17
	v_mfma_f32_16x16x32_bf16 v[116:119], v[214:217], v[204:207], v[116:119]
	s_add_i32 s17, s17, 0x2000
	v_mfma_f32_16x16x32_bf16 v[112:115], v[218:221], v[204:207], v[112:115]
	global_load_lds_dwordx4 v[226:227], off
	v_mfma_f32_16x16x32_bf16 v[108:111], v[196:199], v[210:213], v[108:111]
	v_mfma_f32_16x16x32_bf16 v[104:107], v[200:203], v[210:213], v[104:107]
	v_mfma_f32_16x16x32_bf16 v[100:103], v[214:217], v[210:213], v[100:103]
	v_mfma_f32_16x16x32_bf16 v[96:99], v[218:221], v[210:213], v[96:99]
	ds_read_b128 v[204:207], v230 offset:4096
	ds_read_b128 v[210:213], v230 offset:5120
	s_waitcnt lgkmcnt(2)
	v_mfma_f32_16x16x32_bf16 v[92:95], v[196:199], v[248:251], v[92:95]
	v_lshl_add_u64 v[226:227], v[166:167], 0, s[12:13]
	v_mfma_f32_16x16x32_bf16 v[88:91], v[200:203], v[248:251], v[88:91]
	s_mov_b32 m0, s17
	v_mfma_f32_16x16x32_bf16 v[84:87], v[214:217], v[248:251], v[84:87]
	s_add_i32 s17, s17, 0x2000
	v_mfma_f32_16x16x32_bf16 v[80:83], v[218:221], v[248:251], v[80:83]
	global_load_lds_dwordx4 v[226:227], off
	v_mfma_f32_16x16x32_bf16 v[76:79], v[196:199], v[222:225], v[76:79]
	v_mfma_f32_16x16x32_bf16 v[72:75], v[200:203], v[222:225], v[72:75]
	v_mfma_f32_16x16x32_bf16 v[68:71], v[214:217], v[222:225], v[68:71]
	v_mfma_f32_16x16x32_bf16 v[64:67], v[218:221], v[222:225], v[64:67]
	ds_read_b128 v[248:251], v230 offset:6144
	ds_read_b128 v[222:225], v230 offset:7168
	s_waitcnt lgkmcnt(2)
	v_mfma_f32_16x16x32_bf16 v[60:63], v[196:199], v[204:207], v[60:63]
	v_lshl_add_u64 v[226:227], v[160:161], 0, s[12:13]
	v_mfma_f32_16x16x32_bf16 v[56:59], v[200:203], v[204:207], v[56:59]
	s_mov_b32 m0, s17
	v_mfma_f32_16x16x32_bf16 v[52:55], v[214:217], v[204:207], v[52:55]
	s_add_i32 s17, s17, 0x2000
	v_mfma_f32_16x16x32_bf16 v[48:51], v[218:221], v[204:207], v[48:51]
	global_load_lds_dwordx4 v[226:227], off
	v_mfma_f32_16x16x32_bf16 v[44:47], v[196:199], v[210:213], v[44:47]
	v_mfma_f32_16x16x32_bf16 v[40:43], v[200:203], v[210:213], v[40:43]
	v_mfma_f32_16x16x32_bf16 v[36:39], v[214:217], v[210:213], v[36:39]
	v_mfma_f32_16x16x32_bf16 v[32:35], v[218:221], v[210:213], v[32:35]
	s_add_i32 s5, s5, 0x8000
	s_and_b32 s5, s5, 0x18000
	s_waitcnt vmcnt(7) lgkmcnt(0)
	s_barrier
	v_add3_u32 v244, v183, v151, s5
	v_add3_u32 v230, v183, v153, s5
	s_nop 0
	ds_read_b128 v[232:235], v244 offset:16384
	ds_read_b128 v[236:239], v244 offset:17408
	ds_read_b128 v[240:243], v244 offset:18432
	ds_read_b128 v[244:247], v244 offset:19456
	ds_read_b128 v[204:207], v230
	ds_read_b128 v[210:213], v230 offset:1024
	v_mfma_f32_16x16x32_bf16 v[28:31], v[196:199], v[248:251], v[28:31]
	v_lshl_add_u64 v[226:227], v[162:163], 0, s[12:13]
	v_mfma_f32_16x16x32_bf16 v[24:27], v[200:203], v[248:251], v[24:27]
	s_mov_b32 m0, s17
	v_mfma_f32_16x16x32_bf16 v[20:23], v[214:217], v[248:251], v[20:23]
	s_add_i32 s17, s17, 0x2000
	v_mfma_f32_16x16x32_bf16 v[16:19], v[218:221], v[248:251], v[16:19]
	global_load_lds_dwordx4 v[226:227], off
	v_mfma_f32_16x16x32_bf16 v[12:15], v[196:199], v[222:225], v[12:15]
	s_add_u32 s12, s12, 64
	v_mfma_f32_16x16x32_bf16 v[8:11], v[200:203], v[222:225], v[8:11]
	s_addc_u32 s13, s13, 0
	v_mfma_f32_16x16x32_bf16 v[4:7], v[214:217], v[222:225], v[4:7]
	v_mfma_f32_16x16x32_bf16 v[0:3], v[218:221], v[222:225], v[0:3]
	ds_read_b128 v[248:251], v230 offset:2048
	ds_read_b128 v[222:225], v230 offset:3072
	s_waitcnt lgkmcnt(2)
	v_mfma_f32_16x16x32_bf16 v[124:127], v[232:235], v[204:207], v[124:127]
	v_mfma_f32_16x16x32_bf16 v[120:123], v[236:239], v[204:207], v[120:123]
	v_mfma_f32_16x16x32_bf16 v[116:119], v[240:243], v[204:207], v[116:119]
	v_mfma_f32_16x16x32_bf16 v[112:115], v[244:247], v[204:207], v[112:115]
	v_mfma_f32_16x16x32_bf16 v[108:111], v[232:235], v[210:213], v[108:111]
	v_mfma_f32_16x16x32_bf16 v[104:107], v[236:239], v[210:213], v[104:107]
	v_mfma_f32_16x16x32_bf16 v[100:103], v[240:243], v[210:213], v[100:103]
	v_mfma_f32_16x16x32_bf16 v[96:99], v[244:247], v[210:213], v[96:99]
	ds_read_b128 v[204:207], v230 offset:4096
	ds_read_b128 v[210:213], v230 offset:5120
	s_waitcnt lgkmcnt(2)
	v_mfma_f32_16x16x32_bf16 v[92:95], v[232:235], v[248:251], v[92:95]
	v_mfma_f32_16x16x32_bf16 v[88:91], v[236:239], v[248:251], v[88:91]
	v_mfma_f32_16x16x32_bf16 v[84:87], v[240:243], v[248:251], v[84:87]
	v_mfma_f32_16x16x32_bf16 v[80:83], v[244:247], v[248:251], v[80:83]
	v_mfma_f32_16x16x32_bf16 v[76:79], v[232:235], v[222:225], v[76:79]
	v_mfma_f32_16x16x32_bf16 v[72:75], v[236:239], v[222:225], v[72:75]
	v_mfma_f32_16x16x32_bf16 v[68:71], v[240:243], v[222:225], v[68:71]
	v_mfma_f32_16x16x32_bf16 v[64:67], v[244:247], v[222:225], v[64:67]
	ds_read_b128 v[248:251], v230 offset:6144
	ds_read_b128 v[222:225], v230 offset:7168
	s_waitcnt lgkmcnt(2)
	v_mfma_f32_16x16x32_bf16 v[60:63], v[232:235], v[204:207], v[60:63]
	v_mfma_f32_16x16x32_bf16 v[56:59], v[236:239], v[204:207], v[56:59]
	v_mfma_f32_16x16x32_bf16 v[52:55], v[240:243], v[204:207], v[52:55]
	v_mfma_f32_16x16x32_bf16 v[48:51], v[244:247], v[204:207], v[48:51]
	v_mfma_f32_16x16x32_bf16 v[44:47], v[232:235], v[210:213], v[44:47]
	v_mfma_f32_16x16x32_bf16 v[40:43], v[236:239], v[210:213], v[40:43]
	v_mfma_f32_16x16x32_bf16 v[36:39], v[240:243], v[210:213], v[36:39]
	v_mfma_f32_16x16x32_bf16 v[32:35], v[244:247], v[210:213], v[32:35]
	s_add_i32 s5, s5, 0x8000
	s_and_b32 s5, s5, 0x18000
	s_waitcnt vmcnt(4) lgkmcnt(0)
	s_barrier
; template <class Epi>
; DI void gemm_tile256(const u16* __restrict__ Ag, long lda, const u16* __restrict__ Bg, long ldb, int nk, char* shm, Epi&& epi) {
;     ...
;   for (int i = 0; i < nk; ++i) {
;     if (i + 2 < nk) asm volatile("s_waitcnt vmcnt(8)" ::: "memory");
;     else if (i + 1 < nk) asm volatile("s_waitcnt vmcnt(4)" ::: "memory");
;     else asm volatile("s_waitcnt vmcnt(0)" ::: "memory");
;     __builtin_amdgcn_s_barrier();
;     const char* SA = shm + (i & 3) * 32768; const char* SB = SA + 16384;
;     bf16x8 At[8], Bt[4];
; #pragma unroll
;     for (int n = 0; n < 4; ++n) { const int rb = wc * 64 + n * 16 + fr; Bt[n] = *reinterpret_cast<const bf16x8*>(SB + rb * 64 + ((fq ^ ((rb >> 2) & 3)) * 16)); }
; #pragma unroll
;     for (int m = 0; m < 8; ++m) { const int ra = wr * 128 + m * 16 + fr; At[m] = *reinterpret_cast<const bf16x8*>(SA + ra * 64 + ((fq ^ ((ra >> 2) & 3)) * 16)); }
;     if (i + 3 < nk) stage(i + 3);
; #pragma unroll
;     for (int m = 0; m < 8; ++m)
; #pragma unroll
;       for (int n = 0; n < 4; ++n) acc[m][n] = __builtin_amdgcn_mfma_f32_16x16x32_bf16(Bt[n], At[m], acc[m][n], 0, 0, 0);
;   }
	v_add3_u32 v218, v183, v151, s5
	v_add3_u32 v230, v183, v153, s5
	s_nop 0
	ds_read_b128 v[196:199], v218 offset:16384
	ds_read_b128 v[200:203], v218 offset:17408
	ds_read_b128 v[214:217], v218 offset:18432
	ds_read_b128 v[218:221], v218 offset:19456
	ds_read_b128 v[204:207], v230
	ds_read_b128 v[210:213], v230 offset:1024
	v_mfma_f32_16x16x32_bf16 v[28:31], v[232:235], v[248:251], v[28:31]
	v_mfma_f32_16x16x32_bf16 v[24:27], v[236:239], v[248:251], v[24:27]
	v_mfma_f32_16x16x32_bf16 v[20:23], v[240:243], v[248:251], v[20:23]
	v_mfma_f32_16x16x32_bf16 v[16:19], v[244:247], v[248:251], v[16:19]
	v_mfma_f32_16x16x32_bf16 v[12:15], v[232:235], v[222:225], v[12:15]
	v_mfma_f32_16x16x32_bf16 v[8:11], v[236:239], v[222:225], v[8:11]
	v_mfma_f32_16x16x32_bf16 v[4:7], v[240:243], v[222:225], v[4:7]
	v_mfma_f32_16x16x32_bf16 v[0:3], v[244:247], v[222:225], v[0:3]
	ds_read_b128 v[248:251], v230 offset:2048
	ds_read_b128 v[222:225], v230 offset:3072
	s_waitcnt lgkmcnt(2)
	v_mfma_f32_16x16x32_bf16 v[124:127], v[196:199], v[204:207], v[124:127]
	v_mfma_f32_16x16x32_bf16 v[120:123], v[200:203], v[204:207], v[120:123]
	v_mfma_f32_16x16x32_bf16 v[116:119], v[214:217], v[204:207], v[116:119]
	v_mfma_f32_16x16x32_bf16 v[112:115], v[218:221], v[204:207], v[112:115]
	v_mfma_f32_16x16x32_bf16 v[108:111], v[196:199], v[210:213], v[108:111]
	v_mfma_f32_16x16x32_bf16 v[104:107], v[200:203], v[210:213], v[104:107]
	v_mfma_f32_16x16x32_bf16 v[100:103], v[214:217], v[210:213], v[100:103]
	v_mfma_f32_16x16x32_bf16 v[96:99], v[218:221], v[210:213], v[96:99]
	ds_read_b128 v[204:207], v230 offset:4096
	ds_read_b128 v[210:213], v230 offset:5120
	s_waitcnt lgkmcnt(2)
	v_mfma_f32_16x16x32_bf16 v[92:95], v[196:199], v[248:251], v[92:95]
	v_mfma_f32_16x16x32_bf16 v[88:91], v[200:203], v[248:251], v[88:91]
	v_mfma_f32_16x16x32_bf16 v[84:87], v[214:217], v[248:251], v[84:87]
	v_mfma_f32_16x16x32_bf16 v[80:83], v[218:221], v[248:251], v[80:83]
	v_mfma_f32_16x16x32_bf16 v[76:79], v[196:199], v[222:225], v[76:79]
	v_mfma_f32_16x16x32_bf16 v[72:75], v[200:203], v[222:225], v[72:75]
	v_mfma_f32_16x16x32_bf16 v[68:71], v[214:217], v[222:225], v[68:71]
	v_mfma_f32_16x16x32_bf16 v[64:67], v[218:221], v[222:225], v[64:67]
	ds_read_b128 v[248:251], v230 offset:6144
	ds_read_b128 v[222:225], v230 offset:7168
	s_waitcnt lgkmcnt(2)
	v_mfma_f32_16x16x32_bf16 v[60:63], v[196:199], v[204:207], v[60:63]
	v_mfma_f32_16x16x32_bf16 v[56:59], v[200:203], v[204:207], v[56:59]
	v_mfma_f32_16x16x32_bf16 v[52:55], v[214:217], v[204:207], v[52:55]
	v_mfma_f32_16x16x32_bf16 v[48:51], v[218:221], v[204:207], v[48:51]
	v_mfma_f32_16x16x32_bf16 v[44:47], v[196:199], v[210:213], v[44:47]
	v_mfma_f32_16x16x32_bf16 v[40:43], v[200:203], v[210:213], v[40:43]
	v_mfma_f32_16x16x32_bf16 v[36:39], v[214:217], v[210:213], v[36:39]
	v_mfma_f32_16x16x32_bf16 v[32:35], v[218:221], v[210:213], v[32:35]
	s_add_i32 s5, s5, 0x8000
	s_and_b32 s5, s5, 0x18000
	s_waitcnt vmcnt(0) lgkmcnt(0)
	s_barrier
	v_add3_u32 v244, v183, v151, s5
	v_add3_u32 v230, v183, v153, s5
	s_nop 0
	ds_read_b128 v[232:235], v244 offset:16384
	ds_read_b128 v[236:239], v244 offset:17408
	ds_read_b128 v[240:243], v244 offset:18432
	ds_read_b128 v[244:247], v244 offset:19456
	ds_read_b128 v[204:207], v230
	ds_read_b128 v[210:213], v230 offset:1024
	v_mfma_f32_16x16x32_bf16 v[28:31], v[196:199], v[248:251], v[28:31]
	v_mfma_f32_16x16x32_bf16 v[24:27], v[200:203], v[248:251], v[24:27]
	v_mfma_f32_16x16x32_bf16 v[20:23], v[214:217], v[248:251], v[20:23]
	v_mfma_f32_16x16x32_bf16 v[16:19], v[218:221], v[248:251], v[16:19]
	v_mfma_f32_16x16x32_bf16 v[12:15], v[196:199], v[222:225], v[12:15]
	v_mfma_f32_16x16x32_bf16 v[8:11], v[200:203], v[222:225], v[8:11]
	v_mfma_f32_16x16x32_bf16 v[4:7], v[214:217], v[222:225], v[4:7]
	v_mfma_f32_16x16x32_bf16 v[0:3], v[218:221], v[222:225], v[0:3]
	ds_read_b128 v[248:251], v230 offset:2048
	ds_read_b128 v[222:225], v230 offset:3072
	s_waitcnt lgkmcnt(2)
	v_mfma_f32_16x16x32_bf16 v[124:127], v[232:235], v[204:207], v[124:127]
	v_mfma_f32_16x16x32_bf16 v[120:123], v[236:239], v[204:207], v[120:123]
	v_mfma_f32_16x16x32_bf16 v[116:119], v[240:243], v[204:207], v[116:119]
	v_mfma_f32_16x16x32_bf16 v[112:115], v[244:247], v[204:207], v[112:115]
	v_mfma_f32_16x16x32_bf16 v[108:111], v[232:235], v[210:213], v[108:111]
	v_mfma_f32_16x16x32_bf16 v[104:107], v[236:239], v[210:213], v[104:107]
	v_mfma_f32_16x16x32_bf16 v[100:103], v[240:243], v[210:213], v[100:103]
	v_mfma_f32_16x16x32_bf16 v[96:99], v[244:247], v[210:213], v[96:99]
	ds_read_b128 v[204:207], v230 offset:4096
	ds_read_b128 v[210:213], v230 offset:5120
	s_waitcnt lgkmcnt(2)
	v_mfma_f32_16x16x32_bf16 v[92:95], v[232:235], v[248:251], v[92:95]
	v_mfma_f32_16x16x32_bf16 v[88:91], v[236:239], v[248:251], v[88:91]
	v_mfma_f32_16x16x32_bf16 v[84:87], v[240:243], v[248:251], v[84:87]
	v_mfma_f32_16x16x32_bf16 v[80:83], v[244:247], v[248:251], v[80:83]
	v_mfma_f32_16x16x32_bf16 v[76:79], v[232:235], v[222:225], v[76:79]
	v_mfma_f32_16x16x32_bf16 v[72:75], v[236:239], v[222:225], v[72:75]
	v_mfma_f32_16x16x32_bf16 v[68:71], v[240:243], v[222:225], v[68:71]
	v_mfma_f32_16x16x32_bf16 v[64:67], v[244:247], v[222:225], v[64:67]
	ds_read_b128 v[248:251], v230 offset:6144
	ds_read_b128 v[222:225], v230 offset:7168
	s_waitcnt lgkmcnt(2)
	v_mfma_f32_16x16x32_bf16 v[60:63], v[232:235], v[204:207], v[60:63]
	v_mfma_f32_16x16x32_bf16 v[56:59], v[236:239], v[204:207], v[56:59]
	v_mfma_f32_16x16x32_bf16 v[52:55], v[240:243], v[204:207], v[52:55]
	v_mfma_f32_16x16x32_bf16 v[48:51], v[244:247], v[204:207], v[48:51]
	v_mfma_f32_16x16x32_bf16 v[44:47], v[232:235], v[210:213], v[44:47]
	v_mfma_f32_16x16x32_bf16 v[40:43], v[236:239], v[210:213], v[40:43]
	v_mfma_f32_16x16x32_bf16 v[36:39], v[240:243], v[210:213], v[36:39]
	v_mfma_f32_16x16x32_bf16 v[32:35], v[244:247], v[210:213], v[32:35]
	s_waitcnt lgkmcnt(0)
	v_mfma_f32_16x16x32_bf16 v[28:31], v[232:235], v[248:251], v[28:31]
	v_mfma_f32_16x16x32_bf16 v[24:27], v[236:239], v[248:251], v[24:27]
	v_mfma_f32_16x16x32_bf16 v[20:23], v[240:243], v[248:251], v[20:23]
	v_mfma_f32_16x16x32_bf16 v[16:19], v[244:247], v[248:251], v[16:19]
	v_mfma_f32_16x16x32_bf16 v[12:15], v[232:235], v[222:225], v[12:15]
	v_mfma_f32_16x16x32_bf16 v[8:11], v[236:239], v[222:225], v[8:11]
	v_mfma_f32_16x16x32_bf16 v[4:7], v[240:243], v[222:225], v[4:7]
	v_mfma_f32_16x16x32_bf16 v[0:3], v[244:247], v[222:225], v[0:3]

; template <class Epi>
; DI void gemm_tile256(const u16* __restrict__ Ag, long lda, const u16* __restrict__ Bg, long ldb, int nk, char* shm, Epi&& epi) {
;     ...
;   const int q0 = tid, q1 = 512 + tid;
;   const int r0 = q0 >> 2, r1 = q1 >> 2, c0 = (q0 & 3) ^ ((r0 >> 2) & 3), c1 = (q1 & 3) ^ ((r1 >> 2) & 3);
;   const u16* a0 = Ag + (long)r0 * lda + c0 * 8; const u16* a1 = Ag + (long)r1 * lda + c1 * 8;
;   const u16* b0 = Bg + (long)r0 * ldb + c0 * 8; const u16* b1 = Bg + (long)r1 * ldb + c1 * 8;
;   auto stage = [&](int j) {
;     char* SA = shm + (j & 3) * 32768; char* SB = SA + 16384;
;     __builtin_amdgcn_global_load_lds((const unsigned*)(a0 + j * 32), (__attribute__((address_space(3))) unsigned*)(SA + q0 * 16), 16, 0, 0);
;     __builtin_amdgcn_global_load_lds((const unsigned*)(a1 + j * 32), (__attribute__((address_space(3))) unsigned*)(SA + q1 * 16), 16, 0, 0);
;     __builtin_amdgcn_global_load_lds((const unsigned*)(b0 + j * 32), (__attribute__((address_space(3))) unsigned*)(SB + q0 * 16), 16, 0, 0);
;     __builtin_amdgcn_global_load_lds((const unsigned*)(b1 + j * 32), (__attribute__((address_space(3))) unsigned*)(SB + q1 * 16), 16, 0, 0);
;   };
;   __syncthreads();
;   stage(0);
;   if (nk > 1) stage(1);
;   if (nk > 2) stage(2);
; DI void phase8(const Params& P, char* smem) {
;     ...
;   for (int q = RBLK >> 3; q < 128; q += RGRID >> 3) {
;     const int brow = q * 256, bcol = (RBLK & 7) * 256;
;     gemm_tile256(h1b + (long)brow * 1024, 1024, WqT + (long)bcol * 1024, 1024, 32, smem, [&](int row, int col0, f32x4 v) {
.LBB0_1068:
	s_ashr_i32 s7, s6, 31
	s_lshl_b64 s[10:11], s[6:7], 11
	v_lshl_add_u64 v[158:159], v[150:151], 0, s[10:11]
	v_lshl_add_u64 v[160:161], v[152:153], 0, s[10:11]
	s_lshl_b32 s10, s75, 8
	s_ashr_i32 s11, s10, 31
	s_lshl_b64 s[12:13], s[10:11], 11
	s_add_u32 s12, s40, s12
	s_addc_u32 s13, s41, s13
	v_add_u32_e32 v6, 0, v209
	v_lshl_add_u64 v[0:1], s[12:13], 0, v[130:131]
	v_readfirstlane_b32 s7, v6
	v_add_u32_e32 v7, 0, v162
	v_lshl_add_u64 v[0:1], v[0:1], 0, v[132:133]
	v_lshl_add_u64 v[2:3], s[12:13], 0, v[134:135]
	s_mov_b32 m0, s7
	v_readfirstlane_b32 s7, v7
	v_add_u32_e32 v4, 0x4000, v6
	v_lshl_add_u64 v[2:3], v[2:3], 0, v[132:133]
	s_barrier
	global_load_lds_dwordx4 v[0:1], off
	s_mov_b32 m0, s7
	v_readfirstlane_b32 s7, v4
	v_add_u32_e32 v4, 0x4000, v7
	global_load_lds_dwordx4 v[2:3], off
	s_mov_b32 m0, s7
	v_readfirstlane_b32 s7, v4
	v_add_u32_e32 v8, 0x8000, v6
	global_load_lds_dwordx4 v[136:137], off
	s_mov_b32 m0, s7
	v_readfirstlane_b32 s7, v8
	v_add_u32_e32 v8, 0x8000, v7
	global_load_lds_dwordx4 v[138:139], off
	v_lshl_add_u64 v[4:5], v[0:1], 0, 64
	s_mov_b32 m0, s7
	v_readfirstlane_b32 s7, v8
	global_load_lds_dwordx4 v[4:5], off
	v_lshl_add_u64 v[4:5], v[2:3], 0, 64
	s_mov_b32 m0, s7
	v_lshl_add_u64 v[0:1], v[0:1], 0, s[0:1]
	global_load_lds_dwordx4 v[4:5], off
	v_add_u32_e32 v4, 0xc000, v6
	s_mov_b64 s[12:13], 0
	v_readfirstlane_b32 s7, v4
	v_add_u32_e32 v4, 0xc000, v7
	s_mov_b32 m0, s7
	v_readfirstlane_b32 s7, v4
	v_add_u32_e32 v4, s2, v209
	global_load_lds_dwordx4 v[140:141], off
	s_mov_b32 m0, s7
	v_readfirstlane_b32 s7, v4
	global_load_lds_dwordx4 v[142:143], off
	s_mov_b32 m0, s7
	v_mov_b32_e32 v4, 0
	global_load_lds_dwordx4 v[0:1], off
	v_lshl_add_u64 v[0:1], v[2:3], 0, s[0:1]
	v_add_u32_e32 v2, s2, v162
	v_mov_b32_e32 v3, v133
	v_readfirstlane_b32 s7, v2
	s_mov_b32 m0, s7
	v_mov_b32_e32 v2, v133
	global_load_lds_dwordx4 v[0:1], off
	v_add_u32_e32 v0, s4, v209
	v_mov_b32_e32 v1, v133
	v_readfirstlane_b32 s7, v0
	v_add_u32_e32 v0, s4, v162
	s_mov_b32 m0, s7
	v_readfirstlane_b32 s7, v0
	global_load_lds_dwordx4 v[144:145], off
	s_mov_b32 m0, s7
	s_mov_b32 s7, 0x18000
	global_load_lds_dwordx4 v[146:147], off
	v_mov_b32_e32 v0, 0
	v_mov_b32_e32 v5, v133
	v_mov_b32_e32 v6, v133
	v_mov_b32_e32 v7, v133
	v_mov_b32_e32 v8, 0
	v_mov_b32_e32 v9, v133
	v_mov_b32_e32 v10, v133
	v_mov_b32_e32 v11, v133
	v_mov_b32_e32 v12, 0
	v_mov_b32_e32 v13, v133
	v_mov_b32_e32 v14, v133
	v_mov_b32_e32 v15, v133
	v_mov_b32_e32 v16, 0
	v_mov_b32_e32 v17, v133
	v_mov_b32_e32 v18, v133
	v_mov_b32_e32 v19, v133
	v_mov_b32_e32 v20, 0
	v_mov_b32_e32 v21, v133
	v_mov_b32_e32 v22, v133
	v_mov_b32_e32 v23, v133
	v_mov_b32_e32 v24, 0
	v_mov_b32_e32 v25, v133
	v_mov_b32_e32 v26, v133
	v_mov_b32_e32 v27, v133
	v_mov_b32_e32 v28, 0
	v_mov_b32_e32 v29, v133
	v_mov_b32_e32 v30, v133
	v_mov_b32_e32 v31, v133
	v_mov_b32_e32 v32, 0
	v_mov_b32_e32 v33, v133
	v_mov_b32_e32 v34, v133
	v_mov_b32_e32 v35, v133
	v_mov_b32_e32 v36, 0
	v_mov_b32_e32 v37, v133
	v_mov_b32_e32 v38, v133
	v_mov_b32_e32 v39, v133
	v_mov_b32_e32 v40, 0
	v_mov_b32_e32 v41, v133
	v_mov_b32_e32 v42, v133
	v_mov_b32_e32 v43, v133
	v_mov_b32_e32 v44, 0
	v_mov_b32_e32 v45, v133
	v_mov_b32_e32 v46, v133
	v_mov_b32_e32 v47, v133
	v_mov_b32_e32 v48, 0
	v_mov_b32_e32 v49, v133
	v_mov_b32_e32 v50, v133
	v_mov_b32_e32 v51, v133
	v_mov_b32_e32 v52, 0
	v_mov_b32_e32 v53, v133
	v_mov_b32_e32 v54, v133
	v_mov_b32_e32 v55, v133
	v_mov_b32_e32 v56, 0
	v_mov_b32_e32 v57, v133
	v_mov_b32_e32 v58, v133
	v_mov_b32_e32 v59, v133
	v_mov_b32_e32 v60, 0
	v_mov_b32_e32 v61, v133
	v_mov_b32_e32 v62, v133
	v_mov_b32_e32 v63, v133
	v_mov_b32_e32 v64, 0
	v_mov_b32_e32 v65, v133
	v_mov_b32_e32 v66, v133
	v_mov_b32_e32 v67, v133
	v_mov_b32_e32 v68, 0
	v_mov_b32_e32 v69, v133
	v_mov_b32_e32 v70, v133
	v_mov_b32_e32 v71, v133
	v_mov_b32_e32 v72, 0
	v_mov_b32_e32 v73, v133
	v_mov_b32_e32 v74, v133
	v_mov_b32_e32 v75, v133
	v_mov_b32_e32 v76, 0
	v_mov_b32_e32 v77, v133
	v_mov_b32_e32 v78, v133
	v_mov_b32_e32 v79, v133
	v_mov_b32_e32 v80, 0
	v_mov_b32_e32 v81, v133
	v_mov_b32_e32 v82, v133
	v_mov_b32_e32 v83, v133
	v_mov_b32_e32 v84, 0
	v_mov_b32_e32 v85, v133
	v_mov_b32_e32 v86, v133
	v_mov_b32_e32 v87, v133
	v_mov_b32_e32 v88, 0
	v_mov_b32_e32 v89, v133
	v_mov_b32_e32 v90, v133
	v_mov_b32_e32 v91, v133
	v_mov_b32_e32 v92, 0
	v_mov_b32_e32 v93, v133
	v_mov_b32_e32 v94, v133
	v_mov_b32_e32 v95, v133
	v_mov_b32_e32 v96, 0
	v_mov_b32_e32 v97, v133
	v_mov_b32_e32 v98, v133
	v_mov_b32_e32 v99, v133
	v_mov_b32_e32 v100, 0
	v_mov_b32_e32 v101, v133
	v_mov_b32_e32 v102, v133
	v_mov_b32_e32 v103, v133
	v_mov_b32_e32 v104, 0
	v_mov_b32_e32 v105, v133
	v_mov_b32_e32 v106, v133
	v_mov_b32_e32 v107, v133
	v_mov_b32_e32 v108, 0
	v_mov_b32_e32 v109, v133
	v_mov_b32_e32 v110, v133
	v_mov_b32_e32 v111, v133
	v_mov_b32_e32 v112, 0
	v_mov_b32_e32 v113, v133
	v_mov_b32_e32 v114, v133
	v_mov_b32_e32 v115, v133
	v_mov_b32_e32 v116, 0
	v_mov_b32_e32 v117, v133
	v_mov_b32_e32 v118, v133
	v_mov_b32_e32 v119, v133
	v_mov_b32_e32 v120, 0
	v_mov_b32_e32 v121, v133
	v_mov_b32_e32 v122, v133
	v_mov_b32_e32 v123, v133
	v_mov_b32_e32 v124, 0
	v_mov_b32_e32 v125, v133
	v_mov_b32_e32 v126, v133
	v_mov_b32_e32 v127, v133
	v_readfirstlane_b32 s11, v209
	s_mov_b32 s7, 0
	s_mov_b64 s[12:13], 0
	v_readfirstlane_b32 s26, v158
	v_readfirstlane_b32 s27, v159
	v_readfirstlane_b32 s28, v160
	v_readfirstlane_b32 s29, v161
	v_readfirstlane_b32 s30, v154
	v_readfirstlane_b32 s31, v155
	v_readfirstlane_b32 s32, v156
	v_readfirstlane_b32 s33, v157
	s_sub_u32 s26, s26, 64
	s_subb_u32 s27, s27, 0
	v_subrev_u32_e32 v206, s26, v158
	s_sub_u32 s28, s28, 64
	s_subb_u32 s29, s29, 0
	v_subrev_u32_e32 v207, s28, v160
	s_sub_u32 s30, s30, 64
	s_subb_u32 s31, s31, 0
	v_subrev_u32_e32 v224, s30, v154
	s_sub_u32 s32, s32, 64
	s_subb_u32 s33, s33, 0
	v_subrev_u32_e32 v225, s32, v156
	s_waitcnt vmcnt(8)
	s_barrier
	v_add3_u32 v220, v181, v163, s7
	v_add3_u32 v186, v181, v164, s7
	s_nop 0
	ds_read_b128 v[194:197], v220 offset:16384
	ds_read_b128 v[198:201], v220 offset:17408
	ds_read_b128 v[216:219], v220 offset:18432
	ds_read_b128 v[220:223], v220 offset:19456
	ds_read_b128 v[202:205], v186
	ds_read_b128 v[212:215], v186 offset:1024
; template <class Epi>
; DI void gemm_tile256(const u16* __restrict__ Ag, long lda, const u16* __restrict__ Bg, long ldb, int nk, char* shm, Epi&& epi) {
;     ...
;   for (int i = 0; i < nk; ++i) {
;     if (i + 2 < nk) asm volatile("s_waitcnt vmcnt(8)" ::: "memory");
;     else if (i + 1 < nk) asm volatile("s_waitcnt vmcnt(4)" ::: "memory");
;     else asm volatile("s_waitcnt vmcnt(0)" ::: "memory");
;     __builtin_amdgcn_s_barrier();
;     const char* SA = shm + (i & 3) * 32768; const char* SB = SA + 16384;
;     bf16x8 At[8], Bt[4];
; #pragma unroll
;     for (int n = 0; n < 4; ++n) { const int rb = wc * 64 + n * 16 + fr; Bt[n] = *reinterpret_cast<const bf16x8*>(SB + rb * 64 + ((fq ^ ((rb >> 2) & 3)) * 16)); }
; #pragma unroll
;     for (int m = 0; m < 8; ++m) { const int ra = wr * 128 + m * 16 + fr; At[m] = *reinterpret_cast<const bf16x8*>(SA + ra * 64 + ((fq ^ ((ra >> 2) & 3)) * 16)); }
;     if (i + 3 < nk) stage(i + 3);
; #pragma unroll
;     for (int m = 0; m < 8; ++m)
; #pragma unroll
;       for (int n = 0; n < 4; ++n) acc[m][n] = __builtin_amdgcn_mfma_f32_16x16x32_bf16(Bt[n], At[m], acc[m][n], 0, 0, 0);
;   }
.Lgemm_p8_kloop0:
	s_add_i32 s9, s7, 0x18000
	s_and_b32 s9, s9, 0x18000
	s_add_i32 s14, s9, s11
	ds_read_b128 v[246:249], v186 offset:2048
	ds_read_b128 v[250:253], v186 offset:3072
	s_waitcnt lgkmcnt(2)
	v_mfma_f32_16x16x32_bf16 v[124:127], v[194:197], v[202:205], v[124:127]
	v_lshl_add_u64 v[206:207], v[158:159], 0, s[12:13]
	v_mfma_f32_16x16x32_bf16 v[120:123], v[198:201], v[202:205], v[120:123]
	s_mov_b32 m0, s14
	v_mfma_f32_16x16x32_bf16 v[116:119], v[216:219], v[202:205], v[116:119]
	s_add_i32 s14, s14, 0x2000
	v_mfma_f32_16x16x32_bf16 v[112:115], v[220:223], v[202:205], v[112:115]
	global_load_lds_dwordx4 v[206:207], off
	v_mfma_f32_16x16x32_bf16 v[108:111], v[194:197], v[212:215], v[108:111]
	v_mfma_f32_16x16x32_bf16 v[104:107], v[198:201], v[212:215], v[104:107]
	v_mfma_f32_16x16x32_bf16 v[100:103], v[216:219], v[212:215], v[100:103]
	v_mfma_f32_16x16x32_bf16 v[96:99], v[220:223], v[212:215], v[96:99]
	ds_read_b128 v[202:205], v186 offset:4096
	ds_read_b128 v[212:215], v186 offset:5120
	s_waitcnt lgkmcnt(2)
	v_mfma_f32_16x16x32_bf16 v[92:95], v[194:197], v[246:249], v[92:95]
	v_lshl_add_u64 v[224:225], v[160:161], 0, s[12:13]
	v_mfma_f32_16x16x32_bf16 v[88:91], v[198:201], v[246:249], v[88:91]
	s_mov_b32 m0, s14
	v_mfma_f32_16x16x32_bf16 v[84:87], v[216:219], v[246:249], v[84:87]
	s_add_i32 s14, s14, 0x2000
	v_mfma_f32_16x16x32_bf16 v[80:83], v[220:223], v[246:249], v[80:83]
	global_load_lds_dwordx4 v[224:225], off
	v_mfma_f32_16x16x32_bf16 v[76:79], v[194:197], v[250:253], v[76:79]
	v_mfma_f32_16x16x32_bf16 v[72:75], v[198:201], v[250:253], v[72:75]
	v_mfma_f32_16x16x32_bf16 v[68:71], v[216:219], v[250:253], v[68:71]
	v_mfma_f32_16x16x32_bf16 v[64:67], v[220:223], v[250:253], v[64:67]
	ds_read_b128 v[246:249], v186 offset:6144
	ds_read_b128 v[250:253], v186 offset:7168
	s_waitcnt lgkmcnt(2)
	v_mfma_f32_16x16x32_bf16 v[60:63], v[194:197], v[202:205], v[60:63]
	v_lshl_add_u64 v[226:227], v[154:155], 0, s[12:13]
	v_mfma_f32_16x16x32_bf16 v[56:59], v[198:201], v[202:205], v[56:59]
	s_mov_b32 m0, s14
	v_mfma_f32_16x16x32_bf16 v[52:55], v[216:219], v[202:205], v[52:55]
	s_add_i32 s14, s14, 0x2000
	v_mfma_f32_16x16x32_bf16 v[48:51], v[220:223], v[202:205], v[48:51]
	global_load_lds_dwordx4 v[226:227], off
	v_mfma_f32_16x16x32_bf16 v[44:47], v[194:197], v[212:215], v[44:47]
	v_mfma_f32_16x16x32_bf16 v[40:43], v[198:201], v[212:215], v[40:43]
	v_mfma_f32_16x16x32_bf16 v[36:39], v[216:219], v[212:215], v[36:39]
	v_mfma_f32_16x16x32_bf16 v[32:35], v[220:223], v[212:215], v[32:35]
	s_add_i32 s7, s7, 0x8000
	s_and_b32 s7, s7, 0x18000
	s_waitcnt vmcnt(7) lgkmcnt(0)
	s_barrier
	v_add3_u32 v242, v181, v163, s7
	v_add3_u32 v186, v181, v164, s7
	s_nop 0
	ds_read_b128 v[230:233], v242 offset:16384
	ds_read_b128 v[234:237], v242 offset:17408
	ds_read_b128 v[238:241], v242 offset:18432
	ds_read_b128 v[242:245], v242 offset:19456
	ds_read_b128 v[202:205], v186
	ds_read_b128 v[212:215], v186 offset:1024
	v_mfma_f32_16x16x32_bf16 v[28:31], v[194:197], v[246:249], v[28:31]
	v_lshl_add_u64 v[228:229], v[156:157], 0, s[12:13]
	v_mfma_f32_16x16x32_bf16 v[24:27], v[198:201], v[246:249], v[24:27]
	s_mov_b32 m0, s14
	v_mfma_f32_16x16x32_bf16 v[20:23], v[216:219], v[246:249], v[20:23]
	s_add_i32 s14, s14, 0x2000
	v_mfma_f32_16x16x32_bf16 v[16:19], v[220:223], v[246:249], v[16:19]
	global_load_lds_dwordx4 v[228:229], off
	v_mfma_f32_16x16x32_bf16 v[12:15], v[194:197], v[250:253], v[12:15]
	s_add_u32 s12, s12, 64
	v_mfma_f32_16x16x32_bf16 v[8:11], v[198:201], v[250:253], v[8:11]
	s_addc_u32 s13, s13, 0
	v_mfma_f32_16x16x32_bf16 v[4:7], v[216:219], v[250:253], v[4:7]
	v_mfma_f32_16x16x32_bf16 v[0:3], v[220:223], v[250:253], v[0:3]
	s_add_i32 s9, s7, 0x18000
	s_and_b32 s9, s9, 0x18000
	s_add_i32 s14, s9, s11
	ds_read_b128 v[246:249], v186 offset:2048
	ds_read_b128 v[250:253], v186 offset:3072
	s_waitcnt lgkmcnt(2)
	v_mfma_f32_16x16x32_bf16 v[124:127], v[230:233], v[202:205], v[124:127]
	v_lshl_add_u64 v[206:207], v[158:159], 0, s[12:13]
	v_mfma_f32_16x16x32_bf16 v[120:123], v[234:237], v[202:205], v[120:123]
	s_mov_b32 m0, s14
	v_mfma_f32_16x16x32_bf16 v[116:119], v[238:241], v[202:205], v[116:119]
	s_add_i32 s14, s14, 0x2000
	v_mfma_f32_16x16x32_bf16 v[112:115], v[242:245], v[202:205], v[112:115]
	global_load_lds_dwordx4 v[206:207], off
	v_mfma_f32_16x16x32_bf16 v[108:111], v[230:233], v[212:215], v[108:111]
	v_mfma_f32_16x16x32_bf16 v[104:107], v[234:237], v[212:215], v[104:107]
	v_mfma_f32_16x16x32_bf16 v[100:103], v[238:241], v[212:215], v[100:103]
	v_mfma_f32_16x16x32_bf16 v[96:99], v[242:245], v[212:215], v[96:99]
	ds_read_b128 v[202:205], v186 offset:4096
	ds_read_b128 v[212:215], v186 offset:5120
	s_waitcnt lgkmcnt(2)
	v_mfma_f32_16x16x32_bf16 v[92:95], v[230:233], v[246:249], v[92:95]
	v_lshl_add_u64 v[224:225], v[160:161], 0, s[12:13]
	v_mfma_f32_16x16x32_bf16 v[88:91], v[234:237], v[246:249], v[88:91]
	s_mov_b32 m0, s14
	v_mfma_f32_16x16x32_bf16 v[84:87], v[238:241], v[246:249], v[84:87]
	s_add_i32 s14, s14, 0x2000
	v_mfma_f32_16x16x32_bf16 v[80:83], v[242:245], v[246:249], v[80:83]
	global_load_lds_dwordx4 v[224:225], off
	v_mfma_f32_16x16x32_bf16 v[76:79], v[230:233], v[250:253], v[76:79]
	v_mfma_f32_16x16x32_bf16 v[72:75], v[234:237], v[250:253], v[72:75]
	v_mfma_f32_16x16x32_bf16 v[68:71], v[238:241], v[250:253], v[68:71]
	v_mfma_f32_16x16x32_bf16 v[64:67], v[242:245], v[250:253], v[64:67]
	ds_read_b128 v[246:249], v186 offset:6144
	ds_read_b128 v[250:253], v186 offset:7168
	s_waitcnt lgkmcnt(2)
	v_mfma_f32_16x16x32_bf16 v[60:63], v[230:233], v[202:205], v[60:63]
	v_lshl_add_u64 v[226:227], v[154:155], 0, s[12:13]
	v_mfma_f32_16x16x32_bf16 v[56:59], v[234:237], v[202:205], v[56:59]
	s_mov_b32 m0, s14
	v_mfma_f32_16x16x32_bf16 v[52:55], v[238:241], v[202:205], v[52:55]
	s_add_i32 s14, s14, 0x2000
	v_mfma_f32_16x16x32_bf16 v[48:51], v[242:245], v[202:205], v[48:51]
	global_load_lds_dwordx4 v[226:227], off
	v_mfma_f32_16x16x32_bf16 v[44:47], v[230:233], v[212:215], v[44:47]
	v_mfma_f32_16x16x32_bf16 v[40:43], v[234:237], v[212:215], v[40:43]
	v_mfma_f32_16x16x32_bf16 v[36:39], v[238:241], v[212:215], v[36:39]
	v_mfma_f32_16x16x32_bf16 v[32:35], v[242:245], v[212:215], v[32:35]
	s_add_i32 s7, s7, 0x8000
	s_and_b32 s7, s7, 0x18000
	s_waitcnt vmcnt(7) lgkmcnt(0)
	s_barrier
; template <class Epi>
; DI void gemm_tile256(const u16* __restrict__ Ag, long lda, const u16* __restrict__ Bg, long ldb, int nk, char* shm, Epi&& epi) {
;     ...
;   for (int i = 0; i < nk; ++i) {
;     if (i + 2 < nk) asm volatile("s_waitcnt vmcnt(8)" ::: "memory");
;     else if (i + 1 < nk) asm volatile("s_waitcnt vmcnt(4)" ::: "memory");
;     else asm volatile("s_waitcnt vmcnt(0)" ::: "memory");
;     __builtin_amdgcn_s_barrier();
;     const char* SA = shm + (i & 3) * 32768; const char* SB = SA + 16384;
;     bf16x8 At[8], Bt[4];
; #pragma unroll
;     for (int n = 0; n < 4; ++n) { const int rb = wc * 64 + n * 16 + fr; Bt[n] = *reinterpret_cast<const bf16x8*>(SB + rb * 64 + ((fq ^ ((rb >> 2) & 3)) * 16)); }
; #pragma unroll
;     for (int m = 0; m < 8; ++m) { const int ra = wr * 128 + m * 16 + fr; At[m] = *reinterpret_cast<const bf16x8*>(SA + ra * 64 + ((fq ^ ((ra >> 2) & 3)) * 16)); }
;     if (i + 3 < nk) stage(i + 3);
; #pragma unroll
;     for (int m = 0; m < 8; ++m)
; #pragma unroll
;       for (int n = 0; n < 4; ++n) acc[m][n] = __builtin_amdgcn_mfma_f32_16x16x32_bf16(Bt[n], At[m], acc[m][n], 0, 0, 0);
;   }
	v_add3_u32 v220, v181, v163, s7
	v_add3_u32 v186, v181, v164, s7
	s_nop 0
	ds_read_b128 v[194:197], v220 offset:16384
	ds_read_b128 v[198:201], v220 offset:17408
	ds_read_b128 v[216:219], v220 offset:18432
	ds_read_b128 v[220:223], v220 offset:19456
	ds_read_b128 v[202:205], v186
	ds_read_b128 v[212:215], v186 offset:1024
	v_mfma_f32_16x16x32_bf16 v[28:31], v[230:233], v[246:249], v[28:31]
	v_lshl_add_u64 v[228:229], v[156:157], 0, s[12:13]
	v_mfma_f32_16x16x32_bf16 v[24:27], v[234:237], v[246:249], v[24:27]
	s_mov_b32 m0, s14
	v_mfma_f32_16x16x32_bf16 v[20:23], v[238:241], v[246:249], v[20:23]
	s_add_i32 s14, s14, 0x2000
	v_mfma_f32_16x16x32_bf16 v[16:19], v[242:245], v[246:249], v[16:19]
	global_load_lds_dwordx4 v[228:229], off
	v_mfma_f32_16x16x32_bf16 v[12:15], v[230:233], v[250:253], v[12:15]
	s_add_u32 s12, s12, 64
	v_mfma_f32_16x16x32_bf16 v[8:11], v[234:237], v[250:253], v[8:11]
	s_addc_u32 s13, s13, 0
	v_mfma_f32_16x16x32_bf16 v[4:7], v[238:241], v[250:253], v[4:7]
	v_mfma_f32_16x16x32_bf16 v[0:3], v[242:245], v[250:253], v[0:3]
	s_cmpk_lg_i32 s12, 0x700
	s_cbranch_scc1 .Lgemm_p8_kloop0
	s_add_i32 s9, s7, 0x18000
	s_and_b32 s9, s9, 0x18000
	s_add_i32 s14, s9, s11
	ds_read_b128 v[246:249], v186 offset:2048
	ds_read_b128 v[250:253], v186 offset:3072
	s_waitcnt lgkmcnt(2)
	v_mfma_f32_16x16x32_bf16 v[124:127], v[194:197], v[202:205], v[124:127]
	v_lshl_add_u64 v[206:207], v[158:159], 0, s[12:13]
	v_mfma_f32_16x16x32_bf16 v[120:123], v[198:201], v[202:205], v[120:123]
	s_mov_b32 m0, s14
	v_mfma_f32_16x16x32_bf16 v[116:119], v[216:219], v[202:205], v[116:119]
	s_add_i32 s14, s14, 0x2000
	v_mfma_f32_16x16x32_bf16 v[112:115], v[220:223], v[202:205], v[112:115]
	global_load_lds_dwordx4 v[206:207], off
	v_mfma_f32_16x16x32_bf16 v[108:111], v[194:197], v[212:215], v[108:111]
	v_mfma_f32_16x16x32_bf16 v[104:107], v[198:201], v[212:215], v[104:107]
	v_mfma_f32_16x16x32_bf16 v[100:103], v[216:219], v[212:215], v[100:103]
	v_mfma_f32_16x16x32_bf16 v[96:99], v[220:223], v[212:215], v[96:99]
	ds_read_b128 v[202:205], v186 offset:4096
	ds_read_b128 v[212:215], v186 offset:5120
	s_waitcnt lgkmcnt(2)
	v_mfma_f32_16x16x32_bf16 v[92:95], v[194:197], v[246:249], v[92:95]
	v_lshl_add_u64 v[224:225], v[160:161], 0, s[12:13]
	v_mfma_f32_16x16x32_bf16 v[88:91], v[198:201], v[246:249], v[88:91]
	s_mov_b32 m0, s14
	v_mfma_f32_16x16x32_bf16 v[84:87], v[216:219], v[246:249], v[84:87]
	s_add_i32 s14, s14, 0x2000
	v_mfma_f32_16x16x32_bf16 v[80:83], v[220:223], v[246:249], v[80:83]
	global_load_lds_dwordx4 v[224:225], off
	v_mfma_f32_16x16x32_bf16 v[76:79], v[194:197], v[250:253], v[76:79]
	v_mfma_f32_16x16x32_bf16 v[72:75], v[198:201], v[250:253], v[72:75]
	v_mfma_f32_16x16x32_bf16 v[68:71], v[216:219], v[250:253], v[68:71]
	v_mfma_f32_16x16x32_bf16 v[64:67], v[220:223], v[250:253], v[64:67]
	ds_read_b128 v[246:249], v186 offset:6144
	ds_read_b128 v[250:253], v186 offset:7168
	s_waitcnt lgkmcnt(2)
	v_mfma_f32_16x16x32_bf16 v[60:63], v[194:197], v[202:205], v[60:63]
	v_lshl_add_u64 v[226:227], v[154:155], 0, s[12:13]
	v_mfma_f32_16x16x32_bf16 v[56:59], v[198:201], v[202:205], v[56:59]
	s_mov_b32 m0, s14
	v_mfma_f32_16x16x32_bf16 v[52:55], v[216:219], v[202:205], v[52:55]
	s_add_i32 s14, s14, 0x2000
	v_mfma_f32_16x16x32_bf16 v[48:51], v[220:223], v[202:205], v[48:51]
	global_load_lds_dwordx4 v[226:227], off
	v_mfma_f32_16x16x32_bf16 v[44:47], v[194:197], v[212:215], v[44:47]
	v_mfma_f32_16x16x32_bf16 v[40:43], v[198:201], v[212:215], v[40:43]
	v_mfma_f32_16x16x32_bf16 v[36:39], v[216:219], v[212:215], v[36:39]
	v_mfma_f32_16x16x32_bf16 v[32:35], v[220:223], v[212:215], v[32:35]
	s_add_i32 s7, s7, 0x8000
	s_and_b32 s7, s7, 0x18000
	s_waitcnt vmcnt(7) lgkmcnt(0)
	s_barrier
	v_add3_u32 v242, v181, v163, s7
	v_add3_u32 v186, v181, v164, s7
	s_nop 0
	ds_read_b128 v[230:233], v242 offset:16384
	ds_read_b128 v[234:237], v242 offset:17408
	ds_read_b128 v[238:241], v242 offset:18432
	ds_read_b128 v[242:245], v242 offset:19456
	ds_read_b128 v[202:205], v186
	ds_read_b128 v[212:215], v186 offset:1024
	v_mfma_f32_16x16x32_bf16 v[28:31], v[194:197], v[246:249], v[28:31]
	v_lshl_add_u64 v[228:229], v[156:157], 0, s[12:13]
	v_mfma_f32_16x16x32_bf16 v[24:27], v[198:201], v[246:249], v[24:27]
	s_mov_b32 m0, s14
	v_mfma_f32_16x16x32_bf16 v[20:23], v[216:219], v[246:249], v[20:23]
	s_add_i32 s14, s14, 0x2000
	v_mfma_f32_16x16x32_bf16 v[16:19], v[220:223], v[246:249], v[16:19]
	global_load_lds_dwordx4 v[228:229], off
	v_mfma_f32_16x16x32_bf16 v[12:15], v[194:197], v[250:253], v[12:15]
	s_add_u32 s12, s12, 64
	v_mfma_f32_16x16x32_bf16 v[8:11], v[198:201], v[250:253], v[8:11]
	s_addc_u32 s13, s13, 0
	v_mfma_f32_16x16x32_bf16 v[4:7], v[216:219], v[250:253], v[4:7]
	v_mfma_f32_16x16x32_bf16 v[0:3], v[220:223], v[250:253], v[0:3]
	ds_read_b128 v[246:249], v186 offset:2048
	ds_read_b128 v[250:253], v186 offset:3072
	s_waitcnt lgkmcnt(2)
	v_mfma_f32_16x16x32_bf16 v[124:127], v[230:233], v[202:205], v[124:127]
	v_mfma_f32_16x16x32_bf16 v[120:123], v[234:237], v[202:205], v[120:123]
	v_mfma_f32_16x16x32_bf16 v[116:119], v[238:241], v[202:205], v[116:119]
	v_mfma_f32_16x16x32_bf16 v[112:115], v[242:245], v[202:205], v[112:115]
	v_mfma_f32_16x16x32_bf16 v[108:111], v[230:233], v[212:215], v[108:111]
	v_mfma_f32_16x16x32_bf16 v[104:107], v[234:237], v[212:215], v[104:107]
	v_mfma_f32_16x16x32_bf16 v[100:103], v[238:241], v[212:215], v[100:103]
	v_mfma_f32_16x16x32_bf16 v[96:99], v[242:245], v[212:215], v[96:99]
	ds_read_b128 v[202:205], v186 offset:4096
	ds_read_b128 v[212:215], v186 offset:5120
	s_waitcnt lgkmcnt(2)
	v_mfma_f32_16x16x32_bf16 v[92:95], v[230:233], v[246:249], v[92:95]
	v_mfma_f32_16x16x32_bf16 v[88:91], v[234:237], v[246:249], v[88:91]
	v_mfma_f32_16x16x32_bf16 v[84:87], v[238:241], v[246:249], v[84:87]
	v_mfma_f32_16x16x32_bf16 v[80:83], v[242:245], v[246:249], v[80:83]
	v_mfma_f32_16x16x32_bf16 v[76:79], v[230:233], v[250:253], v[76:79]
	v_mfma_f32_16x16x32_bf16 v[72:75], v[234:237], v[250:253], v[72:75]
	v_mfma_f32_16x16x32_bf16 v[68:71], v[238:241], v[250:253], v[68:71]
	v_mfma_f32_16x16x32_bf16 v[64:67], v[242:245], v[250:253], v[64:67]
	ds_read_b128 v[246:249], v186 offset:6144
	ds_read_b128 v[250:253], v186 offset:7168
	s_waitcnt lgkmcnt(2)
	v_mfma_f32_16x16x32_bf16 v[60:63], v[230:233], v[202:205], v[60:63]
	v_mfma_f32_16x16x32_bf16 v[56:59], v[234:237], v[202:205], v[56:59]
	v_mfma_f32_16x16x32_bf16 v[52:55], v[238:241], v[202:205], v[52:55]
	v_mfma_f32_16x16x32_bf16 v[48:51], v[242:245], v[202:205], v[48:51]
	v_mfma_f32_16x16x32_bf16 v[44:47], v[230:233], v[212:215], v[44:47]
	v_mfma_f32_16x16x32_bf16 v[40:43], v[234:237], v[212:215], v[40:43]
	v_mfma_f32_16x16x32_bf16 v[36:39], v[238:241], v[212:215], v[36:39]
	v_mfma_f32_16x16x32_bf16 v[32:35], v[242:245], v[212:215], v[32:35]
	s_add_i32 s7, s7, 0x8000
	s_and_b32 s7, s7, 0x18000
	s_waitcnt vmcnt(4) lgkmcnt(0)
	s_barrier
; template <class Epi>
; DI void gemm_tile256(const u16* __restrict__ Ag, long lda, const u16* __restrict__ Bg, long ldb, int nk, char* shm, Epi&& epi) {
;     ...
;   for (int i = 0; i < nk; ++i) {
;     if (i + 2 < nk) asm volatile("s_waitcnt vmcnt(8)" ::: "memory");
;     else if (i + 1 < nk) asm volatile("s_waitcnt vmcnt(4)" ::: "memory");
;     else asm volatile("s_waitcnt vmcnt(0)" ::: "memory");
;     __builtin_amdgcn_s_barrier();
;     const char* SA = shm + (i & 3) * 32768; const char* SB = SA + 16384;
;     bf16x8 At[8], Bt[4];
; #pragma unroll
;     for (int n = 0; n < 4; ++n) { const int rb = wc * 64 + n * 16 + fr; Bt[n] = *reinterpret_cast<const bf16x8*>(SB + rb * 64 + ((fq ^ ((rb >> 2) & 3)) * 16)); }
; #pragma unroll
;     for (int m = 0; m < 8; ++m) { const int ra = wr * 128 + m * 16 + fr; At[m] = *reinterpret_cast<const bf16x8*>(SA + ra * 64 + ((fq ^ ((ra >> 2) & 3)) * 16)); }
;     if (i + 3 < nk) stage(i + 3);
; #pragma unroll
;     for (int m = 0; m < 8; ++m)
; #pragma unroll
;       for (int n = 0; n < 4; ++n) acc[m][n] = __builtin_amdgcn_mfma_f32_16x16x32_bf16(Bt[n], At[m], acc[m][n], 0, 0, 0);
;   }
	v_add3_u32 v220, v181, v163, s7
	v_add3_u32 v186, v181, v164, s7
	s_nop 0
	ds_read_b128 v[194:197], v220 offset:16384
	ds_read_b128 v[198:201], v220 offset:17408
	ds_read_b128 v[216:219], v220 offset:18432
	ds_read_b128 v[220:223], v220 offset:19456
	ds_read_b128 v[202:205], v186
	ds_read_b128 v[212:215], v186 offset:1024
	v_mfma_f32_16x16x32_bf16 v[28:31], v[230:233], v[246:249], v[28:31]
	v_mfma_f32_16x16x32_bf16 v[24:27], v[234:237], v[246:249], v[24:27]
	v_mfma_f32_16x16x32_bf16 v[20:23], v[238:241], v[246:249], v[20:23]
	v_mfma_f32_16x16x32_bf16 v[16:19], v[242:245], v[246:249], v[16:19]
	v_mfma_f32_16x16x32_bf16 v[12:15], v[230:233], v[250:253], v[12:15]
	v_mfma_f32_16x16x32_bf16 v[8:11], v[234:237], v[250:253], v[8:11]
	v_mfma_f32_16x16x32_bf16 v[4:7], v[238:241], v[250:253], v[4:7]
	v_mfma_f32_16x16x32_bf16 v[0:3], v[242:245], v[250:253], v[0:3]
	ds_read_b128 v[246:249], v186 offset:2048
	ds_read_b128 v[250:253], v186 offset:3072
	s_waitcnt lgkmcnt(2)
	v_mfma_f32_16x16x32_bf16 v[124:127], v[194:197], v[202:205], v[124:127]
	v_mfma_f32_16x16x32_bf16 v[120:123], v[198:201], v[202:205], v[120:123]
	v_mfma_f32_16x16x32_bf16 v[116:119], v[216:219], v[202:205], v[116:119]
	v_mfma_f32_16x16x32_bf16 v[112:115], v[220:223], v[202:205], v[112:115]
	v_mfma_f32_16x16x32_bf16 v[108:111], v[194:197], v[212:215], v[108:111]
	v_mfma_f32_16x16x32_bf16 v[104:107], v[198:201], v[212:215], v[104:107]
	v_mfma_f32_16x16x32_bf16 v[100:103], v[216:219], v[212:215], v[100:103]
	v_mfma_f32_16x16x32_bf16 v[96:99], v[220:223], v[212:215], v[96:99]
	ds_read_b128 v[202:205], v186 offset:4096
	ds_read_b128 v[212:215], v186 offset:5120
	s_waitcnt lgkmcnt(2)
	v_mfma_f32_16x16x32_bf16 v[92:95], v[194:197], v[246:249], v[92:95]
	v_mfma_f32_16x16x32_bf16 v[88:91], v[198:201], v[246:249], v[88:91]
	v_mfma_f32_16x16x32_bf16 v[84:87], v[216:219], v[246:249], v[84:87]
	v_mfma_f32_16x16x32_bf16 v[80:83], v[220:223], v[246:249], v[80:83]
	v_mfma_f32_16x16x32_bf16 v[76:79], v[194:197], v[250:253], v[76:79]
	v_mfma_f32_16x16x32_bf16 v[72:75], v[198:201], v[250:253], v[72:75]
	v_mfma_f32_16x16x32_bf16 v[68:71], v[216:219], v[250:253], v[68:71]
	v_mfma_f32_16x16x32_bf16 v[64:67], v[220:223], v[250:253], v[64:67]
	ds_read_b128 v[246:249], v186 offset:6144
	ds_read_b128 v[250:253], v186 offset:7168
	s_waitcnt lgkmcnt(2)
	v_mfma_f32_16x16x32_bf16 v[60:63], v[194:197], v[202:205], v[60:63]
	v_mfma_f32_16x16x32_bf16 v[56:59], v[198:201], v[202:205], v[56:59]
	v_mfma_f32_16x16x32_bf16 v[52:55], v[216:219], v[202:205], v[52:55]
	v_mfma_f32_16x16x32_bf16 v[48:51], v[220:223], v[202:205], v[48:51]
	v_mfma_f32_16x16x32_bf16 v[44:47], v[194:197], v[212:215], v[44:47]
	v_mfma_f32_16x16x32_bf16 v[40:43], v[198:201], v[212:215], v[40:43]
	v_mfma_f32_16x16x32_bf16 v[36:39], v[216:219], v[212:215], v[36:39]
	v_mfma_f32_16x16x32_bf16 v[32:35], v[220:223], v[212:215], v[32:35]
	s_add_i32 s7, s7, 0x8000
	s_and_b32 s7, s7, 0x18000
	s_waitcnt vmcnt(0) lgkmcnt(0)
	s_barrier
	v_add3_u32 v242, v181, v163, s7
	v_add3_u32 v186, v181, v164, s7
	s_nop 0
	ds_read_b128 v[230:233], v242 offset:16384
	ds_read_b128 v[234:237], v242 offset:17408
	ds_read_b128 v[238:241], v242 offset:18432
	ds_read_b128 v[242:245], v242 offset:19456
	ds_read_b128 v[202:205], v186
	ds_read_b128 v[212:215], v186 offset:1024
	v_mfma_f32_16x16x32_bf16 v[28:31], v[194:197], v[246:249], v[28:31]
	v_mfma_f32_16x16x32_bf16 v[24:27], v[198:201], v[246:249], v[24:27]
	v_mfma_f32_16x16x32_bf16 v[20:23], v[216:219], v[246:249], v[20:23]
	v_mfma_f32_16x16x32_bf16 v[16:19], v[220:223], v[246:249], v[16:19]
	v_mfma_f32_16x16x32_bf16 v[12:15], v[194:197], v[250:253], v[12:15]
	v_mfma_f32_16x16x32_bf16 v[8:11], v[198:201], v[250:253], v[8:11]
	v_mfma_f32_16x16x32_bf16 v[4:7], v[216:219], v[250:253], v[4:7]
	v_mfma_f32_16x16x32_bf16 v[0:3], v[220:223], v[250:253], v[0:3]
	ds_read_b128 v[246:249], v186 offset:2048
	ds_read_b128 v[250:253], v186 offset:3072
	s_waitcnt lgkmcnt(2)
	v_mfma_f32_16x16x32_bf16 v[124:127], v[230:233], v[202:205], v[124:127]
	v_mfma_f32_16x16x32_bf16 v[120:123], v[234:237], v[202:205], v[120:123]
	v_mfma_f32_16x16x32_bf16 v[116:119], v[238:241], v[202:205], v[116:119]
	v_mfma_f32_16x16x32_bf16 v[112:115], v[242:245], v[202:205], v[112:115]
	v_mfma_f32_16x16x32_bf16 v[108:111], v[230:233], v[212:215], v[108:111]
	v_mfma_f32_16x16x32_bf16 v[104:107], v[234:237], v[212:215], v[104:107]
	v_mfma_f32_16x16x32_bf16 v[100:103], v[238:241], v[212:215], v[100:103]
	v_mfma_f32_16x16x32_bf16 v[96:99], v[242:245], v[212:215], v[96:99]
	ds_read_b128 v[202:205], v186 offset:4096
	ds_read_b128 v[212:215], v186 offset:5120
	s_waitcnt lgkmcnt(2)
	v_mfma_f32_16x16x32_bf16 v[92:95], v[230:233], v[246:249], v[92:95]
	v_mfma_f32_16x16x32_bf16 v[88:91], v[234:237], v[246:249], v[88:91]
	v_mfma_f32_16x16x32_bf16 v[84:87], v[238:241], v[246:249], v[84:87]
	v_mfma_f32_16x16x32_bf16 v[80:83], v[242:245], v[246:249], v[80:83]
	v_mfma_f32_16x16x32_bf16 v[76:79], v[230:233], v[250:253], v[76:79]
	v_mfma_f32_16x16x32_bf16 v[72:75], v[234:237], v[250:253], v[72:75]
	v_mfma_f32_16x16x32_bf16 v[68:71], v[238:241], v[250:253], v[68:71]
	v_mfma_f32_16x16x32_bf16 v[64:67], v[242:245], v[250:253], v[64:67]
	ds_read_b128 v[246:249], v186 offset:6144
	ds_read_b128 v[250:253], v186 offset:7168
	s_waitcnt lgkmcnt(2)
	v_mfma_f32_16x16x32_bf16 v[60:63], v[230:233], v[202:205], v[60:63]
	v_mfma_f32_16x16x32_bf16 v[56:59], v[234:237], v[202:205], v[56:59]
	v_mfma_f32_16x16x32_bf16 v[52:55], v[238:241], v[202:205], v[52:55]
	v_mfma_f32_16x16x32_bf16 v[48:51], v[242:245], v[202:205], v[48:51]
	v_mfma_f32_16x16x32_bf16 v[44:47], v[230:233], v[212:215], v[44:47]
	v_mfma_f32_16x16x32_bf16 v[40:43], v[234:237], v[212:215], v[40:43]
	v_mfma_f32_16x16x32_bf16 v[36:39], v[238:241], v[212:215], v[36:39]
	v_mfma_f32_16x16x32_bf16 v[32:35], v[242:245], v[212:215], v[32:35]
	s_waitcnt lgkmcnt(0)
	v_mfma_f32_16x16x32_bf16 v[28:31], v[230:233], v[246:249], v[28:31]
	v_mfma_f32_16x16x32_bf16 v[24:27], v[234:237], v[246:249], v[24:27]
	v_mfma_f32_16x16x32_bf16 v[20:23], v[238:241], v[246:249], v[20:23]
	v_mfma_f32_16x16x32_bf16 v[16:19], v[242:245], v[246:249], v[16:19]
	v_mfma_f32_16x16x32_bf16 v[12:15], v[230:233], v[250:253], v[12:15]
	v_mfma_f32_16x16x32_bf16 v[8:11], v[234:237], v[250:253], v[8:11]
	v_mfma_f32_16x16x32_bf16 v[4:7], v[238:241], v[250:253], v[4:7]
	v_mfma_f32_16x16x32_bf16 v[0:3], v[242:245], v[250:253], v[0:3]
